# plus: removed 287 redundant v_max canonicalisations (x=max(x,x)) in attention phases, hazard-checked
# speedup vs baseline: 1.0127x; 1.0127x over previous
; DI void gload2(R2& r, const bf16_t* gsrc, size_t gp, int tid) { r.a = ld_chunk(gsrc, gp, tid); r.b = ld_chunk(gsrc, gp, tid + 256); }
; DI void gload4(R4& r, const bf16_t* gsrc, size_t gp, int tid) { r.a = ld_chunk(gsrc, gp, tid); r.b = ld_chunk(gsrc, gp, tid + 256); r.c = ld_chunk(gsrc, gp, tid + 512); r.d = ld_chunk(gsrc, gp, tid + 768); }
; DI float softmax_step(f32x4 (&st)[4], float& m, float& lsum) {
;   float mx = fmaxf(fmaxf(fmaxf(st[0][0], st[0][1]), fmaxf(st[0][2], st[0][3])), fmaxf(fmaxf(st[1][0], st[1][1]), fmaxf(st[1][2], st[1][3])));
;   mx = fmaxf(mx, fmaxf(fmaxf(fmaxf(st[2][0], st[2][1]), fmaxf(st[2][2], st[2][3])), fmaxf(fmaxf(st[3][0], st[3][1]), fmaxf(st[3][2], st[3][3]))));
;   mx = fmaxf(mx, __shfl_xor(mx, 16)); mx = fmaxf(mx, __shfl_xor(mx, 32));
;   const float mn = fmaxf(m, mx);
;   const float mu = mn == -INFINITY ? 0.f : mn;
;   const float alpha = __builtin_amdgcn_exp2f(m - mu);
;   float ps = 0.f;
; #pragma unroll
;   for (int kt = 0; kt < 4; ++kt)
; #pragma unroll
;     for (int j = 0; j < 4; ++j) { const float p = __builtin_amdgcn_exp2f(st[kt][j] - mu); st[kt][j] = p; ps += p; }
;   lsum = lsum * alpha + ps; m = mn;
;   return alpha;
; }
; DI void attn_A(const Params& P, int l, int b, int head, int qt, float lam, char* smem, bf16_t* ybase, size_t ypitch) {
;     ...
;   for (int n = 0; n <= qt; ++n) {
;     const char* sb = smem + (n & 1) * STAGE;
;     if (n < qt) {
;       const bf16_t* kn = kbase + (size_t)(n + 1) * 64 * PW;
;       gload2(rk0, kn, PW, tid); gload2(rk1, kn + 64, PW, tid); gload4(rv, vbase + (n + 1) * 64, SEQ, tid);
;     }
;     f32x4 s0[4], s1[4];
;     qk_tile(s0, sb, qf0, lr, g);
;     qk_tile(s1, sb + 9216, qf1, lr, g);
;     const float a0 = softmax_step(s0, m0, l0), a1 = softmax_step(s1, m1, l1);
; #pragma unroll
;     for (int i = 0; i < 8; ++i) { o0[i] *= a0; o1[i] *= a1; }
.LBB0_810:
	s_bitcmp1_b32 s8, 0
	s_cselect_b32 s9, 0x9000, 0
	v_or_b32_e32 v120, s9, v199
	v_add_u32_e32 v219, v120, v200
	v_add_u32_e32 v202, v120, v201
	ds_read_b128 v[112:115], v219
	ds_read_b128 v[116:119], v219 offset:2048
	ds_read_b128 v[120:123], v202
	ds_read_b128 v[124:127], v202 offset:2048
	s_waitcnt lgkmcnt(3)
	v_mfma_f32_16x16x32_f16 v[112:115], v[112:115], v[0:3], 0
	s_mov_b32 s9, 0xff800000
	s_waitcnt lgkmcnt(1)
	v_mfma_f32_16x16x32_f16 v[136:139], v[120:123], v[8:11], v[112:115]
	s_nop 4
	ds_read_b128 v[112:115], v219 offset:4096
	ds_read_b128 v[120:123], v202 offset:4096
	v_mfma_f32_16x16x32_f16 v[116:119], v[116:119], v[0:3], 0
	s_waitcnt lgkmcnt(1)
	v_mfma_f32_16x16x32_f16 v[112:115], v[112:115], v[0:3], 0
	v_mfma_f32_16x16x32_f16 v[128:131], v[124:127], v[8:11], v[116:119]
	s_nop 4
	ds_read_b128 v[116:119], v219 offset:6144
	ds_read_b128 v[140:143], v219 offset:9216
	ds_read_b128 v[124:127], v202 offset:6144
	ds_read_b128 v[144:147], v202 offset:9216
	ds_read_b128 v[204:207], v219 offset:11264
	ds_read_b128 v[210:213], v219 offset:13312
	s_waitcnt lgkmcnt(6)
	v_mfma_f32_16x16x32_f16 v[132:135], v[120:123], v[8:11], v[112:115]
	ds_read_b128 v[120:123], v202 offset:11264
	ds_read_b128 v[220:223], v202 offset:13312
	ds_read_b128 v[224:227], v219 offset:15360
	s_waitcnt lgkmcnt(8)
	v_mfma_f32_16x16x32_f16 v[112:115], v[116:119], v[0:3], 0
	v_max_f32_e32 v116, v138, v139
	v_max3_f32 v203, v136, v137, v116
	v_max_f32_e32 v116, v130, v131
	s_waitcnt lgkmcnt(6)
	v_mfma_f32_16x16x32_f16 v[124:127], v[124:127], v[8:11], v[112:115]
	v_mfma_f32_16x16x32_f16 v[112:115], v[140:143], v[4:7], 0
	v_max3_f32 v140, v128, v129, v116
	v_max_f32_e32 v141, v132, v133
	s_waitcnt lgkmcnt(4)
	v_mfma_f32_16x16x32_f16 v[116:119], v[204:207], v[4:7], 0
	v_max_f32_e32 v142, v134, v135
	s_waitcnt lgkmcnt(2)
	v_mfma_f32_16x16x32_f16 v[116:119], v[120:123], v[12:15], v[116:119]
	v_max_f32_e32 v120, v126, v127
	v_max3_f32 v143, v124, v125, v120
	v_max3_f32 v141, v141, v142, v143
	v_mfma_f32_16x16x32_f16 v[112:115], v[144:147], v[12:15], v[112:115]
	v_max3_f32 v144, v203, v140, v141
	ds_bpermute_b32 v145, v189, v144
	ds_read_b128 v[140:143], v202 offset:15360
	v_mfma_f32_16x16x32_f16 v[120:123], v[210:213], v[4:7], 0
	s_waitcnt lgkmcnt(1)
	v_max_f32_e32 v203, v144, v145
	ds_bpermute_b32 v204, v188, v203
	v_mfma_f32_16x16x32_f16 v[144:147], v[224:227], v[4:7], 0
	s_waitcnt lgkmcnt(1)
	v_mfma_f32_16x16x32_f16 v[232:235], v[140:143], v[12:15], v[144:147]
	v_mfma_f32_16x16x32_f16 v[120:123], v[220:223], v[12:15], v[120:123]
	s_waitcnt lgkmcnt(0)
	s_nop 3
	v_max3_f32 v146, v209, v203, v204
	v_cmp_neq_f32_e32 vcc, s9, v146
	ds_read_b128 v[220:223], v219 offset:32768
	ds_read_b128 v[224:227], v219 offset:18432
	ds_read_b128 v[228:231], v202 offset:18432
	v_cndmask_b32_e32 v141, 0, v146, vcc
	v_sub_f32_e32 v136, v136, v141
	v_sub_f32_e32 v128, v128, v141
	v_exp_f32_e32 v203, v136
	v_sub_f32_e32 v136, v137, v141
	v_exp_f32_e32 v207, v128
	v_sub_f32_e32 v128, v129, v141
	v_sub_f32_e32 v129, v131, v141
	v_exp_f32_e32 v204, v136
	v_sub_f32_e32 v136, v138, v141
	v_exp_f32_e32 v208, v128
	v_sub_f32_e32 v128, v130, v141
	v_exp_f32_e32 v130, v129
	v_sub_f32_e32 v129, v132, v141
	v_exp_f32_e32 v205, v136
	v_sub_f32_e32 v136, v139, v141
	v_exp_f32_e32 v132, v129
	v_sub_f32_e32 v129, v133, v141
	v_exp_f32_e32 v206, v136
	v_exp_f32_e32 v136, v129
	v_sub_f32_e32 v129, v134, v141
	v_exp_f32_e32 v134, v129
	v_sub_f32_e32 v129, v135, v141
	v_exp_f32_e32 v138, v129
	v_max_f32_e32 v129, v114, v115
	v_max_f32_e32 v131, v118, v119
	v_max_f32_e32 v133, v120, v121
	v_max_f32_e32 v135, v122, v123
	v_max_f32_e32 v137, v234, v235
	v_max3_f32 v137, v232, v233, v137
	v_max3_f32 v129, v112, v113, v129
	v_max3_f32 v131, v116, v117, v131
	v_max3_f32 v133, v133, v135, v137
	v_max3_f32 v129, v129, v131, v133
	ds_bpermute_b32 v131, v189, v129
	v_sub_f32_e32 v125, v125, v141
	v_exp_f32_e32 v140, v125
	v_sub_f32_e32 v125, v126, v141
	v_exp_f32_e32 v126, v125
	s_waitcnt lgkmcnt(0)
	v_max_f32_e32 v125, v129, v131
	ds_bpermute_b32 v129, v188, v125
	v_sub_f32_e32 v127, v127, v141
	v_exp_f32_e32 v142, v127
	v_sub_f32_e32 v127, v209, v141
	v_exp_f32_e32 v128, v128
	s_waitcnt lgkmcnt(0)
	v_max3_f32 v147, v215, v125, v129
	v_cmp_neq_f32_e32 vcc, s9, v147
	v_exp_f32_e32 v144, v127
	ds_read_b128 v[236:239], v219 offset:20480
	v_cndmask_b32_e32 v143, 0, v147, vcc
	v_sub_f32_e32 v112, v112, v143
	v_exp_f32_e32 v209, v112
	v_sub_f32_e32 v112, v113, v143
	v_exp_f32_e32 v210, v112
	v_sub_f32_e32 v112, v114, v143
	v_exp_f32_e32 v211, v112
	v_sub_f32_e32 v112, v115, v143
	v_exp_f32_e32 v212, v112
	v_sub_f32_e32 v112, v116, v143
	v_exp_f32_e32 v213, v112
	v_sub_f32_e32 v112, v117, v143
	v_exp_f32_e32 v214, v112
	v_sub_f32_e32 v112, v118, v143
	v_exp_f32_e32 v129, v112
	v_sub_f32_e32 v112, v119, v143
	v_exp_f32_e32 v131, v112
	v_sub_f32_e32 v112, v120, v143
	v_exp_f32_e32 v133, v112
	v_sub_f32_e32 v112, v121, v143
	v_exp_f32_e32 v137, v112
	v_sub_f32_e32 v112, v122, v143
	v_exp_f32_e32 v135, v112
	v_sub_f32_e32 v112, v215, v143
	v_exp_f32_e32 v120, v112
	v_sub_f32_e32 v121, v123, v143
	v_cvt_pk_f16_f32 v112, v203, v204
	v_cvt_pk_f16_f32 v113, v205, v206
	v_cvt_pk_f16_f32 v114, v207, v208
	v_cvt_pk_f16_f32 v116, v209, v210
	v_cvt_pk_f16_f32 v117, v211, v212
	v_cvt_pk_f16_f32 v118, v213, v214
	v_pk_mul_f32 v[94:95], v[94:95], v[144:145] op_sel_hi:[1,0]
	v_pk_mul_f32 v[92:93], v[92:93], v[144:145] op_sel_hi:[1,0]
	v_cvt_pk_f16_f32 v115, v128, v130
	v_pk_mul_f32 v[102:103], v[102:103], v[120:121] op_sel_hi:[1,0]
	v_pk_mul_f32 v[100:101], v[100:101], v[120:121] op_sel_hi:[1,0]
	v_cvt_pk_f16_f32 v119, v129, v131
; #define MFMA16(a, b, c) __builtin_amdgcn_mfma_f32_16x16x32_f16((a), (b), (c), 0, 0, 0)
; DI void sstoreK2(const R2& r, char* sdst, int tid) { st_chunk_k(sdst, tid, r.a); st_chunk_k(sdst, tid + 256, r.b); }
; DI void sstoreV4(const R4& r, char* sdst, int tid) { st_chunk_v(sdst, tid, r.a); st_chunk_v(sdst, tid + 256, r.b); st_chunk_v(sdst, tid + 512, r.c); st_chunk_v(sdst, tid + 768, r.d); }
; DI void attn_A(const Params& P, int l, int b, int head, int qt, float lam, char* smem, bf16_t* ybase, size_t ypitch) {
;     ...
;     const float a0 = softmax_step(s0, m0, l0), a1 = softmax_step(s1, m1, l1);
; #pragma unroll
;     for (int i = 0; i < 8; ++i) { o0[i] *= a0; o1[i] *= a1; }
; #pragma unroll
;     for (int kk = 0; kk < 2; ++kk) {
;       const bf16x8 p0 = pack8(s0[2 * kk], s0[2 * kk + 1]), p1 = pack8(s1[2 * kk], s1[2 * kk + 1]);
; #pragma unroll
;       for (int dt = 0; dt < 8; ++dt) {
;         const bf16x8 vf = vfrag(sb + 18432, dt, kk, lr, g);
;         o0[dt] = MFMA16(vf, p0, o0[dt]);
;         o1[dt] = MFMA16(vf, p1, o1[dt]);
;       }
;     }
;     if (n < qt) {
;       char* sn = smem + ((n + 1) & 1) * STAGE;
;       sstoreK2(rk0, sn, tid); sstoreK2(rk1, sn + 9216, tid); sstoreV4(rv, sn + 18432, tid);
;     }
;     __syncthreads();
	v_mfma_f32_16x16x32_f16 v[92:95], v[224:227], v[112:115], v[92:95]
	v_exp_f32_e32 v139, v121
	v_pk_mul_f32 v[98:99], v[98:99], v[120:121] op_sel_hi:[1,0]
	v_pk_mul_f32 v[96:97], v[96:97], v[120:121] op_sel_hi:[1,0]
	v_mfma_f32_16x16x32_f16 v[100:103], v[224:227], v[116:119], v[100:103]
	ds_read_b128 v[224:227], v219 offset:22528
	v_sub_f32_e32 v121, v232, v143
	v_pk_mul_f32 v[90:91], v[90:91], v[120:121] op_sel_hi:[1,0]
	v_pk_mul_f32 v[88:89], v[88:89], v[120:121] op_sel_hi:[1,0]
	v_exp_f32_e32 v125, v121
	v_pk_mul_f32 v[82:83], v[82:83], v[120:121] op_sel_hi:[1,0]
	v_pk_mul_f32 v[80:81], v[80:81], v[120:121] op_sel_hi:[1,0]
	v_sub_f32_e32 v121, v233, v143
	v_sub_f32_e32 v124, v124, v141
	v_pk_mul_f32 v[74:75], v[74:75], v[120:121] op_sel_hi:[1,0]
	v_pk_mul_f32 v[72:73], v[72:73], v[120:121] op_sel_hi:[1,0]
	v_exp_f32_e32 v141, v121
	v_pk_mul_f32 v[62:63], v[62:63], v[120:121] op_sel_hi:[1,0]
	v_pk_mul_f32 v[60:61], v[60:61], v[120:121] op_sel_hi:[1,0]
	v_sub_f32_e32 v121, v234, v143
	v_exp_f32_e32 v127, v121
	v_pk_mul_f32 v[50:51], v[50:51], v[120:121] op_sel_hi:[1,0]
	v_pk_mul_f32 v[48:49], v[48:49], v[120:121] op_sel_hi:[1,0]
	v_sub_f32_e32 v121, v235, v143
	v_pk_mul_f32 v[86:87], v[86:87], v[144:145] op_sel_hi:[1,0]
	v_pk_mul_f32 v[84:85], v[84:85], v[144:145] op_sel_hi:[1,0]
	v_pk_mul_f32 v[78:79], v[78:79], v[144:145] op_sel_hi:[1,0]
	v_pk_mul_f32 v[76:77], v[76:77], v[144:145] op_sel_hi:[1,0]
	v_pk_mul_f32 v[106:107], v[106:107], v[144:145] op_sel_hi:[1,0]
	v_pk_mul_f32 v[104:105], v[104:105], v[144:145] op_sel_hi:[1,0]
	v_pk_mul_f32 v[110:111], v[110:111], v[120:121] op_sel_hi:[1,0]
	v_pk_mul_f32 v[108:109], v[108:109], v[120:121] op_sel_hi:[1,0]
	v_mfma_f32_16x16x32_f16 v[104:107], v[220:223], v[112:115], v[104:107]
	v_mul_f32_e64 v70, v70, v144
	v_mul_f32_e64 v71, v71, v144
	v_pk_mul_f32 v[68:69], v[68:69], v[144:145] op_sel_hi:[1,0]
	v_pk_mul_f32 v[58:59], v[58:59], v[144:145] op_sel_hi:[1,0]
	v_mfma_f32_16x16x32_f16 v[108:111], v[220:223], v[116:119], v[108:111]
	ds_read_b128 v[220:223], v202 offset:20480
	v_pk_mul_f32 v[56:57], v[56:57], v[144:145] op_sel_hi:[1,0]
	v_exp_f32_e32 v124, v124
	s_waitcnt lgkmcnt(2)
	v_mfma_f32_16x16x32_f16 v[84:87], v[236:239], v[112:115], v[84:87]
	v_exp_f32_e32 v143, v121
	v_pk_mul_f32 v[46:47], v[46:47], v[144:145] op_sel_hi:[1,0]
	v_pk_mul_f32 v[44:45], v[44:45], v[144:145] op_sel_hi:[1,0]
	v_mfma_f32_16x16x32_f16 v[96:99], v[236:239], v[116:119], v[96:99]
	ds_read_b128 v[236:239], v219 offset:24576
	v_pk_mul_f32 v[42:43], v[42:43], v[144:145] op_sel_hi:[1,0]
	v_pk_mul_f32 v[40:41], v[40:41], v[144:145] op_sel_hi:[1,0]
	s_waitcnt lgkmcnt(2)
	v_mfma_f32_16x16x32_f16 v[76:79], v[224:227], v[112:115], v[76:79]
	s_andn2_b64 vcc, exec, s[6:7]
	v_mfma_f32_16x16x32_f16 v[88:91], v[224:227], v[116:119], v[88:91]
	ds_read_b128 v[224:227], v219 offset:26624
	s_waitcnt lgkmcnt(1)
	v_mfma_f32_16x16x32_f16 v[68:71], v[236:239], v[112:115], v[68:71]
	v_mfma_f32_16x16x32_f16 v[80:83], v[236:239], v[116:119], v[80:83]
	ds_read_b128 v[236:239], v219 offset:28672
	s_waitcnt lgkmcnt(1)
	v_mfma_f32_16x16x32_f16 v[56:59], v[224:227], v[112:115], v[56:59]
	v_mfma_f32_16x16x32_f16 v[72:75], v[224:227], v[116:119], v[72:75]
	ds_read_b128 v[224:227], v219 offset:30720
	s_waitcnt lgkmcnt(1)
	v_mfma_f32_16x16x32_f16 v[44:47], v[236:239], v[112:115], v[44:47]
	v_mfma_f32_16x16x32_f16 v[60:63], v[236:239], v[116:119], v[60:63]
	s_waitcnt lgkmcnt(0)
	v_mfma_f32_16x16x32_f16 v[40:43], v[224:227], v[112:115], v[40:43]
	v_cvt_pk_f16_f32 v112, v133, v137
	v_cvt_pk_f16_f32 v113, v135, v139
	v_cvt_pk_f16_f32 v114, v125, v141
	v_mfma_f32_16x16x32_f16 v[48:51], v[224:227], v[116:119], v[48:51]
	v_cvt_pk_f16_f32 v116, v132, v136
	v_cvt_pk_f16_f32 v117, v134, v138
	v_cvt_pk_f16_f32 v118, v124, v140
	v_cvt_pk_f16_f32 v119, v126, v142
	v_cvt_pk_f16_f32 v115, v127, v143
	s_nop 0
	v_mfma_f32_16x16x32_f16 v[84:87], v[220:223], v[116:119], v[84:87]
	v_mfma_f32_16x16x32_f16 v[96:99], v[220:223], v[112:115], v[96:99]
	ds_read_b128 v[220:223], v202 offset:22528
	s_waitcnt lgkmcnt(0)
	v_mfma_f32_16x16x32_f16 v[76:79], v[220:223], v[116:119], v[76:79]
	v_mfma_f32_16x16x32_f16 v[88:91], v[220:223], v[112:115], v[88:91]
	ds_read_b128 v[220:223], v202 offset:24576
	s_waitcnt lgkmcnt(0)
	v_mfma_f32_16x16x32_f16 v[68:71], v[220:223], v[116:119], v[68:71]
	v_mfma_f32_16x16x32_f16 v[80:83], v[220:223], v[112:115], v[80:83]
	ds_read_b128 v[220:223], v202 offset:26624
	s_waitcnt lgkmcnt(0)
	v_mfma_f32_16x16x32_f16 v[56:59], v[220:223], v[116:119], v[56:59]
	v_mfma_f32_16x16x32_f16 v[72:75], v[220:223], v[112:115], v[72:75]
	ds_read_b128 v[220:223], v202 offset:28672
	s_waitcnt lgkmcnt(0)
	v_mfma_f32_16x16x32_f16 v[44:47], v[220:223], v[116:119], v[44:47]
	v_mfma_f32_16x16x32_f16 v[60:63], v[220:223], v[112:115], v[60:63]
	ds_read_b128 v[220:223], v202 offset:30720
	s_waitcnt lgkmcnt(0)
	v_mfma_f32_16x16x32_f16 v[40:43], v[220:223], v[116:119], v[40:43]
	v_mfma_f32_16x16x32_f16 v[48:51], v[220:223], v[112:115], v[48:51]
	ds_read_b128 v[220:223], v202 offset:32768
	v_mfma_f32_16x16x32_f16 v[92:95], v[228:231], v[116:119], v[92:95]
	v_mfma_f32_16x16x32_f16 v[100:103], v[228:231], v[112:115], v[100:103]
	s_waitcnt lgkmcnt(0)
	v_mfma_f32_16x16x32_f16 v[104:107], v[220:223], v[116:119], v[104:107]
	v_mfma_f32_16x16x32_f16 v[108:111], v[220:223], v[112:115], v[108:111]
	s_cbranch_vccnz .LBB0_807
	s_andn2_b32 s6, 1, s8
	s_mul_i32 s6, s6, 0x9000
	v_add_u32_e32 v112, s6, v155
	v_add_u32_e32 v113, v112, v195
	v_add_u32_e32 v112, v112, v196
	s_waitcnt vmcnt(7)
	ds_write_b128 v113, v[16:19]
	s_waitcnt vmcnt(5)
	ds_write_b128 v113, v[20:23] offset:4096
	ds_write_b128 v113, v[24:27] offset:9216
	s_waitcnt vmcnt(4)
	ds_write_b128 v113, v[28:31] offset:13312
	v_add_u32_e32 v113, v112, v197
	v_add_u32_e32 v112, v112, v198
	s_waitcnt vmcnt(2)
	ds_write2st64_b64 v113, v[32:33], v[36:37] offset0:36 offset1:44
	ds_write2st64_b64 v112, v[34:35], v[38:39] offset0:36 offset1:44
	s_waitcnt vmcnt(0)
	ds_write2st64_b64 v113, v[52:53], v[64:65] offset0:52 offset1:60
	ds_write2st64_b64 v112, v[54:55], v[66:67] offset0:52 offset1:60
	s_branch .LBB0_807

; #define MFMA16(a, b, c) __builtin_amdgcn_mfma_f32_16x16x32_f16((a), (b), (c), 0, 0, 0)
; DI unsigned sortable(float f) { const unsigned u = __float_as_uint(f); return (u & 0x80000000u) ? ~u : (u | 0x80000000u); }
; template <int MODE> ...
;     ...
; #pragma unroll
;     for (int kt = 0; kt < 4; ++kt) {
;       f32x4 sh[4];
; #pragma unroll
;       for (int h = 0; h < 4; ++h) {
;         sh[h] = (f32x4){0.f, 0.f, 0.f, 0.f};
; #pragma unroll
;         for (int ks = 0; ks < 2; ++ks) sh[h] = MFMA16(qf[h][ks], kf[kt][ks], sh[h]);
;       }
; #pragma unroll
;       for (int j = 0; j < 4; ++j) {
;         float sc = w[j][0] * fmaxf(sh[0][j], 0.f) + w[j][1] * fmaxf(sh[1][j], 0.f) + w[j][2] * fmaxf(sh[2][j], 0.f) + w[j][3] * fmaxf(sh[3][j], 0.f);
;         sc += 0.0f;
;         const unsigned u = sortable(sc);
;         if (MODE == 4) {
;           const unsigned um = u & himask;
;           const bool eq = um == pfx[j], zr = u == 0x80000000u;
;           unsigned* qx = hist + (4 * g + j) * C1_HP + 512;
;           if (eq) {
;             const unsigned bin = u & bmask; atomicAdd(&hist[(4 * g + j) * C1_HP + (bin >> 1)], 1u << ((bin & 1u) * 16u));
;             if (!zr) { const unsigned idx = atomicAdd(&qx[320], 1u); if (idx < 64u) qx[256 + idx] = ((unsigned)n << 16) | ((unsigned)(kt * 16 + lr) << 10) | (u & 1023u); }
;           }
;           word[j] |= (u64)((unsigned)(__ballot(um > pfx[j]) >> (16 * g)) & 0xffffu) << (16 * kt);
;           zword[j] |= (u64)((unsigned)(__ballot(zr) >> (16 * g)) & 0xffffu) << (16 * kt);
;         } else if (MODE == 0 || MODE == 3) {
;           if (MODE == 3) base[j] += __popc((unsigned)(__ballot(u == 0x80000000u) >> (16 * g)) & 0xffffu);
;           if (((u ^ pfx[j]) & himask) == 0u) { const unsigned bin = (u >> shift) & bmask; atomicAdd(&hist[(4 * g + j) * C1_HP + (bin >> 1)], 1u << ((bin & 1u) * 16u)); }
;         } else {
.LBB0_831:
	s_waitcnt vmcnt(6)
	v_mov_b64_e32 v[102:103], v[38:39]
	v_mov_b64_e32 v[58:59], v[34:35]
	v_mov_b64_e32 v[100:101], v[36:37]
	v_mov_b64_e32 v[56:57], v[32:33]
	v_mov_b32_e32 v36, v146
	v_add_u32_e32 v146, 4, v36
	v_mfma_f32_16x16x32_f16 v[60:63], v[12:15], v[56:59], 0
	v_cmp_lt_i32_e32 vcc, s2, v146
	v_mfma_f32_16x16x32_f16 v[32:35], v[24:27], v[56:59], 0
	s_nop 0
	v_cndmask_b32_e32 v36, v146, v36, vcc
	v_lshlrev_b32_e32 v147, 6, v36
	v_or_b32_e32 v44, 16, v147
	v_mfma_f32_16x16x32_f16 v[40:43], v[4:7], v[56:59], 0
	v_or_b32_e32 v48, 32, v147
	v_mad_i64_i32 v[36:37], s[4:5], v147, s0, v[122:123]
	v_mfma_f32_16x16x32_f16 v[96:99], v[16:19], v[100:103], v[60:63]
	v_mad_i64_i32 v[44:45], s[4:5], v44, s0, v[122:123]
	v_mad_i64_i32 v[52:53], s[4:5], v48, s0, v[122:123]
	s_nop 0
	v_or_b32_e32 v60, 48, v147
	v_mad_i64_i32 v[60:61], s[4:5], v60, s0, v[122:123]
	v_mfma_f32_16x16x32_f16 v[88:91], v[0:3], v[100:103], v[32:35]
	s_nop 2
	global_load_dwordx4 v[32:35], v[36:37], off
	s_nop 0
	global_load_dwordx4 v[36:39], v[36:37], off offset:64
	s_nop 1
	v_mfma_f32_16x16x32_f16 v[92:95], v[8:11], v[100:103], v[40:43]
	s_nop 2
	global_load_dwordx4 v[40:43], v[44:45], off
	s_nop 0
	global_load_dwordx4 v[44:47], v[44:45], off offset:64
	s_nop 0
	global_load_dwordx4 v[48:51], v[52:53], off
	s_nop 0
	global_load_dwordx4 v[52:55], v[52:53], off offset:64
	v_mfma_f32_16x16x32_f16 v[154:157], v[20:23], v[56:59], 0
	global_load_dwordx4 v[56:59], v[60:61], off
	s_nop 0
	global_load_dwordx4 v[60:63], v[60:61], off offset:64
	v_mfma_f32_16x16x32_f16 v[100:103], v[28:31], v[100:103], v[154:157]
	s_nop 3
	v_max_f32_e32 v154, 0, v88
	v_max_f32_e32 v155, 0, v92
	v_max_f32_e32 v156, 0, v96
	v_pk_mul_f32 v[154:155], v[154:155], v[106:107]
	v_max_f32_e32 v157, 0, v100
	v_pk_mul_f32 v[156:157], v[156:157], v[108:109]
	v_add_f32_e32 v88, v154, v155
	v_add_f32_e32 v88, v88, v156
	v_add_f32_e32 v88, v88, v157
	v_add_f32_e32 v88, 0, v88
	v_not_b32_e32 v92, v88
	v_or_b32_e32 v96, 0x80000000, v88
	v_cmp_gt_i32_e64 s[4:5], 0, v88
	s_nop 1
	v_cndmask_b32_e64 v88, v96, v92, s[4:5]
	v_bitop3_b32 v92, v88, s30, v142 bitop3:0x48
	v_cmp_eq_u32_e64 s[4:5], 0, v92
	s_and_saveexec_b64 s[10:11], s[4:5]
	s_cbranch_execz .LBB0_833
	v_lshrrev_b32_e32 v88, s12, v88
	v_and_b32_e32 v88, s31, v88
	v_lshlrev_b32_e32 v92, 1, v88
	v_and_b32_e32 v92, -4, v92
	v_lshlrev_b32_e32 v88, 4, v88
	v_add_u32_e32 v92, v137, v92
	v_lshlrev_b32_e64 v88, v88, 1
	ds_add_u32 v92, v88
.LBB0_833:
	s_or_b64 exec, exec, s[10:11]
	v_max_f32_e32 v88, 0, v89
	v_max_f32_e32 v89, 0, v93
	v_pk_mul_f32 v[88:89], v[88:89], v[110:111]
	v_max_f32_e32 v92, 0, v97
	v_max_f32_e32 v93, 0, v101
	v_pk_mul_f32 v[92:93], v[92:93], v[112:113]
	v_add_f32_e32 v88, v88, v89
	v_add_f32_e32 v88, v88, v92
	v_add_f32_e32 v88, v88, v93
	v_add_f32_e32 v88, 0, v88
	v_not_b32_e32 v89, v88
	v_or_b32_e32 v92, 0x80000000, v88
	v_cmp_gt_i32_e64 s[4:5], 0, v88
	s_nop 1
	v_cndmask_b32_e64 v88, v92, v89, s[4:5]
	v_bitop3_b32 v89, v88, s30, v143 bitop3:0x48
	v_cmp_eq_u32_e64 s[4:5], 0, v89
	s_and_saveexec_b64 s[10:11], s[4:5]
	s_cbranch_execz .LBB0_835
	v_lshrrev_b32_e32 v88, s12, v88
	v_and_b32_e32 v88, s31, v88
	v_lshlrev_b32_e32 v89, 1, v88
	v_and_b32_e32 v89, -4, v89
	v_lshlrev_b32_e32 v88, 4, v88
	v_add_u32_e32 v89, v137, v89
	v_lshlrev_b32_e64 v88, v88, 1
	ds_add_u32 v89, v88 offset:4112
.LBB0_835:
	s_or_b64 exec, exec, s[10:11]
	v_max_f32_e32 v88, 0, v90
	v_max_f32_e32 v89, 0, v94
	v_max_f32_e32 v92, 0, v98
	v_pk_mul_f32 v[88:89], v[88:89], v[114:115]
	v_max_f32_e32 v93, 0, v102
	v_pk_mul_f32 v[92:93], v[92:93], v[116:117]
	v_add_f32_e32 v88, v88, v89
	v_add_f32_e32 v88, v88, v92
	v_add_f32_e32 v88, v88, v93
	v_add_f32_e32 v88, 0, v88
	v_not_b32_e32 v89, v88
	v_or_b32_e32 v90, 0x80000000, v88
	v_cmp_gt_i32_e64 s[4:5], 0, v88
	s_nop 1
	v_cndmask_b32_e64 v88, v90, v89, s[4:5]
	v_bitop3_b32 v89, v88, s30, v144 bitop3:0x48
	v_cmp_eq_u32_e64 s[4:5], 0, v89
	s_and_saveexec_b64 s[10:11], s[4:5]
	s_cbranch_execz .LBB0_837
	v_lshrrev_b32_e32 v88, s12, v88
	v_and_b32_e32 v88, s31, v88
	v_lshlrev_b32_e32 v89, 1, v88
	v_and_b32_e32 v89, -4, v89
	v_lshlrev_b32_e32 v88, 4, v88
	v_add_u32_e32 v89, v137, v89
	v_lshlrev_b32_e64 v88, v88, 1
	ds_add_u32 v89, v88 offset:8224
.LBB0_837:
	s_or_b64 exec, exec, s[10:11]
	v_max_f32_e32 v88, 0, v91
	v_max_f32_e32 v89, 0, v95
	v_pk_mul_f32 v[88:89], v[88:89], v[118:119]
	v_max_f32_e32 v90, 0, v99
	v_max_f32_e32 v91, 0, v103
	v_pk_mul_f32 v[90:91], v[90:91], v[120:121]
	v_add_f32_e32 v88, v88, v89
	v_add_f32_e32 v88, v88, v90
	v_add_f32_e32 v88, v88, v91
	v_add_f32_e32 v88, 0, v88
	v_not_b32_e32 v89, v88
	v_or_b32_e32 v90, 0x80000000, v88
	v_cmp_gt_i32_e64 s[4:5], 0, v88
	s_nop 1
	v_cndmask_b32_e64 v88, v90, v89, s[4:5]
	v_bitop3_b32 v89, v88, s30, v145 bitop3:0x48
	v_cmp_eq_u32_e64 s[4:5], 0, v89
	s_and_saveexec_b64 s[10:11], s[4:5]
	s_cbranch_execz .LBB0_839
	v_lshrrev_b32_e32 v88, s12, v88
	v_and_b32_e32 v88, s31, v88
	v_lshlrev_b32_e32 v89, 1, v88
	v_and_b32_e32 v89, -4, v89
	v_lshlrev_b32_e32 v88, 4, v88
	v_add_u32_e32 v89, v137, v89
	v_lshlrev_b32_e64 v88, v88, 1
	ds_add_u32 v89, v88 offset:12336
; #define MFMA16(a, b, c) __builtin_amdgcn_mfma_f32_16x16x32_f16((a), (b), (c), 0, 0, 0)
; DI unsigned sortable(float f) { const unsigned u = __float_as_uint(f); return (u & 0x80000000u) ? ~u : (u | 0x80000000u); }
; template <int MODE> ...
;     ...
; #pragma unroll
;     for (int kt = 0; kt < 4; ++kt) {
;       f32x4 sh[4];
; #pragma unroll
;       for (int h = 0; h < 4; ++h) {
;         sh[h] = (f32x4){0.f, 0.f, 0.f, 0.f};
; #pragma unroll
;         for (int ks = 0; ks < 2; ++ks) sh[h] = MFMA16(qf[h][ks], kf[kt][ks], sh[h]);
;       }
; #pragma unroll
;       for (int j = 0; j < 4; ++j) {
;         float sc = w[j][0] * fmaxf(sh[0][j], 0.f) + w[j][1] * fmaxf(sh[1][j], 0.f) + w[j][2] * fmaxf(sh[2][j], 0.f) + w[j][3] * fmaxf(sh[3][j], 0.f);
;         sc += 0.0f;
;         const unsigned u = sortable(sc);
;         if (MODE == 4) {
;           const unsigned um = u & himask;
;           const bool eq = um == pfx[j], zr = u == 0x80000000u;
;           unsigned* qx = hist + (4 * g + j) * C1_HP + 512;
;           if (eq) {
;             const unsigned bin = u & bmask; atomicAdd(&hist[(4 * g + j) * C1_HP + (bin >> 1)], 1u << ((bin & 1u) * 16u));
;             if (!zr) { const unsigned idx = atomicAdd(&qx[320], 1u); if (idx < 64u) qx[256 + idx] = ((unsigned)n << 16) | ((unsigned)(kt * 16 + lr) << 10) | (u & 1023u); }
;           }
;           word[j] |= (u64)((unsigned)(__ballot(um > pfx[j]) >> (16 * g)) & 0xffffu) << (16 * kt);
;           zword[j] |= (u64)((unsigned)(__ballot(zr) >> (16 * g)) & 0xffffu) << (16 * kt);
;         } else if (MODE == 0 || MODE == 3) {
;           if (MODE == 3) base[j] += __popc((unsigned)(__ballot(u == 0x80000000u) >> (16 * g)) & 0xffffu);
;           if (((u ^ pfx[j]) & himask) == 0u) { const unsigned bin = (u >> shift) & bmask; atomicAdd(&hist[(4 * g + j) * C1_HP + (bin >> 1)], 1u << ((bin & 1u) * 16u)); }
;         } else {
.LBB0_839:
	s_or_b64 exec, exec, s[10:11]
	s_waitcnt vmcnt(13)
	v_mfma_f32_16x16x32_f16 v[88:91], v[24:27], v[80:83], 0
	s_waitcnt vmcnt(12)
	v_mfma_f32_16x16x32_f16 v[92:95], v[0:3], v[84:87], v[88:91]
	v_mfma_f32_16x16x32_f16 v[88:91], v[4:7], v[80:83], 0
	v_mfma_f32_16x16x32_f16 v[96:99], v[8:11], v[84:87], v[88:91]
	v_mfma_f32_16x16x32_f16 v[88:91], v[12:15], v[80:83], 0
	v_mfma_f32_16x16x32_f16 v[80:83], v[20:23], v[80:83], 0
	v_mfma_f32_16x16x32_f16 v[88:91], v[16:19], v[84:87], v[88:91]
	v_mfma_f32_16x16x32_f16 v[80:83], v[28:31], v[84:87], v[80:83]
	s_nop 1
	v_max_f32_e32 v84, v92, v92
	s_nop 0
	v_max_f32_e32 v84, 0, v84
	v_max_f32_e32 v85, 0, v96
	v_pk_mul_f32 v[84:85], v[84:85], v[106:107]
	v_max_f32_e32 v86, 0, v88
	v_max_f32_e32 v87, 0, v80
	v_pk_mul_f32 v[86:87], v[86:87], v[108:109]
	v_add_f32_e32 v80, v84, v85
	v_add_f32_e32 v80, v80, v86
	v_add_f32_e32 v80, v80, v87
	v_add_f32_e32 v80, 0, v80
	v_not_b32_e32 v84, v80
	v_or_b32_e32 v85, 0x80000000, v80
	v_cmp_gt_i32_e64 s[4:5], 0, v80
	s_nop 1
	v_cndmask_b32_e64 v80, v85, v84, s[4:5]
	v_bitop3_b32 v84, v80, s30, v142 bitop3:0x48
	v_cmp_eq_u32_e64 s[4:5], 0, v84
	s_and_saveexec_b64 s[10:11], s[4:5]
	s_cbranch_execz .LBB0_841
	v_lshrrev_b32_e32 v80, s12, v80
	v_and_b32_e32 v80, s31, v80
	v_lshlrev_b32_e32 v84, 1, v80
	v_and_b32_e32 v84, -4, v84
	v_lshlrev_b32_e32 v80, 4, v80
	v_add_u32_e32 v84, v137, v84
	v_lshlrev_b32_e64 v80, v80, 1
	ds_add_u32 v84, v80
.LBB0_841:
	s_or_b64 exec, exec, s[10:11]
	v_max_f32_e32 v84, 0, v93
	v_max_f32_e32 v85, 0, v97
	v_pk_mul_f32 v[84:85], v[84:85], v[110:111]
	v_max_f32_e32 v80, 0, v89
	v_max_f32_e32 v81, 0, v81
	v_pk_mul_f32 v[80:81], v[80:81], v[112:113]
	v_add_f32_e32 v84, v84, v85
	v_add_f32_e32 v80, v84, v80
	v_add_f32_e32 v80, v80, v81
	v_add_f32_e32 v80, 0, v80
	v_not_b32_e32 v81, v80
	v_or_b32_e32 v84, 0x80000000, v80
	v_cmp_gt_i32_e64 s[4:5], 0, v80
	s_nop 1
	v_cndmask_b32_e64 v80, v84, v81, s[4:5]
	v_bitop3_b32 v81, v80, s30, v143 bitop3:0x48
	v_cmp_eq_u32_e64 s[4:5], 0, v81
	s_and_saveexec_b64 s[10:11], s[4:5]
	s_cbranch_execz .LBB0_843
	v_lshrrev_b32_e32 v80, s12, v80
	v_and_b32_e32 v80, s31, v80
	v_lshlrev_b32_e32 v81, 1, v80
	v_and_b32_e32 v81, -4, v81
	v_lshlrev_b32_e32 v80, 4, v80
	v_add_u32_e32 v81, v137, v81
	v_lshlrev_b32_e64 v80, v80, 1
	ds_add_u32 v81, v80 offset:4112
.LBB0_843:
	s_or_b64 exec, exec, s[10:11]
	v_max_f32_e32 v80, 0, v94
	v_max_f32_e32 v81, 0, v98
	v_pk_mul_f32 v[80:81], v[80:81], v[114:115]
	v_max_f32_e32 v84, 0, v90
	v_max_f32_e32 v85, 0, v82
	v_pk_mul_f32 v[84:85], v[84:85], v[116:117]
	v_add_f32_e32 v80, v80, v81
	v_add_f32_e32 v80, v80, v84
	v_add_f32_e32 v80, v80, v85
	v_add_f32_e32 v80, 0, v80
	v_not_b32_e32 v81, v80
	v_or_b32_e32 v82, 0x80000000, v80
	v_cmp_gt_i32_e64 s[4:5], 0, v80
	s_nop 1
	v_cndmask_b32_e64 v80, v82, v81, s[4:5]
	v_bitop3_b32 v81, v80, s30, v144 bitop3:0x48
	v_cmp_eq_u32_e64 s[4:5], 0, v81
	s_and_saveexec_b64 s[10:11], s[4:5]
	s_cbranch_execz .LBB0_845
	v_lshrrev_b32_e32 v80, s12, v80
	v_and_b32_e32 v80, s31, v80
	v_lshlrev_b32_e32 v81, 1, v80
	v_and_b32_e32 v81, -4, v81
	v_lshlrev_b32_e32 v80, 4, v80
	v_add_u32_e32 v81, v137, v81
	v_lshlrev_b32_e64 v80, v80, 1
	ds_add_u32 v81, v80 offset:8224
.LBB0_845:
	s_or_b64 exec, exec, s[10:11]
	v_max_f32_e32 v80, 0, v95
	v_max_f32_e32 v81, 0, v99
	v_pk_mul_f32 v[80:81], v[80:81], v[118:119]
	v_max_f32_e32 v82, 0, v91
	v_max_f32_e32 v83, 0, v83
	v_pk_mul_f32 v[82:83], v[82:83], v[120:121]
	v_add_f32_e32 v80, v80, v81
	v_add_f32_e32 v80, v80, v82
	v_add_f32_e32 v80, v80, v83
	v_add_f32_e32 v80, 0, v80
	v_not_b32_e32 v81, v80
	v_or_b32_e32 v82, 0x80000000, v80
	v_cmp_gt_i32_e64 s[4:5], 0, v80
	s_nop 1
	v_cndmask_b32_e64 v80, v82, v81, s[4:5]
	v_bitop3_b32 v81, v80, s30, v145 bitop3:0x48
	v_cmp_eq_u32_e64 s[4:5], 0, v81
	s_and_saveexec_b64 s[10:11], s[4:5]
	s_cbranch_execz .LBB0_847
	v_lshrrev_b32_e32 v80, s12, v80
	v_and_b32_e32 v80, s31, v80
	v_lshlrev_b32_e32 v81, 1, v80
	v_and_b32_e32 v81, -4, v81
	v_lshlrev_b32_e32 v80, 4, v80
	v_add_u32_e32 v81, v137, v81
	v_lshlrev_b32_e64 v80, v80, 1
	ds_add_u32 v81, v80 offset:12336
.LBB0_847:
	s_or_b64 exec, exec, s[10:11]
	s_waitcnt vmcnt(11)
	v_mfma_f32_16x16x32_f16 v[80:83], v[24:27], v[72:75], 0
	s_waitcnt vmcnt(10)
	v_mfma_f32_16x16x32_f16 v[84:87], v[0:3], v[76:79], v[80:83]
	v_mfma_f32_16x16x32_f16 v[80:83], v[4:7], v[72:75], 0
	v_mfma_f32_16x16x32_f16 v[88:91], v[8:11], v[76:79], v[80:83]
	v_mfma_f32_16x16x32_f16 v[80:83], v[12:15], v[72:75], 0
	v_mfma_f32_16x16x32_f16 v[72:75], v[20:23], v[72:75], 0
	v_mfma_f32_16x16x32_f16 v[80:83], v[16:19], v[76:79], v[80:83]
	v_mfma_f32_16x16x32_f16 v[72:75], v[28:31], v[76:79], v[72:75]
	s_nop 1
	v_max_f32_e32 v76, v84, v84
	s_nop 0
	v_max_f32_e32 v76, 0, v76
	v_max_f32_e32 v77, 0, v88
	v_pk_mul_f32 v[76:77], v[76:77], v[106:107]
	v_max_f32_e32 v78, 0, v80
	v_max_f32_e32 v79, 0, v72
	v_pk_mul_f32 v[78:79], v[78:79], v[108:109]
	v_add_f32_e32 v72, v76, v77
	v_add_f32_e32 v72, v72, v78
	v_add_f32_e32 v72, v72, v79
	v_add_f32_e32 v72, 0, v72
	v_not_b32_e32 v76, v72
	v_or_b32_e32 v77, 0x80000000, v72
	v_cmp_gt_i32_e64 s[4:5], 0, v72
	s_nop 1
	v_cndmask_b32_e64 v72, v77, v76, s[4:5]
	v_bitop3_b32 v76, v72, s30, v142 bitop3:0x48
	v_cmp_eq_u32_e64 s[4:5], 0, v76
	s_and_saveexec_b64 s[10:11], s[4:5]
	s_cbranch_execz .LBB0_849
	v_lshrrev_b32_e32 v72, s12, v72
	v_and_b32_e32 v72, s31, v72
	v_lshlrev_b32_e32 v76, 1, v72
	v_and_b32_e32 v76, -4, v76
	v_lshlrev_b32_e32 v72, 4, v72
	v_add_u32_e32 v76, v137, v76
	v_lshlrev_b32_e64 v72, v72, 1
	ds_add_u32 v76, v72
; #define MFMA16(a, b, c) __builtin_amdgcn_mfma_f32_16x16x32_f16((a), (b), (c), 0, 0, 0)
; DI unsigned sortable(float f) { const unsigned u = __float_as_uint(f); return (u & 0x80000000u) ? ~u : (u | 0x80000000u); }
; template <int MODE> ...
;     ...
; #pragma unroll
;     for (int kt = 0; kt < 4; ++kt) {
;       f32x4 sh[4];
; #pragma unroll
;       for (int h = 0; h < 4; ++h) {
;         sh[h] = (f32x4){0.f, 0.f, 0.f, 0.f};
; #pragma unroll
;         for (int ks = 0; ks < 2; ++ks) sh[h] = MFMA16(qf[h][ks], kf[kt][ks], sh[h]);
;       }
; #pragma unroll
;       for (int j = 0; j < 4; ++j) {
;         float sc = w[j][0] * fmaxf(sh[0][j], 0.f) + w[j][1] * fmaxf(sh[1][j], 0.f) + w[j][2] * fmaxf(sh[2][j], 0.f) + w[j][3] * fmaxf(sh[3][j], 0.f);
;         sc += 0.0f;
;         const unsigned u = sortable(sc);
;         if (MODE == 4) {
;           const unsigned um = u & himask;
;           const bool eq = um == pfx[j], zr = u == 0x80000000u;
;           unsigned* qx = hist + (4 * g + j) * C1_HP + 512;
;           if (eq) {
;             const unsigned bin = u & bmask; atomicAdd(&hist[(4 * g + j) * C1_HP + (bin >> 1)], 1u << ((bin & 1u) * 16u));
;             if (!zr) { const unsigned idx = atomicAdd(&qx[320], 1u); if (idx < 64u) qx[256 + idx] = ((unsigned)n << 16) | ((unsigned)(kt * 16 + lr) << 10) | (u & 1023u); }
;           }
;           word[j] |= (u64)((unsigned)(__ballot(um > pfx[j]) >> (16 * g)) & 0xffffu) << (16 * kt);
;           zword[j] |= (u64)((unsigned)(__ballot(zr) >> (16 * g)) & 0xffffu) << (16 * kt);
;         } else if (MODE == 0 || MODE == 3) {
;           if (MODE == 3) base[j] += __popc((unsigned)(__ballot(u == 0x80000000u) >> (16 * g)) & 0xffffu);
;           if (((u ^ pfx[j]) & himask) == 0u) { const unsigned bin = (u >> shift) & bmask; atomicAdd(&hist[(4 * g + j) * C1_HP + (bin >> 1)], 1u << ((bin & 1u) * 16u)); }
;         } else {
.LBB0_849:
	s_or_b64 exec, exec, s[10:11]
	v_max_f32_e32 v76, 0, v85
	v_max_f32_e32 v77, 0, v89
	v_pk_mul_f32 v[76:77], v[76:77], v[110:111]
	v_max_f32_e32 v72, 0, v81
	v_max_f32_e32 v73, 0, v73
	v_pk_mul_f32 v[72:73], v[72:73], v[112:113]
	v_add_f32_e32 v76, v76, v77
	v_add_f32_e32 v72, v76, v72
	v_add_f32_e32 v72, v72, v73
	v_add_f32_e32 v72, 0, v72
	v_not_b32_e32 v73, v72
	v_or_b32_e32 v76, 0x80000000, v72
	v_cmp_gt_i32_e64 s[4:5], 0, v72
	s_nop 1
	v_cndmask_b32_e64 v72, v76, v73, s[4:5]
	v_bitop3_b32 v73, v72, s30, v143 bitop3:0x48
	v_cmp_eq_u32_e64 s[4:5], 0, v73
	s_and_saveexec_b64 s[10:11], s[4:5]
	s_cbranch_execz .LBB0_851
	v_lshrrev_b32_e32 v72, s12, v72
	v_and_b32_e32 v72, s31, v72
	v_lshlrev_b32_e32 v73, 1, v72
	v_and_b32_e32 v73, -4, v73
	v_lshlrev_b32_e32 v72, 4, v72
	v_add_u32_e32 v73, v137, v73
	v_lshlrev_b32_e64 v72, v72, 1
	ds_add_u32 v73, v72 offset:4112
.LBB0_851:
	s_or_b64 exec, exec, s[10:11]
	v_max_f32_e32 v72, 0, v86
	v_max_f32_e32 v73, 0, v90
	v_pk_mul_f32 v[72:73], v[72:73], v[114:115]
	v_max_f32_e32 v76, 0, v82
	v_max_f32_e32 v77, 0, v74
	v_pk_mul_f32 v[76:77], v[76:77], v[116:117]
	v_add_f32_e32 v72, v72, v73
	v_add_f32_e32 v72, v72, v76
	v_add_f32_e32 v72, v72, v77
	v_add_f32_e32 v72, 0, v72
	v_not_b32_e32 v73, v72
	v_or_b32_e32 v74, 0x80000000, v72
	v_cmp_gt_i32_e64 s[4:5], 0, v72
	s_nop 1
	v_cndmask_b32_e64 v72, v74, v73, s[4:5]
	v_bitop3_b32 v73, v72, s30, v144 bitop3:0x48
	v_cmp_eq_u32_e64 s[4:5], 0, v73
	s_and_saveexec_b64 s[10:11], s[4:5]
	s_cbranch_execz .LBB0_853
	v_lshrrev_b32_e32 v72, s12, v72
	v_and_b32_e32 v72, s31, v72
	v_lshlrev_b32_e32 v73, 1, v72
	v_and_b32_e32 v73, -4, v73
	v_lshlrev_b32_e32 v72, 4, v72
	v_add_u32_e32 v73, v137, v73
	v_lshlrev_b32_e64 v72, v72, 1
	ds_add_u32 v73, v72 offset:8224
.LBB0_853:
	s_or_b64 exec, exec, s[10:11]
	v_max_f32_e32 v72, 0, v87
	v_max_f32_e32 v73, 0, v91
	v_pk_mul_f32 v[72:73], v[72:73], v[118:119]
	v_max_f32_e32 v74, 0, v83
	v_max_f32_e32 v75, 0, v75
	v_pk_mul_f32 v[74:75], v[74:75], v[120:121]
	v_add_f32_e32 v72, v72, v73
	v_add_f32_e32 v72, v72, v74
	v_add_f32_e32 v72, v72, v75
	v_add_f32_e32 v72, 0, v72
	v_not_b32_e32 v73, v72
	v_or_b32_e32 v74, 0x80000000, v72
	v_cmp_gt_i32_e64 s[4:5], 0, v72
	s_nop 1
	v_cndmask_b32_e64 v72, v74, v73, s[4:5]
	v_bitop3_b32 v73, v72, s30, v145 bitop3:0x48
	v_cmp_eq_u32_e64 s[4:5], 0, v73
	s_and_saveexec_b64 s[10:11], s[4:5]
	s_cbranch_execz .LBB0_855
	v_lshrrev_b32_e32 v72, s12, v72
	v_and_b32_e32 v72, s31, v72
	v_lshlrev_b32_e32 v73, 1, v72
	v_and_b32_e32 v73, -4, v73
	v_lshlrev_b32_e32 v72, 4, v72
	v_add_u32_e32 v73, v137, v73
	v_lshlrev_b32_e64 v72, v72, 1
	ds_add_u32 v73, v72 offset:12336
.LBB0_855:
	s_or_b64 exec, exec, s[10:11]
	s_waitcnt vmcnt(9)
	v_mfma_f32_16x16x32_f16 v[72:75], v[24:27], v[64:67], 0
	s_waitcnt vmcnt(8)
	v_mfma_f32_16x16x32_f16 v[76:79], v[0:3], v[68:71], v[72:75]
	v_mfma_f32_16x16x32_f16 v[72:75], v[4:7], v[64:67], 0
	v_mfma_f32_16x16x32_f16 v[80:83], v[8:11], v[68:71], v[72:75]
	v_mfma_f32_16x16x32_f16 v[72:75], v[12:15], v[64:67], 0
	v_mfma_f32_16x16x32_f16 v[64:67], v[20:23], v[64:67], 0
	v_mfma_f32_16x16x32_f16 v[72:75], v[16:19], v[68:71], v[72:75]
	v_mfma_f32_16x16x32_f16 v[64:67], v[28:31], v[68:71], v[64:67]
	s_nop 1
	v_max_f32_e32 v68, v76, v76
	s_nop 0
	v_max_f32_e32 v68, 0, v68
	v_max_f32_e32 v69, 0, v80
	v_pk_mul_f32 v[68:69], v[68:69], v[106:107]
	v_max_f32_e32 v70, 0, v72
	v_max_f32_e32 v71, 0, v64
	v_pk_mul_f32 v[70:71], v[70:71], v[108:109]
	v_add_f32_e32 v64, v68, v69
	v_add_f32_e32 v64, v64, v70
	v_add_f32_e32 v64, v64, v71
	v_add_f32_e32 v64, 0, v64
	v_not_b32_e32 v68, v64
	v_or_b32_e32 v69, 0x80000000, v64
	v_cmp_gt_i32_e64 s[4:5], 0, v64
	s_nop 1
	v_cndmask_b32_e64 v64, v69, v68, s[4:5]
	v_bitop3_b32 v68, v64, s30, v142 bitop3:0x48
	v_cmp_eq_u32_e64 s[4:5], 0, v68
	s_and_saveexec_b64 s[10:11], s[4:5]
	s_cbranch_execz .LBB0_857
	v_lshrrev_b32_e32 v64, s12, v64
	v_and_b32_e32 v64, s31, v64
	v_lshlrev_b32_e32 v68, 1, v64
	v_and_b32_e32 v68, -4, v68
	v_lshlrev_b32_e32 v64, 4, v64
	v_add_u32_e32 v68, v137, v68
	v_lshlrev_b32_e64 v64, v64, 1
	ds_add_u32 v68, v64
.LBB0_857:
	s_or_b64 exec, exec, s[10:11]
	v_max_f32_e32 v68, 0, v77
	v_max_f32_e32 v69, 0, v81
	v_pk_mul_f32 v[68:69], v[68:69], v[110:111]
	v_max_f32_e32 v64, 0, v73
	v_max_f32_e32 v65, 0, v65
	v_pk_mul_f32 v[64:65], v[64:65], v[112:113]
	v_add_f32_e32 v68, v68, v69
	v_add_f32_e32 v64, v68, v64
	v_add_f32_e32 v64, v64, v65
	v_add_f32_e32 v64, 0, v64
	v_not_b32_e32 v65, v64
	v_or_b32_e32 v68, 0x80000000, v64
	v_cmp_gt_i32_e64 s[4:5], 0, v64
	s_nop 1
	v_cndmask_b32_e64 v64, v68, v65, s[4:5]
	v_bitop3_b32 v65, v64, s30, v143 bitop3:0x48
	v_cmp_eq_u32_e64 s[4:5], 0, v65
	s_and_saveexec_b64 s[10:11], s[4:5]
	s_cbranch_execz .LBB0_859
	v_lshrrev_b32_e32 v64, s12, v64
	v_and_b32_e32 v64, s31, v64
	v_lshlrev_b32_e32 v65, 1, v64
	v_and_b32_e32 v65, -4, v65
	v_lshlrev_b32_e32 v64, 4, v64
	v_add_u32_e32 v65, v137, v65
	v_lshlrev_b32_e64 v64, v64, 1
	ds_add_u32 v65, v64 offset:4112
.LBB0_859:
	s_or_b64 exec, exec, s[10:11]
	v_max_f32_e32 v64, 0, v78
	v_max_f32_e32 v65, 0, v82
	v_pk_mul_f32 v[64:65], v[64:65], v[114:115]
	v_max_f32_e32 v68, 0, v74
	v_max_f32_e32 v69, 0, v66
	v_pk_mul_f32 v[68:69], v[68:69], v[116:117]
	v_add_f32_e32 v64, v64, v65
	v_add_f32_e32 v64, v64, v68
	v_add_f32_e32 v64, v64, v69
	v_add_f32_e32 v64, 0, v64
	v_not_b32_e32 v65, v64
	v_or_b32_e32 v66, 0x80000000, v64
	v_cmp_gt_i32_e64 s[4:5], 0, v64
	s_nop 1
	v_cndmask_b32_e64 v64, v66, v65, s[4:5]
	v_bitop3_b32 v65, v64, s30, v144 bitop3:0x48
	v_cmp_eq_u32_e64 s[4:5], 0, v65
	s_and_saveexec_b64 s[10:11], s[4:5]
	s_cbranch_execz .LBB0_861
	v_lshrrev_b32_e32 v64, s12, v64
	v_and_b32_e32 v64, s31, v64
	v_lshlrev_b32_e32 v65, 1, v64
	v_and_b32_e32 v65, -4, v65
	v_lshlrev_b32_e32 v64, 4, v64
	v_add_u32_e32 v65, v137, v65
	v_lshlrev_b32_e64 v64, v64, 1
	ds_add_u32 v65, v64 offset:8224
.LBB0_861:
	s_or_b64 exec, exec, s[10:11]
	v_max_f32_e32 v64, 0, v79
	v_max_f32_e32 v65, 0, v83
	v_pk_mul_f32 v[64:65], v[64:65], v[118:119]
	v_max_f32_e32 v66, 0, v75
	v_max_f32_e32 v67, 0, v67
	v_pk_mul_f32 v[66:67], v[66:67], v[120:121]
	v_add_f32_e32 v64, v64, v65
	v_add_f32_e32 v64, v64, v66
	v_add_f32_e32 v64, v64, v67
	v_add_f32_e32 v64, 0, v64
	v_not_b32_e32 v65, v64
	v_or_b32_e32 v66, 0x80000000, v64
	v_cmp_gt_i32_e64 s[4:5], 0, v64
	s_nop 1
	v_cndmask_b32_e64 v64, v66, v65, s[4:5]
	v_bitop3_b32 v65, v64, s30, v145 bitop3:0x48
	v_cmp_eq_u32_e64 s[4:5], 0, v65
	s_and_saveexec_b64 s[10:11], s[4:5]
	s_cbranch_execz .LBB0_830
	v_lshrrev_b32_e32 v64, s12, v64
	v_and_b32_e32 v64, s31, v64
	v_lshlrev_b32_e32 v65, 1, v64
	v_and_b32_e32 v65, -4, v65
	v_lshlrev_b32_e32 v64, 4, v64
	v_add_u32_e32 v65, v137, v65
	v_lshlrev_b32_e64 v64, v64, 1
	ds_add_u32 v65, v64 offset:12336
	s_branch .LBB0_830

; #define MFMA16(a, b, c) __builtin_amdgcn_mfma_f32_16x16x32_f16((a), (b), (c), 0, 0, 0)
; DI unsigned sortable(float f) { const unsigned u = __float_as_uint(f); return (u & 0x80000000u) ? ~u : (u | 0x80000000u); }
; template <int MODE> ...
;     ...
;     for (int kt = 0; kt < 4; ++kt) {
;       f32x4 sh[4];
; #pragma unroll
;       for (int h = 0; h < 4; ++h) {
;         sh[h] = (f32x4){0.f, 0.f, 0.f, 0.f};
; #pragma unroll
;         for (int ks = 0; ks < 2; ++ks) sh[h] = MFMA16(qf[h][ks], kf[kt][ks], sh[h]);
;       }
; #pragma unroll
;       for (int j = 0; j < 4; ++j) {
;         float sc = w[j][0] * fmaxf(sh[0][j], 0.f) + w[j][1] * fmaxf(sh[1][j], 0.f) + w[j][2] * fmaxf(sh[2][j], 0.f) + w[j][3] * fmaxf(sh[3][j], 0.f);
;         sc += 0.0f;
;         const unsigned u = sortable(sc);
;         if (MODE == 4) {
;           const unsigned um = u & himask;
;           const bool eq = um == pfx[j], zr = u == 0x80000000u;
;           unsigned* qx = hist + (4 * g + j) * C1_HP + 512;
;           if (eq) {
;             const unsigned bin = u & bmask; atomicAdd(&hist[(4 * g + j) * C1_HP + (bin >> 1)], 1u << ((bin & 1u) * 16u));
;             if (!zr) { const unsigned idx = atomicAdd(&qx[320], 1u); if (idx < 64u) qx[256 + idx] = ((unsigned)n << 16) | ((unsigned)(kt * 16 + lr) << 10) | (u & 1023u); }
;           }
;           word[j] |= (u64)((unsigned)(__ballot(um > pfx[j]) >> (16 * g)) & 0xffffu) << (16 * kt);
;           zword[j] |= (u64)((unsigned)(__ballot(zr) >> (16 * g)) & 0xffffu) << (16 * kt);
;         } else if (MODE == 0 || MODE == 3) {
;           if (MODE == 3) base[j] += __popc((unsigned)(__ballot(u == 0x80000000u) >> (16 * g)) & 0xffffu);
.LBB0_870:
	s_waitcnt vmcnt(6)
	v_mov_b64_e32 v[102:103], v[38:39]
	v_mov_b64_e32 v[58:59], v[34:35]
	v_mov_b64_e32 v[100:101], v[36:37]
	v_mov_b64_e32 v[56:57], v[32:33]
	v_mov_b32_e32 v36, v154
	v_add_u32_e32 v154, 4, v36
	v_mfma_f32_16x16x32_f16 v[60:63], v[12:15], v[56:59], 0
	v_cmp_lt_i32_e64 s[4:5], s2, v154
	v_mfma_f32_16x16x32_f16 v[32:35], v[24:27], v[56:59], 0
	s_nop 0
	v_cndmask_b32_e64 v36, v154, v36, s[4:5]
	v_lshlrev_b32_e32 v155, 6, v36
	v_or_b32_e32 v44, 16, v155
	v_mfma_f32_16x16x32_f16 v[40:43], v[4:7], v[56:59], 0
	v_or_b32_e32 v48, 32, v155
	v_mad_i64_i32 v[36:37], s[6:7], v155, s0, v[122:123]
	v_mfma_f32_16x16x32_f16 v[96:99], v[16:19], v[100:103], v[60:63]
	v_mad_i64_i32 v[44:45], s[6:7], v44, s0, v[122:123]
	v_mad_i64_i32 v[52:53], s[6:7], v48, s0, v[122:123]
	s_nop 0
	v_or_b32_e32 v60, 48, v155
	v_mad_i64_i32 v[60:61], s[6:7], v60, s0, v[122:123]
	v_mfma_f32_16x16x32_f16 v[88:91], v[0:3], v[100:103], v[32:35]
	s_nop 2
	global_load_dwordx4 v[32:35], v[36:37], off
	s_nop 0
	global_load_dwordx4 v[36:39], v[36:37], off offset:64
	s_nop 1
	v_mfma_f32_16x16x32_f16 v[92:95], v[8:11], v[100:103], v[40:43]
	s_nop 2
	global_load_dwordx4 v[40:43], v[44:45], off
	s_nop 0
	global_load_dwordx4 v[44:47], v[44:45], off offset:64
	s_nop 0
	global_load_dwordx4 v[48:51], v[52:53], off
	s_nop 0
	global_load_dwordx4 v[52:55], v[52:53], off offset:64
	v_mfma_f32_16x16x32_f16 v[156:159], v[20:23], v[56:59], 0
	global_load_dwordx4 v[56:59], v[60:61], off
	s_nop 0
	global_load_dwordx4 v[60:63], v[60:61], off offset:64
	v_mfma_f32_16x16x32_f16 v[100:103], v[28:31], v[100:103], v[156:159]
	s_nop 3
	v_max_f32_e32 v156, 0, v88
	v_max_f32_e32 v157, 0, v92
	v_max_f32_e32 v158, 0, v96
	v_pk_mul_f32 v[156:157], v[156:157], v[106:107]
	v_max_f32_e32 v159, 0, v100
	v_pk_mul_f32 v[158:159], v[158:159], v[108:109]
	v_add_f32_e32 v88, v156, v157
	v_add_f32_e32 v88, v88, v158
	v_add_f32_e32 v88, v88, v159
	v_add_f32_e32 v88, 0, v88
	v_not_b32_e32 v92, v88
	v_or_b32_e32 v96, 0x80000000, v88
	v_cmp_gt_i32_e32 vcc, 0, v88
	s_nop 1
	v_cndmask_b32_e32 v92, v96, v92, vcc
	v_and_b32_e32 v88, s30, v92
	v_cmp_eq_u32_e64 s[8:9], v88, v142
	v_cmp_eq_u32_e32 vcc, s3, v92
	v_cmp_ne_u32_e64 s[6:7], s3, v92
	s_and_saveexec_b64 s[10:11], s[8:9]
	s_cbranch_execz .LBB0_874
	v_and_b32_e32 v96, s31, v92
	v_lshlrev_b32_e32 v100, 1, v96
	v_and_b32_e32 v100, -4, v100
	v_lshlrev_b32_e32 v96, 4, v96
	v_add_u32_e32 v100, v137, v100
	v_lshlrev_b32_e64 v96, v96, 1
	ds_add_u32 v100, v96
	s_and_b64 exec, exec, s[6:7]
	s_cbranch_execz .LBB0_874
	ds_add_rtn_u32 v96, v137, v174 offset:3328
	s_waitcnt lgkmcnt(0)
	v_cmp_gt_u32_e64 s[6:7], 64, v96
	s_and_b64 exec, exec, s[6:7]
	v_and_b32_e32 v92, 0x3ff, v92
	v_add_u32_e32 v92, v146, v92
	v_lshl_add_u32 v96, v96, 2, v137
	ds_write_b32 v96, v92 offset:3072
.LBB0_874:
	s_or_b64 exec, exec, s[10:11]
	v_cmp_gt_u32_e64 s[56:57], v88, v142
	v_cndmask_b32_e64 v88, 0, 1, vcc
	v_cmp_ne_u32_e64 s[58:59], 0, v88
	v_max_f32_e32 v88, 0, v89
	v_max_f32_e32 v89, 0, v93
	v_pk_mul_f32 v[88:89], v[88:89], v[110:111]
	v_max_f32_e32 v92, 0, v97
	v_max_f32_e32 v93, 0, v101
	v_pk_mul_f32 v[92:93], v[92:93], v[112:113]
	v_add_f32_e32 v88, v88, v89
	v_add_f32_e32 v88, v88, v92
	v_add_f32_e32 v88, v88, v93
	v_add_f32_e32 v88, 0, v88
	v_not_b32_e32 v89, v88
	v_or_b32_e32 v92, 0x80000000, v88
	v_cmp_gt_i32_e32 vcc, 0, v88
	s_nop 1
	v_cndmask_b32_e32 v89, v92, v89, vcc
	v_and_b32_e32 v88, s30, v89
	v_cmp_eq_u32_e64 s[8:9], v88, v143
	v_cmp_eq_u32_e32 vcc, s3, v89
	v_cmp_ne_u32_e64 s[6:7], s3, v89
	s_and_saveexec_b64 s[10:11], s[8:9]
	s_cbranch_execz .LBB0_878
	v_and_b32_e32 v92, s31, v89
	v_lshlrev_b32_e32 v93, 1, v92
	v_and_b32_e32 v93, -4, v93
	v_lshlrev_b32_e32 v92, 4, v92
	v_add_u32_e32 v93, v137, v93
	v_lshlrev_b32_e64 v92, v92, 1
	ds_add_u32 v93, v92 offset:4112
	s_and_b64 exec, exec, s[6:7]
	s_cbranch_execz .LBB0_878
	ds_add_rtn_u32 v92, v137, v174 offset:7440
	s_waitcnt lgkmcnt(0)
	v_cmp_gt_u32_e64 s[6:7], 64, v92
	s_and_b64 exec, exec, s[6:7]
	v_and_b32_e32 v89, 0x3ff, v89
	v_add_u32_e32 v89, v146, v89
	v_lshl_add_u32 v92, v92, 2, v137
	ds_write_b32 v92, v89 offset:7184
.LBB0_878:
	s_or_b64 exec, exec, s[10:11]
	v_cmp_gt_u32_e64 s[60:61], v88, v143
	v_cndmask_b32_e64 v88, 0, 1, vcc
	v_cmp_ne_u32_e64 s[62:63], 0, v88
	v_max_f32_e32 v88, 0, v90
	v_max_f32_e32 v89, 0, v94
	v_max_f32_e32 v92, 0, v98
	v_pk_mul_f32 v[88:89], v[88:89], v[114:115]
	v_max_f32_e32 v93, 0, v102
	v_pk_mul_f32 v[92:93], v[92:93], v[116:117]
	v_add_f32_e32 v88, v88, v89
	v_add_f32_e32 v88, v88, v92
	v_add_f32_e32 v88, v88, v93
	v_add_f32_e32 v88, 0, v88
	v_not_b32_e32 v89, v88
	v_or_b32_e32 v90, 0x80000000, v88
	v_cmp_gt_i32_e32 vcc, 0, v88
	s_nop 1
	v_cndmask_b32_e32 v89, v90, v89, vcc
	v_and_b32_e32 v88, s30, v89
	v_cmp_eq_u32_e64 s[8:9], v88, v144
	v_cmp_eq_u32_e32 vcc, s3, v89
	v_cmp_ne_u32_e64 s[6:7], s3, v89
	s_and_saveexec_b64 s[10:11], s[8:9]
	s_cbranch_execz .LBB0_882
	v_and_b32_e32 v90, s31, v89
	v_lshlrev_b32_e32 v92, 1, v90
	v_and_b32_e32 v92, -4, v92
	v_lshlrev_b32_e32 v90, 4, v90
	v_add_u32_e32 v92, v137, v92
	v_lshlrev_b32_e64 v90, v90, 1
	ds_add_u32 v92, v90 offset:8224
	s_and_b64 exec, exec, s[6:7]
	s_cbranch_execz .LBB0_882
	ds_add_rtn_u32 v90, v137, v174 offset:11552
	s_waitcnt lgkmcnt(0)
	v_cmp_gt_u32_e64 s[6:7], 64, v90
	s_and_b64 exec, exec, s[6:7]
	v_and_b32_e32 v89, 0x3ff, v89
	v_add_u32_e32 v89, v146, v89
	v_lshl_add_u32 v90, v90, 2, v137
	ds_write_b32 v90, v89 offset:11296
; #define MFMA16(a, b, c) __builtin_amdgcn_mfma_f32_16x16x32_f16((a), (b), (c), 0, 0, 0)
; DI unsigned sortable(float f) { const unsigned u = __float_as_uint(f); return (u & 0x80000000u) ? ~u : (u | 0x80000000u); }
; template <int MODE> ...
;     ...
;     for (int kt = 0; kt < 4; ++kt) {
;       f32x4 sh[4];
; #pragma unroll
;       for (int h = 0; h < 4; ++h) {
;         sh[h] = (f32x4){0.f, 0.f, 0.f, 0.f};
; #pragma unroll
;         for (int ks = 0; ks < 2; ++ks) sh[h] = MFMA16(qf[h][ks], kf[kt][ks], sh[h]);
;       }
; #pragma unroll
;       for (int j = 0; j < 4; ++j) {
;         float sc = w[j][0] * fmaxf(sh[0][j], 0.f) + w[j][1] * fmaxf(sh[1][j], 0.f) + w[j][2] * fmaxf(sh[2][j], 0.f) + w[j][3] * fmaxf(sh[3][j], 0.f);
;         sc += 0.0f;
;         const unsigned u = sortable(sc);
;         if (MODE == 4) {
;           const unsigned um = u & himask;
;           const bool eq = um == pfx[j], zr = u == 0x80000000u;
;           unsigned* qx = hist + (4 * g + j) * C1_HP + 512;
;           if (eq) {
;             const unsigned bin = u & bmask; atomicAdd(&hist[(4 * g + j) * C1_HP + (bin >> 1)], 1u << ((bin & 1u) * 16u));
;             if (!zr) { const unsigned idx = atomicAdd(&qx[320], 1u); if (idx < 64u) qx[256 + idx] = ((unsigned)n << 16) | ((unsigned)(kt * 16 + lr) << 10) | (u & 1023u); }
;           }
;           word[j] |= (u64)((unsigned)(__ballot(um > pfx[j]) >> (16 * g)) & 0xffffu) << (16 * kt);
;           zword[j] |= (u64)((unsigned)(__ballot(zr) >> (16 * g)) & 0xffffu) << (16 * kt);
;         } else if (MODE == 0 || MODE == 3) {
;           if (MODE == 3) base[j] += __popc((unsigned)(__ballot(u == 0x80000000u) >> (16 * g)) & 0xffffu);
.LBB0_882:
	s_or_b64 exec, exec, s[10:11]
	v_cmp_gt_u32_e64 s[68:69], v88, v144
	v_cndmask_b32_e64 v88, 0, 1, vcc
	v_cmp_ne_u32_e64 s[70:71], 0, v88
	v_max_f32_e32 v88, 0, v91
	v_max_f32_e32 v89, 0, v95
	v_pk_mul_f32 v[88:89], v[88:89], v[118:119]
	v_max_f32_e32 v90, 0, v99
	v_max_f32_e32 v91, 0, v103
	v_pk_mul_f32 v[90:91], v[90:91], v[120:121]
	v_add_f32_e32 v88, v88, v89
	v_add_f32_e32 v88, v88, v90
	v_add_f32_e32 v88, v88, v91
	v_add_f32_e32 v88, 0, v88
	v_not_b32_e32 v89, v88
	v_or_b32_e32 v90, 0x80000000, v88
	v_cmp_gt_i32_e32 vcc, 0, v88
	s_nop 1
	v_cndmask_b32_e32 v89, v90, v89, vcc
	v_and_b32_e32 v88, s30, v89
	v_cmp_eq_u32_e64 s[8:9], v88, v145
	v_cmp_eq_u32_e32 vcc, s3, v89
	v_cmp_ne_u32_e64 s[6:7], s3, v89
	s_and_saveexec_b64 s[10:11], s[8:9]
	s_cbranch_execz .LBB0_886
	v_and_b32_e32 v90, s31, v89
	v_lshlrev_b32_e32 v91, 1, v90
	v_and_b32_e32 v91, -4, v91
	v_lshlrev_b32_e32 v90, 4, v90
	v_add_u32_e32 v91, v137, v91
	v_lshlrev_b32_e64 v90, v90, 1
	ds_add_u32 v91, v90 offset:12336
	s_and_b64 exec, exec, s[6:7]
	s_cbranch_execz .LBB0_886
	ds_add_rtn_u32 v90, v137, v174 offset:15664
	s_waitcnt lgkmcnt(0)
	v_cmp_gt_u32_e64 s[6:7], 64, v90
	s_and_b64 exec, exec, s[6:7]
	v_and_b32_e32 v89, 0x3ff, v89
	v_add_u32_e32 v89, v146, v89
	v_lshl_add_u32 v90, v90, 2, v137
	ds_write_b32 v90, v89 offset:15408
.LBB0_886:
	s_or_b64 exec, exec, s[10:11]
	v_cmp_gt_u32_e64 s[64:65], v88, v145
	v_cndmask_b32_e64 v88, 0, 1, vcc
	v_cmp_ne_u32_e64 s[66:67], 0, v88
	s_waitcnt vmcnt(13)
	v_mfma_f32_16x16x32_f16 v[88:91], v[24:27], v[80:83], 0
	v_mfma_f32_16x16x32_f16 v[92:95], v[4:7], v[80:83], 0
	v_mfma_f32_16x16x32_f16 v[96:99], v[12:15], v[80:83], 0
	v_mfma_f32_16x16x32_f16 v[80:83], v[20:23], v[80:83], 0
	s_waitcnt vmcnt(12)
	v_mfma_f32_16x16x32_f16 v[88:91], v[0:3], v[84:87], v[88:91]
	v_mfma_f32_16x16x32_f16 v[92:95], v[8:11], v[84:87], v[92:95]
	v_mfma_f32_16x16x32_f16 v[96:99], v[16:19], v[84:87], v[96:99]
	v_mfma_f32_16x16x32_f16 v[80:83], v[28:31], v[84:87], v[80:83]
	s_nop 4
	v_max_f32_e32 v84, 0, v88
	v_max_f32_e32 v85, 0, v92
	v_pk_mul_f32 v[84:85], v[84:85], v[106:107]
	v_max_f32_e32 v86, 0, v96
	v_max_f32_e32 v87, 0, v80
	v_pk_mul_f32 v[86:87], v[86:87], v[108:109]
	v_add_f32_e32 v80, v84, v85
	v_add_f32_e32 v80, v80, v86
	v_add_f32_e32 v80, v80, v87
	v_add_f32_e32 v80, 0, v80
	v_not_b32_e32 v84, v80
	v_or_b32_e32 v85, 0x80000000, v80
	v_cmp_gt_i32_e32 vcc, 0, v80
	s_nop 1
	v_cndmask_b32_e32 v84, v85, v84, vcc
	v_and_b32_e32 v80, s30, v84
	v_cmp_eq_u32_e64 s[8:9], v80, v142
	v_cmp_eq_u32_e32 vcc, s3, v84
	v_cmp_ne_u32_e64 s[6:7], s3, v84
	s_and_saveexec_b64 s[10:11], s[8:9]
	s_cbranch_execz .LBB0_890
	v_and_b32_e32 v85, s31, v84
	v_lshlrev_b32_e32 v86, 1, v85
	v_and_b32_e32 v86, -4, v86
	v_lshlrev_b32_e32 v85, 4, v85
	v_add_u32_e32 v86, v137, v86
	v_lshlrev_b32_e64 v85, v85, 1
	ds_add_u32 v86, v85
	s_and_b64 exec, exec, s[6:7]
	s_cbranch_execz .LBB0_890
	ds_add_rtn_u32 v85, v137, v174 offset:3328
	s_waitcnt lgkmcnt(0)
	v_cmp_gt_u32_e64 s[6:7], 64, v85
	s_and_b64 exec, exec, s[6:7]
	v_and_b32_e32 v84, 0x3ff, v84
	s_movk_i32 s6, 0x4000
	v_add3_u32 v84, v146, v84, s6
	v_lshl_add_u32 v85, v85, 2, v137
	ds_write_b32 v85, v84 offset:3072
.LBB0_890:
	s_or_b64 exec, exec, s[10:11]
	v_cmp_gt_u32_e64 s[74:75], v80, v142
	v_cndmask_b32_e64 v80, 0, 1, vcc
	v_cmp_ne_u32_e64 s[72:73], 0, v80
	v_max_f32_e32 v84, 0, v89
	v_max_f32_e32 v85, 0, v93
	v_pk_mul_f32 v[84:85], v[84:85], v[110:111]
	v_max_f32_e32 v80, 0, v97
	v_max_f32_e32 v81, 0, v81
	v_pk_mul_f32 v[80:81], v[80:81], v[112:113]
	v_add_f32_e32 v84, v84, v85
	v_add_f32_e32 v80, v84, v80
	v_add_f32_e32 v80, v80, v81
	v_add_f32_e32 v80, 0, v80
	v_not_b32_e32 v81, v80
	v_or_b32_e32 v84, 0x80000000, v80
	v_cmp_gt_i32_e32 vcc, 0, v80
	s_nop 1
	v_cndmask_b32_e32 v81, v84, v81, vcc
	v_and_b32_e32 v80, s30, v81
	v_cmp_eq_u32_e64 s[8:9], v80, v143
	v_cmp_eq_u32_e32 vcc, s3, v81
	v_cmp_ne_u32_e64 s[6:7], s3, v81
	s_and_saveexec_b64 s[10:11], s[8:9]
	s_cbranch_execz .LBB0_894
	v_and_b32_e32 v84, s31, v81
	v_lshlrev_b32_e32 v85, 1, v84
	v_and_b32_e32 v85, -4, v85
	v_lshlrev_b32_e32 v84, 4, v84
	v_add_u32_e32 v85, v137, v85
	v_lshlrev_b32_e64 v84, v84, 1
	ds_add_u32 v85, v84 offset:4112
	s_and_b64 exec, exec, s[6:7]
	s_cbranch_execz .LBB0_894
	ds_add_rtn_u32 v84, v137, v174 offset:7440
	s_waitcnt lgkmcnt(0)
	v_cmp_gt_u32_e64 s[6:7], 64, v84
	s_and_b64 exec, exec, s[6:7]
	v_and_b32_e32 v81, 0x3ff, v81
	s_movk_i32 s6, 0x4000
	v_add3_u32 v81, v146, v81, s6
	v_lshl_add_u32 v84, v84, 2, v137
	ds_write_b32 v84, v81 offset:7184
.LBB0_894:
	s_or_b64 exec, exec, s[10:11]
	v_cmp_gt_u32_e64 s[78:79], v80, v143
	v_cndmask_b32_e64 v80, 0, 1, vcc
	v_cmp_ne_u32_e64 s[76:77], 0, v80
	v_max_f32_e32 v80, 0, v90
	v_max_f32_e32 v81, 0, v94
	v_pk_mul_f32 v[80:81], v[80:81], v[114:115]
	v_max_f32_e32 v84, 0, v98
	v_max_f32_e32 v85, 0, v82
	v_pk_mul_f32 v[84:85], v[84:85], v[116:117]
	v_add_f32_e32 v80, v80, v81
	v_add_f32_e32 v80, v80, v84
	v_add_f32_e32 v80, v80, v85
	v_add_f32_e32 v80, 0, v80
	v_not_b32_e32 v81, v80
	v_or_b32_e32 v82, 0x80000000, v80
	v_cmp_gt_i32_e32 vcc, 0, v80
	s_nop 1
	v_cndmask_b32_e32 v81, v82, v81, vcc
	v_and_b32_e32 v80, s30, v81
	v_cmp_eq_u32_e64 s[8:9], v80, v144
	v_cmp_eq_u32_e32 vcc, s3, v81
	v_cmp_ne_u32_e64 s[6:7], s3, v81
	s_and_saveexec_b64 s[10:11], s[8:9]
	s_cbranch_execz .LBB0_898
	v_and_b32_e32 v82, s31, v81
	v_lshlrev_b32_e32 v84, 1, v82
	v_and_b32_e32 v84, -4, v84
	v_lshlrev_b32_e32 v82, 4, v82
	v_add_u32_e32 v84, v137, v84
	v_lshlrev_b32_e64 v82, v82, 1
	ds_add_u32 v84, v82 offset:8224
	s_and_b64 exec, exec, s[6:7]
	s_cbranch_execz .LBB0_898
	ds_add_rtn_u32 v82, v137, v174 offset:11552
	s_waitcnt lgkmcnt(0)
	v_cmp_gt_u32_e64 s[6:7], 64, v82
	s_and_b64 exec, exec, s[6:7]
	v_and_b32_e32 v81, 0x3ff, v81
	s_movk_i32 s6, 0x4000
	v_add3_u32 v81, v146, v81, s6
	v_lshl_add_u32 v82, v82, 2, v137
	ds_write_b32 v82, v81 offset:11296
; #define MFMA16(a, b, c) __builtin_amdgcn_mfma_f32_16x16x32_f16((a), (b), (c), 0, 0, 0)
; DI unsigned sortable(float f) { const unsigned u = __float_as_uint(f); return (u & 0x80000000u) ? ~u : (u | 0x80000000u); }
; template <int MODE> ...
;     ...
;     for (int kt = 0; kt < 4; ++kt) {
;       f32x4 sh[4];
; #pragma unroll
;       for (int h = 0; h < 4; ++h) {
;         sh[h] = (f32x4){0.f, 0.f, 0.f, 0.f};
; #pragma unroll
;         for (int ks = 0; ks < 2; ++ks) sh[h] = MFMA16(qf[h][ks], kf[kt][ks], sh[h]);
;       }
; #pragma unroll
;       for (int j = 0; j < 4; ++j) {
;         float sc = w[j][0] * fmaxf(sh[0][j], 0.f) + w[j][1] * fmaxf(sh[1][j], 0.f) + w[j][2] * fmaxf(sh[2][j], 0.f) + w[j][3] * fmaxf(sh[3][j], 0.f);
;         sc += 0.0f;
;         const unsigned u = sortable(sc);
;         if (MODE == 4) {
;           const unsigned um = u & himask;
;           const bool eq = um == pfx[j], zr = u == 0x80000000u;
;           unsigned* qx = hist + (4 * g + j) * C1_HP + 512;
;           if (eq) {
;             const unsigned bin = u & bmask; atomicAdd(&hist[(4 * g + j) * C1_HP + (bin >> 1)], 1u << ((bin & 1u) * 16u));
;             if (!zr) { const unsigned idx = atomicAdd(&qx[320], 1u); if (idx < 64u) qx[256 + idx] = ((unsigned)n << 16) | ((unsigned)(kt * 16 + lr) << 10) | (u & 1023u); }
;           }
;           word[j] |= (u64)((unsigned)(__ballot(um > pfx[j]) >> (16 * g)) & 0xffffu) << (16 * kt);
;           zword[j] |= (u64)((unsigned)(__ballot(zr) >> (16 * g)) & 0xffffu) << (16 * kt);
;         } else if (MODE == 0 || MODE == 3) {
;           if (MODE == 3) base[j] += __popc((unsigned)(__ballot(u == 0x80000000u) >> (16 * g)) & 0xffffu);
.LBB0_898:
	s_or_b64 exec, exec, s[10:11]
	v_cmp_gt_u32_e64 s[86:87], v80, v144
	v_cndmask_b32_e64 v80, 0, 1, vcc
	v_cmp_ne_u32_e64 s[84:85], 0, v80
	v_max_f32_e32 v80, 0, v91
	v_max_f32_e32 v81, 0, v95
	v_pk_mul_f32 v[80:81], v[80:81], v[118:119]
	v_max_f32_e32 v82, 0, v99
	v_max_f32_e32 v83, 0, v83
	v_pk_mul_f32 v[82:83], v[82:83], v[120:121]
	v_add_f32_e32 v80, v80, v81
	v_add_f32_e32 v80, v80, v82
	v_add_f32_e32 v80, v80, v83
	v_add_f32_e32 v80, 0, v80
	v_not_b32_e32 v81, v80
	v_or_b32_e32 v82, 0x80000000, v80
	v_cmp_gt_i32_e32 vcc, 0, v80
	s_nop 1
	v_cndmask_b32_e32 v81, v82, v81, vcc
	v_and_b32_e32 v80, s30, v81
	v_cmp_eq_u32_e64 s[8:9], v80, v145
	v_cmp_eq_u32_e32 vcc, s3, v81
	v_cmp_ne_u32_e64 s[6:7], s3, v81
	s_and_saveexec_b64 s[10:11], s[8:9]
	s_cbranch_execz .LBB0_902
	v_and_b32_e32 v82, s31, v81
	v_lshlrev_b32_e32 v83, 1, v82
	v_and_b32_e32 v83, -4, v83
	v_lshlrev_b32_e32 v82, 4, v82
	v_add_u32_e32 v83, v137, v83
	v_lshlrev_b32_e64 v82, v82, 1
	ds_add_u32 v83, v82 offset:12336
	s_and_b64 exec, exec, s[6:7]
	s_cbranch_execz .LBB0_902
	ds_add_rtn_u32 v82, v137, v174 offset:15664
	s_waitcnt lgkmcnt(0)
	v_cmp_gt_u32_e64 s[6:7], 64, v82
	s_and_b64 exec, exec, s[6:7]
	v_and_b32_e32 v81, 0x3ff, v81
	s_movk_i32 s6, 0x4000
	v_add3_u32 v81, v146, v81, s6
	v_lshl_add_u32 v82, v82, 2, v137
	ds_write_b32 v82, v81 offset:15408
.LBB0_902:
	s_or_b64 exec, exec, s[10:11]
	v_cmp_gt_u32_e64 s[82:83], v80, v145
	v_cndmask_b32_e64 v80, 0, 1, vcc
	v_cmp_ne_u32_e64 s[80:81], 0, v80
	s_waitcnt vmcnt(11)
	v_mfma_f32_16x16x32_f16 v[80:83], v[24:27], v[72:75], 0
	v_mfma_f32_16x16x32_f16 v[84:87], v[4:7], v[72:75], 0
	v_mfma_f32_16x16x32_f16 v[88:91], v[12:15], v[72:75], 0
	v_mfma_f32_16x16x32_f16 v[72:75], v[20:23], v[72:75], 0
	s_waitcnt vmcnt(10)
	v_mfma_f32_16x16x32_f16 v[80:83], v[0:3], v[76:79], v[80:83]
	v_mfma_f32_16x16x32_f16 v[84:87], v[8:11], v[76:79], v[84:87]
	v_mfma_f32_16x16x32_f16 v[88:91], v[16:19], v[76:79], v[88:91]
	v_mfma_f32_16x16x32_f16 v[72:75], v[28:31], v[76:79], v[72:75]
	s_nop 4
	v_max_f32_e32 v76, 0, v80
	v_max_f32_e32 v77, 0, v84
	v_pk_mul_f32 v[76:77], v[76:77], v[106:107]
	v_max_f32_e32 v78, 0, v88
	v_max_f32_e32 v79, 0, v72
	v_pk_mul_f32 v[78:79], v[78:79], v[108:109]
	v_add_f32_e32 v72, v76, v77
	v_add_f32_e32 v72, v72, v78
	v_add_f32_e32 v72, v72, v79
	v_add_f32_e32 v72, 0, v72
	v_not_b32_e32 v76, v72
	v_or_b32_e32 v77, 0x80000000, v72
	v_cmp_gt_i32_e32 vcc, 0, v72
	s_nop 1
	v_cndmask_b32_e32 v76, v77, v76, vcc
	v_and_b32_e32 v72, s30, v76
	v_cmp_eq_u32_e64 s[8:9], v72, v142
	v_cmp_eq_u32_e32 vcc, s3, v76
	v_cmp_ne_u32_e64 s[6:7], s3, v76
	s_and_saveexec_b64 s[10:11], s[8:9]
	s_cbranch_execz .LBB0_906
	v_and_b32_e32 v77, s31, v76
	v_lshlrev_b32_e32 v78, 1, v77
	v_and_b32_e32 v78, -4, v78
	v_lshlrev_b32_e32 v77, 4, v77
	v_add_u32_e32 v78, v137, v78
	v_lshlrev_b32_e64 v77, v77, 1
	ds_add_u32 v78, v77
	s_and_b64 exec, exec, s[6:7]
	s_cbranch_execz .LBB0_906
	ds_add_rtn_u32 v77, v137, v174 offset:3328
	s_waitcnt lgkmcnt(0)
	v_cmp_gt_u32_e64 s[6:7], 64, v77
	s_and_b64 exec, exec, s[6:7]
	v_and_b32_e32 v76, 0x3ff, v76
	s_mov_b32 s6, 0x8000
	v_add3_u32 v76, v146, v76, s6
	v_lshl_add_u32 v77, v77, 2, v137
	ds_write_b32 v77, v76 offset:3072
.LBB0_906:
	s_or_b64 exec, exec, s[10:11]
	v_cmp_gt_u32_e64 s[88:89], v72, v142
	v_cndmask_b32_e64 v72, 0, 1, vcc
	v_cmp_ne_u32_e64 s[90:91], 0, v72
	v_max_f32_e32 v76, 0, v81
	v_max_f32_e32 v77, 0, v85
	v_pk_mul_f32 v[76:77], v[76:77], v[110:111]
	v_max_f32_e32 v72, 0, v89
	v_max_f32_e32 v73, 0, v73
	v_pk_mul_f32 v[72:73], v[72:73], v[112:113]
	v_add_f32_e32 v76, v76, v77
	v_add_f32_e32 v72, v76, v72
	v_add_f32_e32 v72, v72, v73
	v_add_f32_e32 v72, 0, v72
	v_not_b32_e32 v73, v72
	v_or_b32_e32 v76, 0x80000000, v72
	v_cmp_gt_i32_e32 vcc, 0, v72
	s_nop 1
	v_cndmask_b32_e32 v73, v76, v73, vcc
	v_and_b32_e32 v72, s30, v73
	v_cmp_eq_u32_e64 s[8:9], v72, v143
	v_cmp_eq_u32_e32 vcc, s3, v73
	v_cmp_ne_u32_e64 s[6:7], s3, v73
	s_and_saveexec_b64 s[10:11], s[8:9]
	s_cbranch_execz .LBB0_910
	v_and_b32_e32 v76, s31, v73
	v_lshlrev_b32_e32 v77, 1, v76
	v_and_b32_e32 v77, -4, v77
	v_lshlrev_b32_e32 v76, 4, v76
	v_add_u32_e32 v77, v137, v77
	v_lshlrev_b32_e64 v76, v76, 1
	ds_add_u32 v77, v76 offset:4112
	s_and_b64 exec, exec, s[6:7]
	s_cbranch_execz .LBB0_910
	ds_add_rtn_u32 v76, v137, v174 offset:7440
	s_waitcnt lgkmcnt(0)
	v_cmp_gt_u32_e64 s[6:7], 64, v76
	s_and_b64 exec, exec, s[6:7]
	v_and_b32_e32 v73, 0x3ff, v73
	s_mov_b32 s6, 0x8000
	v_add3_u32 v73, v146, v73, s6
	v_lshl_add_u32 v76, v76, 2, v137
	ds_write_b32 v76, v73 offset:7184
.LBB0_910:
	s_or_b64 exec, exec, s[10:11]
	v_cmp_gt_u32_e64 s[92:93], v72, v143
	v_cndmask_b32_e64 v72, 0, 1, vcc
	v_cmp_ne_u32_e64 s[94:95], 0, v72
	v_max_f32_e32 v72, 0, v82
	v_max_f32_e32 v73, 0, v86
	v_pk_mul_f32 v[72:73], v[72:73], v[114:115]
	v_max_f32_e32 v76, 0, v90
	v_max_f32_e32 v77, 0, v74
	v_pk_mul_f32 v[76:77], v[76:77], v[116:117]
	v_add_f32_e32 v72, v72, v73
	v_add_f32_e32 v72, v72, v76
	v_add_f32_e32 v72, v72, v77
	v_add_f32_e32 v72, 0, v72
	v_not_b32_e32 v73, v72
	v_or_b32_e32 v74, 0x80000000, v72
	v_cmp_gt_i32_e32 vcc, 0, v72
	s_nop 1
	v_cndmask_b32_e32 v73, v74, v73, vcc
	v_and_b32_e32 v72, s30, v73
	v_cmp_eq_u32_e64 s[8:9], v72, v144
	v_cmp_eq_u32_e32 vcc, s3, v73
	v_cmp_ne_u32_e64 s[6:7], s3, v73
	s_and_saveexec_b64 s[10:11], s[8:9]
	s_cbranch_execz .LBB0_914
	v_and_b32_e32 v74, s31, v73
	v_lshlrev_b32_e32 v76, 1, v74
	v_and_b32_e32 v76, -4, v76
	v_lshlrev_b32_e32 v74, 4, v74
	v_add_u32_e32 v76, v137, v76
	v_lshlrev_b32_e64 v74, v74, 1
	ds_add_u32 v76, v74 offset:8224
	s_and_b64 exec, exec, s[6:7]
	s_cbranch_execz .LBB0_914
	ds_add_rtn_u32 v74, v137, v174 offset:11552
	s_waitcnt lgkmcnt(0)
	v_cmp_gt_u32_e64 s[6:7], 64, v74
	s_and_b64 exec, exec, s[6:7]
	v_and_b32_e32 v73, 0x3ff, v73
	s_mov_b32 s6, 0x8000
	v_add3_u32 v73, v146, v73, s6
	v_lshl_add_u32 v74, v74, 2, v137
	ds_write_b32 v74, v73 offset:11296
; #define MFMA16(a, b, c) __builtin_amdgcn_mfma_f32_16x16x32_f16((a), (b), (c), 0, 0, 0)
; DI unsigned sortable(float f) { const unsigned u = __float_as_uint(f); return (u & 0x80000000u) ? ~u : (u | 0x80000000u); }
; template <int MODE> ...
;     ...
;     for (int kt = 0; kt < 4; ++kt) {
;       f32x4 sh[4];
; #pragma unroll
;       for (int h = 0; h < 4; ++h) {
;         sh[h] = (f32x4){0.f, 0.f, 0.f, 0.f};
; #pragma unroll
;         for (int ks = 0; ks < 2; ++ks) sh[h] = MFMA16(qf[h][ks], kf[kt][ks], sh[h]);
;       }
; #pragma unroll
;       for (int j = 0; j < 4; ++j) {
;         float sc = w[j][0] * fmaxf(sh[0][j], 0.f) + w[j][1] * fmaxf(sh[1][j], 0.f) + w[j][2] * fmaxf(sh[2][j], 0.f) + w[j][3] * fmaxf(sh[3][j], 0.f);
;         sc += 0.0f;
;         const unsigned u = sortable(sc);
;         if (MODE == 4) {
;           const unsigned um = u & himask;
;           const bool eq = um == pfx[j], zr = u == 0x80000000u;
;           unsigned* qx = hist + (4 * g + j) * C1_HP + 512;
;           if (eq) {
;             const unsigned bin = u & bmask; atomicAdd(&hist[(4 * g + j) * C1_HP + (bin >> 1)], 1u << ((bin & 1u) * 16u));
;             if (!zr) { const unsigned idx = atomicAdd(&qx[320], 1u); if (idx < 64u) qx[256 + idx] = ((unsigned)n << 16) | ((unsigned)(kt * 16 + lr) << 10) | (u & 1023u); }
;           }
;           word[j] |= (u64)((unsigned)(__ballot(um > pfx[j]) >> (16 * g)) & 0xffffu) << (16 * kt);
;           zword[j] |= (u64)((unsigned)(__ballot(zr) >> (16 * g)) & 0xffffu) << (16 * kt);
;         } else if (MODE == 0 || MODE == 3) {
;           if (MODE == 3) base[j] += __popc((unsigned)(__ballot(u == 0x80000000u) >> (16 * g)) & 0xffffu);
.LBB0_914:
	s_or_b64 exec, exec, s[10:11]
	v_cmp_gt_u32_e64 s[10:11], v72, v144
	v_cndmask_b32_e64 v72, 0, 1, vcc
	v_cmp_ne_u32_e64 s[8:9], 0, v72
	v_max_f32_e32 v72, 0, v83
	v_max_f32_e32 v73, 0, v87
	v_pk_mul_f32 v[72:73], v[72:73], v[118:119]
	v_max_f32_e32 v74, 0, v91
	v_max_f32_e32 v75, 0, v75
	v_pk_mul_f32 v[74:75], v[74:75], v[120:121]
	v_add_f32_e32 v72, v72, v73
	v_add_f32_e32 v72, v72, v74
	v_add_f32_e32 v72, v72, v75
	v_add_f32_e32 v72, 0, v72
	v_not_b32_e32 v73, v72
	v_or_b32_e32 v74, 0x80000000, v72
	v_cmp_gt_i32_e32 vcc, 0, v72
	s_nop 1
	v_cndmask_b32_e32 v73, v74, v73, vcc
	v_and_b32_e32 v72, s30, v73
	v_cmp_eq_u32_e64 s[12:13], v72, v145
	v_cmp_eq_u32_e32 vcc, s3, v73
	v_cmp_ne_u32_e64 s[6:7], s3, v73
	s_and_saveexec_b64 s[14:15], s[12:13]
	s_cbranch_execz .LBB0_918
	v_and_b32_e32 v74, s31, v73
	v_lshlrev_b32_e32 v75, 1, v74
	v_and_b32_e32 v75, -4, v75
	v_lshlrev_b32_e32 v74, 4, v74
	v_add_u32_e32 v75, v137, v75
	v_lshlrev_b32_e64 v74, v74, 1
	ds_add_u32 v75, v74 offset:12336
	s_and_b64 exec, exec, s[6:7]
	s_cbranch_execz .LBB0_918
	ds_add_rtn_u32 v74, v137, v174 offset:15664
	s_waitcnt lgkmcnt(0)
	v_cmp_gt_u32_e64 s[6:7], 64, v74
	s_and_b64 exec, exec, s[6:7]
	v_and_b32_e32 v73, 0x3ff, v73
	s_mov_b32 s6, 0x8000
	v_add3_u32 v73, v146, v73, s6
	v_lshl_add_u32 v74, v74, 2, v137
	ds_write_b32 v74, v73 offset:15408
.LBB0_918:
	s_or_b64 exec, exec, s[14:15]
	v_cmp_gt_u32_e64 s[96:97], v72, v145
	v_cndmask_b32_e64 v72, 0, 1, vcc
	v_cmp_ne_u32_e64 s[6:7], 0, v72
	s_waitcnt vmcnt(9)
	v_mfma_f32_16x16x32_f16 v[72:75], v[24:27], v[64:67], 0
	v_mfma_f32_16x16x32_f16 v[76:79], v[4:7], v[64:67], 0
	v_mfma_f32_16x16x32_f16 v[80:83], v[12:15], v[64:67], 0
	v_mfma_f32_16x16x32_f16 v[64:67], v[20:23], v[64:67], 0
	s_waitcnt vmcnt(8)
	v_mfma_f32_16x16x32_f16 v[72:75], v[0:3], v[68:71], v[72:75]
	v_mfma_f32_16x16x32_f16 v[76:79], v[8:11], v[68:71], v[76:79]
	v_mfma_f32_16x16x32_f16 v[80:83], v[16:19], v[68:71], v[80:83]
	v_mfma_f32_16x16x32_f16 v[64:67], v[28:31], v[68:71], v[64:67]
	s_nop 4
	v_max_f32_e32 v68, 0, v72
	v_max_f32_e32 v69, 0, v76
	v_pk_mul_f32 v[68:69], v[68:69], v[106:107]
	v_max_f32_e32 v70, 0, v80
	v_max_f32_e32 v71, 0, v64
	v_pk_mul_f32 v[70:71], v[70:71], v[108:109]
	v_add_f32_e32 v64, v68, v69
	v_add_f32_e32 v64, v64, v70
	v_add_f32_e32 v64, v64, v71
	v_add_f32_e32 v64, 0, v64
	v_not_b32_e32 v68, v64
	v_or_b32_e32 v69, 0x80000000, v64
	v_cmp_gt_i32_e32 vcc, 0, v64
	s_nop 1
	v_cndmask_b32_e32 v68, v69, v68, vcc
	v_and_b32_e32 v64, s30, v68
	v_cmp_eq_u32_e64 s[14:15], v64, v142
	v_cmp_eq_u32_e32 vcc, s3, v68
	v_cmp_ne_u32_e64 s[12:13], s3, v68
	s_and_saveexec_b64 s[16:17], s[14:15]
	s_cbranch_execz .LBB0_922
	v_and_b32_e32 v69, s31, v68
	v_lshlrev_b32_e32 v70, 1, v69
	v_and_b32_e32 v70, -4, v70
	v_lshlrev_b32_e32 v69, 4, v69
	v_add_u32_e32 v70, v137, v70
	v_lshlrev_b32_e64 v69, v69, 1
	ds_add_u32 v70, v69
	s_and_b64 exec, exec, s[12:13]
	s_cbranch_execz .LBB0_922
	ds_add_rtn_u32 v69, v137, v174 offset:3328
	s_waitcnt lgkmcnt(0)
	v_cmp_gt_u32_e64 s[12:13], 64, v69
	s_and_b64 exec, exec, s[12:13]
	v_and_b32_e32 v68, 0x3ff, v68
	s_mov_b32 s12, 0xc000
	v_add3_u32 v68, v146, v68, s12
	v_lshl_add_u32 v69, v69, 2, v137
	ds_write_b32 v69, v68 offset:3072
; #define MFMA16(a, b, c) __builtin_amdgcn_mfma_f32_16x16x32_f16((a), (b), (c), 0, 0, 0)
; DI unsigned sortable(float f) { const unsigned u = __float_as_uint(f); return (u & 0x80000000u) ? ~u : (u | 0x80000000u); }
; template <int MODE> ...
;     ...
;     for (int kt = 0; kt < 4; ++kt) {
;       f32x4 sh[4];
; #pragma unroll
;       for (int h = 0; h < 4; ++h) {
;         sh[h] = (f32x4){0.f, 0.f, 0.f, 0.f};
; #pragma unroll
;         for (int ks = 0; ks < 2; ++ks) sh[h] = MFMA16(qf[h][ks], kf[kt][ks], sh[h]);
;       }
; #pragma unroll
;       for (int j = 0; j < 4; ++j) {
;         float sc = w[j][0] * fmaxf(sh[0][j], 0.f) + w[j][1] * fmaxf(sh[1][j], 0.f) + w[j][2] * fmaxf(sh[2][j], 0.f) + w[j][3] * fmaxf(sh[3][j], 0.f);
;         sc += 0.0f;
;         const unsigned u = sortable(sc);
;         if (MODE == 4) {
;           const unsigned um = u & himask;
;           const bool eq = um == pfx[j], zr = u == 0x80000000u;
;           unsigned* qx = hist + (4 * g + j) * C1_HP + 512;
;           if (eq) {
;             const unsigned bin = u & bmask; atomicAdd(&hist[(4 * g + j) * C1_HP + (bin >> 1)], 1u << ((bin & 1u) * 16u));
;             if (!zr) { const unsigned idx = atomicAdd(&qx[320], 1u); if (idx < 64u) qx[256 + idx] = ((unsigned)n << 16) | ((unsigned)(kt * 16 + lr) << 10) | (u & 1023u); }
;           }
;           word[j] |= (u64)((unsigned)(__ballot(um > pfx[j]) >> (16 * g)) & 0xffffu) << (16 * kt);
;           zword[j] |= (u64)((unsigned)(__ballot(zr) >> (16 * g)) & 0xffffu) << (16 * kt);
;         } else if (MODE == 0 || MODE == 3) {
;           if (MODE == 3) base[j] += __popc((unsigned)(__ballot(u == 0x80000000u) >> (16 * g)) & 0xffffu);
.LBB0_922:
	s_or_b64 exec, exec, s[16:17]
	v_cmp_gt_u32_e64 s[14:15], v64, v142
	v_cndmask_b32_e64 v64, 0, 1, vcc
	v_cmp_ne_u32_e64 s[12:13], 0, v64
	v_max_f32_e32 v68, 0, v73
	v_max_f32_e32 v69, 0, v77
	v_pk_mul_f32 v[68:69], v[68:69], v[110:111]
	v_max_f32_e32 v64, 0, v81
	v_max_f32_e32 v65, 0, v65
	v_pk_mul_f32 v[64:65], v[64:65], v[112:113]
	v_add_f32_e32 v68, v68, v69
	v_add_f32_e32 v64, v68, v64
	v_add_f32_e32 v64, v64, v65
	v_add_f32_e32 v64, 0, v64
	v_not_b32_e32 v65, v64
	v_or_b32_e32 v68, 0x80000000, v64
	v_cmp_gt_i32_e32 vcc, 0, v64
	s_nop 1
	v_cndmask_b32_e32 v65, v68, v65, vcc
	v_and_b32_e32 v64, s30, v65
	v_cmp_eq_u32_e64 s[18:19], v64, v143
	v_cmp_eq_u32_e32 vcc, s3, v65
	v_cmp_ne_u32_e64 s[16:17], s3, v65
	s_and_saveexec_b64 s[20:21], s[18:19]
	s_cbranch_execz .LBB0_926
	v_and_b32_e32 v68, s31, v65
	v_lshlrev_b32_e32 v69, 1, v68
	v_and_b32_e32 v69, -4, v69
	v_lshlrev_b32_e32 v68, 4, v68
	v_add_u32_e32 v69, v137, v69
	v_lshlrev_b32_e64 v68, v68, 1
	ds_add_u32 v69, v68 offset:4112
	s_and_b64 exec, exec, s[16:17]
	s_cbranch_execz .LBB0_926
	ds_add_rtn_u32 v68, v137, v174 offset:7440
	s_waitcnt lgkmcnt(0)
	v_cmp_gt_u32_e64 s[16:17], 64, v68
	s_and_b64 exec, exec, s[16:17]
	v_and_b32_e32 v65, 0x3ff, v65
	s_mov_b32 s16, 0xc000
	v_add3_u32 v65, v146, v65, s16
	v_lshl_add_u32 v68, v68, 2, v137
	ds_write_b32 v68, v65 offset:7184
.LBB0_926:
	s_or_b64 exec, exec, s[20:21]
	v_cmp_gt_u32_e64 s[18:19], v64, v143
	v_cndmask_b32_e64 v64, 0, 1, vcc
	v_cmp_ne_u32_e64 s[16:17], 0, v64
	v_max_f32_e32 v64, 0, v74
	v_max_f32_e32 v65, 0, v78
	v_pk_mul_f32 v[64:65], v[64:65], v[114:115]
	v_max_f32_e32 v68, 0, v82
	v_max_f32_e32 v69, 0, v66
	v_pk_mul_f32 v[68:69], v[68:69], v[116:117]
	v_add_f32_e32 v64, v64, v65
	v_add_f32_e32 v64, v64, v68
	v_add_f32_e32 v64, v64, v69
	v_add_f32_e32 v64, 0, v64
	v_not_b32_e32 v65, v64
	v_or_b32_e32 v66, 0x80000000, v64
	v_cmp_gt_i32_e32 vcc, 0, v64
	s_nop 1
	v_cndmask_b32_e32 v65, v66, v65, vcc
	v_and_b32_e32 v64, s30, v65
	v_cmp_eq_u32_e64 s[22:23], v64, v144
	v_cmp_eq_u32_e64 s[20:21], s3, v65
	v_cmp_ne_u32_e32 vcc, s3, v65
	s_and_saveexec_b64 s[24:25], s[22:23]
	s_cbranch_execz .LBB0_930
	v_and_b32_e32 v66, s31, v65
	v_lshlrev_b32_e32 v68, 1, v66
	v_and_b32_e32 v68, -4, v68
	v_lshlrev_b32_e32 v66, 4, v66
	v_add_u32_e32 v68, v137, v68
	v_lshlrev_b32_e64 v66, v66, 1
	ds_add_u32 v68, v66 offset:8224
	s_and_b64 exec, exec, vcc
	s_cbranch_execz .LBB0_930
	ds_add_rtn_u32 v66, v137, v174 offset:11552
	s_waitcnt lgkmcnt(0)
	v_cmp_gt_u32_e32 vcc, 64, v66
	s_and_b64 exec, exec, vcc
	v_and_b32_e32 v65, 0x3ff, v65
	s_mov_b32 s22, 0xc000
	v_add3_u32 v65, v146, v65, s22
	v_lshl_add_u32 v66, v66, 2, v137
	ds_write_b32 v66, v65 offset:11296
.LBB0_930:
	s_or_b64 exec, exec, s[24:25]
	v_cmp_gt_u32_e64 s[28:29], v64, v144
	v_cndmask_b32_e64 v64, 0, 1, s[20:21]
	v_cmp_ne_u32_e64 s[24:25], 0, v64
	v_max_f32_e32 v64, 0, v75
	v_max_f32_e32 v65, 0, v79
	v_pk_mul_f32 v[64:65], v[64:65], v[118:119]
	v_max_f32_e32 v66, 0, v83
	v_max_f32_e32 v67, 0, v67
	v_pk_mul_f32 v[66:67], v[66:67], v[120:121]
	v_add_f32_e32 v64, v64, v65
	v_add_f32_e32 v64, v64, v66
	v_add_f32_e32 v64, v64, v67
	v_add_f32_e32 v64, 0, v64
	v_not_b32_e32 v65, v64
	v_or_b32_e32 v66, 0x80000000, v64
	v_cmp_gt_i32_e64 s[20:21], 0, v64
	s_nop 1
	v_cndmask_b32_e64 v65, v66, v65, s[20:21]
	v_and_b32_e32 v64, s30, v65
	v_cmp_eq_u32_e32 vcc, v64, v145
	v_cmp_eq_u32_e64 s[22:23], s3, v65
	v_cmp_ne_u32_e64 s[20:21], s3, v65
	s_and_saveexec_b64 s[34:35], vcc
	s_cbranch_execz .LBB0_934
	v_and_b32_e32 v66, s31, v65
	v_lshlrev_b32_e32 v67, 1, v66
	v_and_b32_e32 v67, -4, v67
	v_lshlrev_b32_e32 v66, 4, v66
	v_add_u32_e32 v67, v137, v67
	v_lshlrev_b32_e64 v66, v66, 1
	ds_add_u32 v67, v66 offset:12336
	s_and_b64 exec, exec, s[20:21]
	s_cbranch_execz .LBB0_934
	ds_add_rtn_u32 v66, v137, v174 offset:15664
	s_waitcnt lgkmcnt(0)
	v_cmp_gt_u32_e32 vcc, 64, v66
	s_and_b64 exec, exec, vcc
	v_and_b32_e32 v65, 0x3ff, v65
	s_mov_b32 s20, 0xc000
	v_add3_u32 v65, v146, v65, s20
	v_lshl_add_u32 v66, v66, 2, v137
	ds_write_b32 v66, v65 offset:15408

; #define MFMA16(a, b, c) __builtin_amdgcn_mfma_f32_16x16x32_f16((a), (b), (c), 0, 0, 0)
; template <int MODE> ...
;     ...
; #pragma unroll
;     for (int kt = 0; kt < 4; ++kt) {
;       f32x4 sh[4];
; #pragma unroll
;       for (int h = 0; h < 4; ++h) {
;         sh[h] = (f32x4){0.f, 0.f, 0.f, 0.f};
; #pragma unroll
;         for (int ks = 0; ks < 2; ++ks) sh[h] = MFMA16(qf[h][ks], kf[kt][ks], sh[h]);
;       }
; #pragma unroll
;       for (int j = 0; j < 4; ++j) {
;         float sc = w[j][0] * fmaxf(sh[0][j], 0.f) + w[j][1] * fmaxf(sh[1][j], 0.f) + w[j][2] * fmaxf(sh[2][j], 0.f) + w[j][3] * fmaxf(sh[3][j], 0.f);
;         sc += 0.0f;
;         const unsigned u = sortable(sc);
;         if (MODE == 4) {
;           const unsigned um = u & himask;
;           const bool eq = um == pfx[j], zr = u == 0x80000000u;
;           unsigned* qx = hist + (4 * g + j) * C1_HP + 512;
;           if (eq) {
;             const unsigned bin = u & bmask; atomicAdd(&hist[(4 * g + j) * C1_HP + (bin >> 1)], 1u << ((bin & 1u) * 16u));
;             if (!zr) { const unsigned idx = atomicAdd(&qx[320], 1u); if (idx < 64u) qx[256 + idx] = ((unsigned)n << 16) | ((unsigned)(kt * 16 + lr) << 10) | (u & 1023u); }
;           }
;           word[j] |= (u64)((unsigned)(__ballot(um > pfx[j]) >> (16 * g)) & 0xffffu) << (16 * kt);
;           zword[j] |= (u64)((unsigned)(__ballot(zr) >> (16 * g)) & 0xffffu) << (16 * kt);
;         } else if (MODE == 0 || MODE == 3) {
;           if (MODE == 3) base[j] += __popc((unsigned)(__ballot(u == 0x80000000u) >> (16 * g)) & 0xffffu);
;           if (((u ^ pfx[j]) & himask) == 0u) { const unsigned bin = (u >> shift) & bmask; atomicAdd(&hist[(4 * g + j) * C1_HP + (bin >> 1)], 1u << ((bin & 1u) * 16u)); }
;         } else {
;           const bool eq = u == pfx[j];
;           const unsigned fe = (unsigned)(__ballot(eq) >> (16 * g)) & 0xffffu;
;           if (MODE == 1) {
;             base[j] += __popc(fe);
;           } else {
;             const unsigned rank = base[j] + __popc(fe & ((1u << lr) - 1u));
;             const bool sel = (u > pfx[j]) || (eq && rank < need[j]);
;             base[j] += __popc(fe);
;             const unsigned fs = (unsigned)(__ballot(sel) >> (16 * g)) & 0xffffu;
;             word[j] |= (u64)fs << (16 * kt);
;           }
;         }
.LBB0_993:
	s_waitcnt vmcnt(1)
	v_mov_b64_e32 v[78:79], v[66:67]
	v_mov_b64_e32 v[76:77], v[64:65]
	v_mov_b64_e32 v[66:67], v[42:43]
	v_mov_b64_e32 v[86:87], v[58:59]
	v_mov_b64_e32 v[96:97], v[50:51]
	v_mov_b64_e32 v[64:65], v[40:41]
	v_mov_b64_e32 v[84:85], v[56:57]
	v_mov_b64_e32 v[94:95], v[48:49]
	v_mfma_f32_16x16x32_f16 v[40:43], v[24:27], v[64:67], 0
	v_mov_b64_e32 v[100:101], v[46:47]
	v_mov_b64_e32 v[98:99], v[44:45]
	v_mov_b32_e32 v44, v89
	v_mfma_f32_16x16x32_f16 v[48:51], v[4:7], v[64:67], 0
	v_add_u32_e32 v89, 4, v44
	v_cmp_lt_i32_e32 vcc, s2, v89
	s_waitcnt vmcnt(0)
	v_mov_b64_e32 v[74:75], v[70:71]
	v_mfma_f32_16x16x32_f16 v[56:59], v[12:15], v[64:67], 0
	v_cndmask_b32_e32 v44, v89, v44, vcc
	v_mov_b64_e32 v[72:73], v[68:69]
	v_mov_b64_e32 v[82:83], v[62:63]
	v_mfma_f32_16x16x32_f16 v[154:157], v[20:23], v[64:67], 0
	v_mov_b64_e32 v[92:93], v[54:55]
	v_lshlrev_b32_e32 v68, 6, v44
	v_mov_b64_e32 v[80:81], v[60:61]
	v_mfma_f32_16x16x32_f16 v[136:139], v[0:3], v[98:101], v[40:43]
	v_mov_b64_e32 v[90:91], v[52:53]
	v_mad_i64_i32 v[44:45], s[4:5], v68, s0, v[122:123]
	v_mfma_f32_16x16x32_f16 v[140:143], v[8:11], v[98:101], v[48:51]
	v_or_b32_e32 v52, 16, v68
	s_nop 3
	v_max_f32_e32 v102, 0, v136
	v_mfma_f32_16x16x32_f16 v[144:147], v[16:19], v[98:101], v[56:59]
	v_or_b32_e32 v60, 32, v68
	v_max_f32_e32 v103, v140, v140
	v_max_f32_e32 v103, 0, v103
	v_mfma_f32_16x16x32_f16 v[98:101], v[28:31], v[98:101], v[154:157]
	v_mul_f32_e64 v102, v102, v106
	v_mul_f32_e64 v103, v103, v107
	s_nop 1
	v_max_f32_e32 v105, v144, v144
	v_mov_b32_e32 v140, v102
	v_max_f32_e32 v154, 0, v105
	v_or_b32_e32 v68, 48, v68
	v_max_f32_e32 v155, 0, v98
	v_max_f32_e32 v136, 0, v137
	v_max_f32_e32 v137, 0, v141
	v_pk_mul_f32 v[136:137], v[136:137], v[110:111]
	v_max_f32_e32 v98, 0, v145
	v_max_f32_e32 v99, 0, v99
	v_pk_mul_f32 v[154:155], v[154:155], v[108:109]
	v_pk_mul_f32 v[98:99], v[98:99], v[112:113]
	v_mov_b32_e32 v141, v136
	v_mov_b32_e32 v136, v103
	v_pk_add_f32 v[102:103], v[140:141], v[136:137]
	v_mov_b32_e32 v136, v154
	v_mov_b32_e32 v137, v98
	v_pk_add_f32 v[102:103], v[102:103], v[136:137]
	v_mov_b32_e32 v98, v155
	v_pk_add_f32 v[98:99], v[102:103], v[98:99]
	v_mad_i64_i32 v[52:53], s[4:5], v52, s0, v[122:123]
	v_pk_add_f32 v[98:99], v[98:99], 0 op_sel_hi:[1,0]
	v_mad_i64_i32 v[60:61], s[4:5], v60, s0, v[122:123]
	v_mad_i64_i32 v[68:69], s[4:5], v68, s0, v[122:123]
	v_and_b32_e32 v103, 0x7fffffff, v99
	v_and_b32_e32 v102, 0x7fffffff, v98
	v_xor_b32_e32 v105, -1, v99
	v_pk_add_f32 v[102:103], v[102:103], 0 neg_lo:[1,1] neg_hi:[1,1]
	v_cmp_gt_i32_e64 s[4:5], 0, v99
	v_xor_b32_e32 v135, -1, v98
	global_load_dwordx4 v[40:43], v[44:45], off
	s_nop 0
	global_load_dwordx4 v[44:47], v[44:45], off offset:64
	v_cndmask_b32_e64 v99, v103, v105, s[4:5]
	v_cmp_gt_i32_e64 s[4:5], 0, v98
	v_cmp_eq_u32_e64 s[50:51], v99, v33
	v_max_f32_e32 v99, v142, v142
	v_cndmask_b32_e64 v98, v102, v135, s[4:5]
	v_cmp_eq_u32_e64 s[48:49], v98, v32
	v_max_f32_e32 v98, 0, v138
	v_max_f32_e32 v99, 0, v99
	v_pk_mul_f32 v[102:103], v[98:99], v[114:115]
	v_max_f32_e32 v98, 0, v146
	v_max_f32_e32 v99, 0, v100
	v_pk_mul_f32 v[140:141], v[98:99], v[116:117]
	v_max_f32_e32 v98, 0, v139
	v_max_f32_e32 v99, 0, v143
	v_pk_mul_f32 v[136:137], v[98:99], v[118:119]
	v_max_f32_e32 v138, 0, v147
	v_max_f32_e32 v139, 0, v101
	v_pk_mul_f32 v[142:143], v[138:139], v[120:121]
	v_mov_b32_e32 v138, v102
	v_mov_b32_e32 v139, v136
	v_mov_b32_e32 v136, v103
	v_pk_add_f32 v[102:103], v[138:139], v[136:137]
	v_mov_b32_e32 v144, v140
	v_mov_b32_e32 v145, v142
	v_pk_add_f32 v[102:103], v[102:103], v[144:145]
	v_mov_b32_e32 v142, v141
	v_mfma_f32_16x16x32_f16 v[98:101], v[24:27], v[94:97], 0
	v_add_f32_e64 v102, v102, v142
	v_add_f32_e64 v103, v103, v143
	global_load_dwordx4 v[48:51], v[52:53], off
	s_nop 0
	global_load_dwordx4 v[52:55], v[52:53], off offset:64
	v_pk_add_f32 v[102:103], v[102:103], 0 op_sel_hi:[1,0]
	v_mfma_f32_16x16x32_f16 v[136:139], v[4:7], v[94:97], 0
	v_and_b32_e32 v145, 0x7fffffff, v103
	v_and_b32_e32 v144, 0x7fffffff, v102
	v_xor_b32_e32 v105, -1, v103
	v_mfma_f32_16x16x32_f16 v[140:143], v[12:15], v[94:97], 0
	v_add_f32_e64 v144, -v144, neg(0)
	v_add_f32_e64 v145, -v145, neg(0)
	v_cmp_gt_i32_e64 s[4:5], 0, v103
	v_xor_b32_e32 v135, -1, v102
	v_mfma_f32_16x16x32_f16 v[94:97], v[20:23], v[94:97], 0
	v_cndmask_b32_e64 v103, v145, v105, s[4:5]
	v_cmp_gt_i32_e64 s[4:5], 0, v102
	v_cmp_eq_u32_e64 s[54:55], v103, v35
	v_mfma_f32_16x16x32_f16 v[98:101], v[0:3], v[90:93], v[98:101]
	v_cndmask_b32_e64 v102, v144, v135, s[4:5]
	v_cmp_eq_u32_e64 s[52:53], v102, v34
	global_load_dwordx4 v[56:59], v[60:61], off
	s_nop 0
	global_load_dwordx4 v[60:63], v[60:61], off offset:64
	v_mfma_f32_16x16x32_f16 v[136:139], v[8:11], v[90:93], v[136:139]
	global_load_dwordx4 v[64:67], v[68:69], off
	s_nop 0
	global_load_dwordx4 v[68:71], v[68:69], off offset:64
	v_mfma_f32_16x16x32_f16 v[140:143], v[16:19], v[90:93], v[140:143]
	v_mfma_f32_16x16x32_f16 v[90:93], v[28:31], v[90:93], v[94:97]
	s_nop 2
	v_max_f32_e32 v94, v98, v98
	v_max_f32_e32 v95, v136, v136
	s_nop 2
	v_max_f32_e32 v97, 0, v90
	v_max_f32_e32 v98, 0, v99
	v_max_f32_e32 v94, 0, v94
	v_max_f32_e32 v95, 0, v95
	v_max_f32_e32 v99, 0, v137
	v_pk_mul_f32 v[94:95], v[94:95], v[106:107]
	v_max_f32_e32 v96, 0, v140
	v_pk_mul_f32 v[98:99], v[98:99], v[110:111]
	v_max_f32_e32 v90, 0, v141
	v_max_f32_e32 v91, 0, v91
	v_pk_mul_f32 v[96:97], v[96:97], v[108:109]
	v_pk_mul_f32 v[90:91], v[90:91], v[112:113]
	v_mov_b32_e32 v102, v94
	v_mov_b32_e32 v103, v98
	v_mov_b32_e32 v98, v95
	v_pk_add_f32 v[94:95], v[102:103], v[98:99]
	v_mov_b32_e32 v98, v96
; #define MFMA16(a, b, c) __builtin_amdgcn_mfma_f32_16x16x32_f16((a), (b), (c), 0, 0, 0)
; template <int MODE> ...
;     ...
; #pragma unroll
;     for (int kt = 0; kt < 4; ++kt) {
;       f32x4 sh[4];
; #pragma unroll
;       for (int h = 0; h < 4; ++h) {
;         sh[h] = (f32x4){0.f, 0.f, 0.f, 0.f};
; #pragma unroll
;         for (int ks = 0; ks < 2; ++ks) sh[h] = MFMA16(qf[h][ks], kf[kt][ks], sh[h]);
;       }
; #pragma unroll
;       for (int j = 0; j < 4; ++j) {
;         float sc = w[j][0] * fmaxf(sh[0][j], 0.f) + w[j][1] * fmaxf(sh[1][j], 0.f) + w[j][2] * fmaxf(sh[2][j], 0.f) + w[j][3] * fmaxf(sh[3][j], 0.f);
;         sc += 0.0f;
;         const unsigned u = sortable(sc);
;         if (MODE == 4) {
;           const unsigned um = u & himask;
;           const bool eq = um == pfx[j], zr = u == 0x80000000u;
;           unsigned* qx = hist + (4 * g + j) * C1_HP + 512;
;           if (eq) {
;             const unsigned bin = u & bmask; atomicAdd(&hist[(4 * g + j) * C1_HP + (bin >> 1)], 1u << ((bin & 1u) * 16u));
;             if (!zr) { const unsigned idx = atomicAdd(&qx[320], 1u); if (idx < 64u) qx[256 + idx] = ((unsigned)n << 16) | ((unsigned)(kt * 16 + lr) << 10) | (u & 1023u); }
;           }
;           word[j] |= (u64)((unsigned)(__ballot(um > pfx[j]) >> (16 * g)) & 0xffffu) << (16 * kt);
;           zword[j] |= (u64)((unsigned)(__ballot(zr) >> (16 * g)) & 0xffffu) << (16 * kt);
;         } else if (MODE == 0 || MODE == 3) {
;           if (MODE == 3) base[j] += __popc((unsigned)(__ballot(u == 0x80000000u) >> (16 * g)) & 0xffffu);
;           if (((u ^ pfx[j]) & himask) == 0u) { const unsigned bin = (u >> shift) & bmask; atomicAdd(&hist[(4 * g + j) * C1_HP + (bin >> 1)], 1u << ((bin & 1u) * 16u)); }
;         } else {
;           const bool eq = u == pfx[j];
;           const unsigned fe = (unsigned)(__ballot(eq) >> (16 * g)) & 0xffffu;
;           if (MODE == 1) {
;             base[j] += __popc(fe);
;           } else {
;             const unsigned rank = base[j] + __popc(fe & ((1u << lr) - 1u));
;             const bool sel = (u > pfx[j]) || (eq && rank < need[j]);
;             base[j] += __popc(fe);
;             const unsigned fs = (unsigned)(__ballot(sel) >> (16 * g)) & 0xffffu;
;             word[j] |= (u64)fs << (16 * kt);
;           }
;         }
	v_mov_b32_e32 v99, v90
	v_pk_add_f32 v[94:95], v[94:95], v[98:99]
	v_mov_b32_e32 v90, v97
	v_pk_add_f32 v[90:91], v[94:95], v[90:91]
	s_nop 0
	v_pk_add_f32 v[90:91], v[90:91], 0 op_sel_hi:[1,0]
	s_nop 0
	v_and_b32_e32 v95, 0x7fffffff, v91
	v_and_b32_e32 v94, 0x7fffffff, v90
	v_xor_b32_e32 v96, -1, v91
	v_pk_add_f32 v[94:95], v[94:95], 0 neg_lo:[1,1] neg_hi:[1,1]
	v_cmp_gt_i32_e64 s[4:5], 0, v91
	v_xor_b32_e32 v97, -1, v90
	s_nop 0
	v_cndmask_b32_e64 v91, v95, v96, s[4:5]
	v_cmp_gt_i32_e64 s[4:5], 0, v90
	v_cmp_eq_u32_e64 s[58:59], v91, v33
	v_max_f32_e32 v91, v138, v138
	v_cndmask_b32_e64 v90, v94, v97, s[4:5]
	v_cmp_eq_u32_e64 s[56:57], v90, v32
	v_max_f32_e32 v90, 0, v100
	v_max_f32_e32 v91, 0, v91
	v_pk_mul_f32 v[94:95], v[90:91], v[114:115]
	v_max_f32_e32 v90, 0, v142
	v_max_f32_e32 v91, 0, v92
	v_pk_mul_f32 v[98:99], v[90:91], v[116:117]
	v_max_f32_e32 v90, 0, v101
	v_max_f32_e32 v91, 0, v139
	v_pk_mul_f32 v[96:97], v[90:91], v[118:119]
	v_max_f32_e32 v100, 0, v143
	v_max_f32_e32 v101, 0, v93
	v_pk_mul_f32 v[100:101], v[100:101], v[120:121]
	v_mov_b32_e32 v102, v94
	v_mov_b32_e32 v103, v96
	v_mov_b32_e32 v96, v95
	v_pk_add_f32 v[102:103], v[102:103], v[96:97]
	v_mov_b32_e32 v136, v98
	v_mov_b32_e32 v137, v100
	v_pk_add_f32 v[102:103], v[102:103], v[136:137]
	v_mov_b32_e32 v100, v99
	v_pk_add_f32 v[98:99], v[102:103], v[100:101]
	v_mfma_f32_16x16x32_f16 v[90:93], v[24:27], v[84:87], 0
	v_add_f32_e64 v102, v98, 0
	v_add_f32_e64 v103, v99, 0
	v_and_b32_e32 v137, 0x7fffffff, v103
	v_mfma_f32_16x16x32_f16 v[94:97], v[4:7], v[84:87], 0
	v_and_b32_e32 v136, 0x7fffffff, v102
	v_xor_b32_e32 v105, -1, v103
	v_pk_add_f32 v[136:137], v[136:137], 0 neg_lo:[1,1] neg_hi:[1,1]
	v_mfma_f32_16x16x32_f16 v[98:101], v[12:15], v[84:87], 0
	v_cmp_gt_i32_e64 s[4:5], 0, v103
	v_xor_b32_e32 v135, -1, v102
	v_mfma_f32_16x16x32_f16 v[84:87], v[20:23], v[84:87], 0
	v_cndmask_b32_e64 v103, v137, v105, s[4:5]
	v_cmp_gt_i32_e64 s[4:5], 0, v102
	v_cmp_eq_u32_e64 s[6:7], v103, v35
	v_mfma_f32_16x16x32_f16 v[90:93], v[0:3], v[80:83], v[90:93]
	v_cndmask_b32_e64 v102, v136, v135, s[4:5]
	v_cmp_eq_u32_e64 s[4:5], v102, v34
	v_mfma_f32_16x16x32_f16 v[94:97], v[8:11], v[80:83], v[94:97]
	v_mfma_f32_16x16x32_f16 v[98:101], v[16:19], v[80:83], v[98:101]
	v_mfma_f32_16x16x32_f16 v[80:83], v[28:31], v[80:83], v[84:87]
	s_nop 2
	v_max_f32_e32 v84, v90, v90
	s_nop 1
	v_max_f32_e32 v85, v94, v94
	s_nop 0
	v_max_f32_e32 v87, 0, v80
	v_max_f32_e32 v90, 0, v91
	v_max_f32_e32 v84, 0, v84
	v_max_f32_e32 v85, 0, v85
	v_max_f32_e32 v91, 0, v95
	v_pk_mul_f32 v[84:85], v[84:85], v[106:107]
	v_max_f32_e32 v86, 0, v98
	v_pk_mul_f32 v[90:91], v[90:91], v[110:111]
	v_max_f32_e32 v80, 0, v99
	v_max_f32_e32 v81, 0, v81
	v_pk_mul_f32 v[86:87], v[86:87], v[108:109]
	v_pk_mul_f32 v[80:81], v[80:81], v[112:113]
	v_mov_b32_e32 v94, v84
	v_mov_b32_e32 v95, v90
	v_mov_b32_e32 v90, v85
	v_pk_add_f32 v[84:85], v[94:95], v[90:91]
	v_mov_b32_e32 v90, v86
	v_mov_b32_e32 v91, v80
	v_pk_add_f32 v[84:85], v[84:85], v[90:91]
	v_mov_b32_e32 v80, v87
	v_pk_add_f32 v[80:81], v[84:85], v[80:81]
	s_nop 0
	v_pk_add_f32 v[80:81], v[80:81], 0 op_sel_hi:[1,0]
	s_nop 0
	v_and_b32_e32 v85, 0x7fffffff, v81
	v_and_b32_e32 v84, 0x7fffffff, v80
	v_xor_b32_e32 v86, -1, v81
	v_pk_add_f32 v[84:85], v[84:85], 0 neg_lo:[1,1] neg_hi:[1,1]
	v_cmp_gt_i32_e64 s[8:9], 0, v81
	v_xor_b32_e32 v87, -1, v80
	s_nop 0
	v_cndmask_b32_e64 v81, v85, v86, s[8:9]
	v_cmp_gt_i32_e64 s[8:9], 0, v80
	v_cmp_eq_u32_e64 s[10:11], v81, v33
	v_max_f32_e32 v81, v96, v96
	v_cndmask_b32_e64 v80, v84, v87, s[8:9]
	v_cmp_eq_u32_e64 s[8:9], v80, v32
	v_max_f32_e32 v80, 0, v92
	v_max_f32_e32 v81, 0, v81
	v_pk_mul_f32 v[84:85], v[80:81], v[114:115]
	v_max_f32_e32 v80, 0, v100
	v_max_f32_e32 v81, 0, v82
	v_pk_mul_f32 v[90:91], v[80:81], v[116:117]
	v_max_f32_e32 v80, 0, v93
	v_max_f32_e32 v81, 0, v97
	v_pk_mul_f32 v[86:87], v[80:81], v[118:119]
	v_max_f32_e32 v92, 0, v101
	v_max_f32_e32 v93, 0, v83
	v_pk_mul_f32 v[92:93], v[92:93], v[120:121]
	v_mov_b32_e32 v94, v84
	v_mov_b32_e32 v95, v86
	v_mov_b32_e32 v86, v85
	v_pk_add_f32 v[94:95], v[94:95], v[86:87]
	v_mov_b32_e32 v96, v90
	v_mov_b32_e32 v97, v92
	v_pk_add_f32 v[94:95], v[94:95], v[96:97]
	v_mov_b32_e32 v92, v91
	v_pk_add_f32 v[90:91], v[94:95], v[92:93]
	v_mfma_f32_16x16x32_f16 v[80:83], v[24:27], v[76:79], 0
	v_add_f32_e64 v94, v90, 0
	v_add_f32_e64 v95, v91, 0
	v_and_b32_e32 v97, 0x7fffffff, v95
	v_mfma_f32_16x16x32_f16 v[84:87], v[4:7], v[76:79], 0
	v_and_b32_e32 v96, 0x7fffffff, v94
	v_xor_b32_e32 v98, -1, v95
	v_pk_add_f32 v[96:97], v[96:97], 0 neg_lo:[1,1] neg_hi:[1,1]
	v_mfma_f32_16x16x32_f16 v[90:93], v[12:15], v[76:79], 0
	v_cmp_gt_i32_e64 s[12:13], 0, v95
	v_xor_b32_e32 v99, -1, v94
	v_mfma_f32_16x16x32_f16 v[76:79], v[20:23], v[76:79], 0
	v_cndmask_b32_e64 v95, v97, v98, s[12:13]
; template <int MODE> ...
;     ...
; #pragma unroll
;     for (int kt = 0; kt < 4; ++kt) {
;       f32x4 sh[4];
; #pragma unroll
;       for (int h = 0; h < 4; ++h) {
;         sh[h] = (f32x4){0.f, 0.f, 0.f, 0.f};
; #pragma unroll
;         for (int ks = 0; ks < 2; ++ks) sh[h] = MFMA16(qf[h][ks], kf[kt][ks], sh[h]);
;       }
; #pragma unroll
;       for (int j = 0; j < 4; ++j) {
;         float sc = w[j][0] * fmaxf(sh[0][j], 0.f) + w[j][1] * fmaxf(sh[1][j], 0.f) + w[j][2] * fmaxf(sh[2][j], 0.f) + w[j][3] * fmaxf(sh[3][j], 0.f);
;         sc += 0.0f;
;         const unsigned u = sortable(sc);
;         if (MODE == 4) {
;           const unsigned um = u & himask;
;           const bool eq = um == pfx[j], zr = u == 0x80000000u;
;           unsigned* qx = hist + (4 * g + j) * C1_HP + 512;
;           if (eq) {
;             const unsigned bin = u & bmask; atomicAdd(&hist[(4 * g + j) * C1_HP + (bin >> 1)], 1u << ((bin & 1u) * 16u));
;             if (!zr) { const unsigned idx = atomicAdd(&qx[320], 1u); if (idx < 64u) qx[256 + idx] = ((unsigned)n << 16) | ((unsigned)(kt * 16 + lr) << 10) | (u & 1023u); }
;           }
;           word[j] |= (u64)((unsigned)(__ballot(um > pfx[j]) >> (16 * g)) & 0xffffu) << (16 * kt);
;           zword[j] |= (u64)((unsigned)(__ballot(zr) >> (16 * g)) & 0xffffu) << (16 * kt);
;         } else if (MODE == 0 || MODE == 3) {
;           if (MODE == 3) base[j] += __popc((unsigned)(__ballot(u == 0x80000000u) >> (16 * g)) & 0xffffu);
;           if (((u ^ pfx[j]) & himask) == 0u) { const unsigned bin = (u >> shift) & bmask; atomicAdd(&hist[(4 * g + j) * C1_HP + (bin >> 1)], 1u << ((bin & 1u) * 16u)); }
;         } else {
;           const bool eq = u == pfx[j];
;           const unsigned fe = (unsigned)(__ballot(eq) >> (16 * g)) & 0xffffu;
;           if (MODE == 1) {
;             base[j] += __popc(fe);
;           } else {
;             const unsigned rank = base[j] + __popc(fe & ((1u << lr) - 1u));
;             const bool sel = (u > pfx[j]) || (eq && rank < need[j]);
;             base[j] += __popc(fe);
;             const unsigned fs = (unsigned)(__ballot(sel) >> (16 * g)) & 0xffffu;
;             word[j] |= (u64)fs << (16 * kt);
;           }
;         }
;       }
;     }
;     if ((MODE == 1 || MODE == 3) && lr == 0) {
; #pragma unroll
;       for (int j = 0; j < 4; ++j) cnt[(4 * g + j) * 64 + n] = (unsigned short)base[j];
;     }
	v_cmp_gt_i32_e64 s[12:13], 0, v94
	v_cmp_eq_u32_e64 s[14:15], v95, v35
	v_mfma_f32_16x16x32_f16 v[80:83], v[0:3], v[72:75], v[80:83]
	v_cndmask_b32_e64 v94, v96, v99, s[12:13]
	v_cmp_eq_u32_e64 s[12:13], v94, v34
	v_mfma_f32_16x16x32_f16 v[84:87], v[8:11], v[72:75], v[84:87]
	v_mfma_f32_16x16x32_f16 v[90:93], v[16:19], v[72:75], v[90:93]
	v_mfma_f32_16x16x32_f16 v[72:75], v[28:31], v[72:75], v[76:79]
	s_nop 2
	v_max_f32_e32 v76, v80, v80
	s_nop 1
	v_max_f32_e32 v77, v84, v84
	s_nop 0
	v_max_f32_e32 v79, 0, v72
	v_max_f32_e32 v80, 0, v81
	v_max_f32_e32 v76, 0, v76
	v_max_f32_e32 v77, 0, v77
	v_max_f32_e32 v81, 0, v85
	v_pk_mul_f32 v[76:77], v[76:77], v[106:107]
	v_max_f32_e32 v78, 0, v90
	v_pk_mul_f32 v[80:81], v[80:81], v[110:111]
	v_max_f32_e32 v72, 0, v91
	v_max_f32_e32 v73, 0, v73
	v_pk_mul_f32 v[78:79], v[78:79], v[108:109]
	v_pk_mul_f32 v[72:73], v[72:73], v[112:113]
	v_mov_b32_e32 v84, v76
	v_mov_b32_e32 v85, v80
	v_mov_b32_e32 v80, v77
	v_pk_add_f32 v[76:77], v[84:85], v[80:81]
	v_mov_b32_e32 v80, v78
	v_mov_b32_e32 v81, v72
	v_pk_add_f32 v[76:77], v[76:77], v[80:81]
	v_mov_b32_e32 v72, v79
	v_pk_add_f32 v[72:73], v[76:77], v[72:73]
	v_pk_add_f32 v[72:73], v[72:73], 0 op_sel_hi:[1,0]
	v_and_b32_e32 v77, 0x7fffffff, v73
	v_and_b32_e32 v76, 0x7fffffff, v72
	v_xor_b32_e32 v78, -1, v73
	v_pk_add_f32 v[76:77], v[76:77], 0 neg_lo:[1,1] neg_hi:[1,1]
	v_cmp_gt_i32_e64 s[16:17], 0, v73
	v_xor_b32_e32 v79, -1, v72
	v_max_f32_e32 v75, 0, v75
	v_cndmask_b32_e64 v73, v77, v78, s[16:17]
	v_cmp_gt_i32_e64 s[16:17], 0, v72
	v_max_f32_e32 v77, 0, v74
	v_max_f32_e32 v74, v83, v83
	v_cndmask_b32_e64 v72, v76, v79, s[16:17]
	v_cmp_eq_u32_e64 s[16:17], v72, v32
	v_cmp_eq_u32_e64 s[18:19], v73, v33
	v_max_f32_e32 v78, 0, v74
	v_max_f32_e32 v72, 0, v82
	v_max_f32_e32 v73, 0, v86
	v_max_f32_e32 v79, 0, v87
	v_pk_mul_f32 v[72:73], v[72:73], v[114:115]
	v_max_f32_e32 v76, 0, v92
	v_pk_mul_f32 v[78:79], v[78:79], v[118:119]
	v_max_f32_e32 v74, 0, v93
	v_pk_mul_f32 v[76:77], v[76:77], v[116:117]
	v_pk_mul_f32 v[74:75], v[74:75], v[120:121]
	v_mov_b32_e32 v80, v72
	v_mov_b32_e32 v81, v78
	v_mov_b32_e32 v78, v73
	v_pk_add_f32 v[72:73], v[80:81], v[78:79]
	v_mov_b32_e32 v78, v76
	v_mov_b32_e32 v79, v74
	v_pk_add_f32 v[72:73], v[72:73], v[78:79]
	v_mov_b32_e32 v74, v77
	v_pk_add_f32 v[72:73], v[72:73], v[74:75]
	s_nop 0
	v_pk_add_f32 v[72:73], v[72:73], 0 op_sel_hi:[1,0]
	s_nop 0
	v_and_b32_e32 v75, 0x7fffffff, v73
	v_and_b32_e32 v74, 0x7fffffff, v72
	v_xor_b32_e32 v76, -1, v73
	v_pk_add_f32 v[74:75], v[74:75], 0 neg_lo:[1,1] neg_hi:[1,1]
	v_cmp_gt_i32_e64 s[20:21], 0, v73
	v_xor_b32_e32 v77, -1, v72
	s_nop 0
	v_cndmask_b32_e64 v73, v75, v76, s[20:21]
	v_cmp_gt_i32_e64 s[20:21], 0, v72
	v_cmp_eq_u32_e64 s[22:23], v73, v35
	s_nop 0
	v_cndmask_b32_e64 v72, v74, v77, s[20:21]
	v_cmp_eq_u32_e64 s[20:21], v72, v34
	s_and_saveexec_b64 s[36:37], s[40:41]
	s_cbranch_execz .LBB0_992
	v_lshrrev_b64 v[72:73], v150, s[22:23]
	v_and_b32_e32 v72, 0xffff, v72
	v_bcnt_u32_b32 v74, v72, 0
	v_lshrrev_b64 v[72:73], v150, s[14:15]
	v_and_b32_e32 v72, 0xffff, v72
	v_bcnt_u32_b32 v75, v72, 0
	v_lshrrev_b64 v[72:73], v150, s[6:7]
	v_and_b32_e32 v76, 0xffff, v72
	v_lshrrev_b64 v[72:73], v150, s[54:55]
	v_and_b32_e32 v72, 0xffff, v72
	v_bcnt_u32_b32 v72, v72, 0
	v_bcnt_u32_b32 v72, v76, v72
	v_add3_u32 v74, v72, v75, v74
	v_lshrrev_b64 v[72:73], v150, s[20:21]
	v_and_b32_e32 v72, 0xffff, v72
	v_bcnt_u32_b32 v75, v72, 0
	v_lshrrev_b64 v[72:73], v150, s[12:13]
	v_and_b32_e32 v72, 0xffff, v72
	v_bcnt_u32_b32 v76, v72, 0
	v_lshrrev_b64 v[72:73], v150, s[4:5]
	v_and_b32_e32 v77, 0xffff, v72
	v_lshrrev_b64 v[72:73], v150, s[52:53]
	v_and_b32_e32 v72, 0xffff, v72
	v_bcnt_u32_b32 v72, v72, 0
	v_bcnt_u32_b32 v72, v77, v72
	v_add3_u32 v75, v72, v76, v75
	v_lshrrev_b64 v[72:73], v150, s[18:19]
	v_and_b32_e32 v72, 0xffff, v72
	v_bcnt_u32_b32 v76, v72, 0
	v_lshrrev_b64 v[72:73], v150, s[10:11]
	v_and_b32_e32 v72, 0xffff, v72
	v_bcnt_u32_b32 v77, v72, 0
	v_lshrrev_b64 v[72:73], v150, s[58:59]
	v_and_b32_e32 v78, 0xffff, v72
	v_lshrrev_b64 v[72:73], v150, s[50:51]
	v_and_b32_e32 v72, 0xffff, v72
	v_bcnt_u32_b32 v72, v72, 0
	v_bcnt_u32_b32 v72, v78, v72
	v_add3_u32 v76, v72, v77, v76
	v_lshrrev_b64 v[72:73], v150, s[16:17]
	v_and_b32_e32 v72, 0xffff, v72
	v_bcnt_u32_b32 v77, v72, 0
	v_lshrrev_b64 v[72:73], v150, s[8:9]
	v_and_b32_e32 v72, 0xffff, v72
	v_bcnt_u32_b32 v78, v72, 0
	v_lshrrev_b64 v[72:73], v150, s[56:57]
	v_and_b32_e32 v79, 0xffff, v72
	v_lshrrev_b64 v[72:73], v150, s[48:49]
	v_and_b32_e32 v72, 0xffff, v72
	v_bcnt_u32_b32 v72, v72, 0
	v_bcnt_u32_b32 v72, v79, v72
	v_add3_u32 v72, v72, v78, v77
	ds_write_b16 v88, v72
	ds_write_b16 v88, v76 offset:128
	ds_write_b16 v88, v75 offset:256
	ds_write_b16 v88, v74 offset:384
	s_branch .LBB0_992

; template <int MODE> ...
;     ...
; #pragma unroll
;     for (int kt = 0; kt < 4; ++kt) {
;       f32x4 sh[4];
; #pragma unroll
;       for (int h = 0; h < 4; ++h) {
;         sh[h] = (f32x4){0.f, 0.f, 0.f, 0.f};
; #pragma unroll
;         for (int ks = 0; ks < 2; ++ks) sh[h] = MFMA16(qf[h][ks], kf[kt][ks], sh[h]);
;       }
; #pragma unroll
;       for (int j = 0; j < 4; ++j) {
;         float sc = w[j][0] * fmaxf(sh[0][j], 0.f) + w[j][1] * fmaxf(sh[1][j], 0.f) + w[j][2] * fmaxf(sh[2][j], 0.f) + w[j][3] * fmaxf(sh[3][j], 0.f);
;         sc += 0.0f;
;         const unsigned u = sortable(sc);
;         if (MODE == 4) {
;           const unsigned um = u & himask;
;           const bool eq = um == pfx[j], zr = u == 0x80000000u;
;           unsigned* qx = hist + (4 * g + j) * C1_HP + 512;
;           if (eq) {
;             const unsigned bin = u & bmask; atomicAdd(&hist[(4 * g + j) * C1_HP + (bin >> 1)], 1u << ((bin & 1u) * 16u));
;             if (!zr) { const unsigned idx = atomicAdd(&qx[320], 1u); if (idx < 64u) qx[256 + idx] = ((unsigned)n << 16) | ((unsigned)(kt * 16 + lr) << 10) | (u & 1023u); }
;           }
;           word[j] |= (u64)((unsigned)(__ballot(um > pfx[j]) >> (16 * g)) & 0xffffu) << (16 * kt);
;           zword[j] |= (u64)((unsigned)(__ballot(zr) >> (16 * g)) & 0xffffu) << (16 * kt);
;         } else if (MODE == 0 || MODE == 3) {
;           if (MODE == 3) base[j] += __popc((unsigned)(__ballot(u == 0x80000000u) >> (16 * g)) & 0xffffu);
;           if (((u ^ pfx[j]) & himask) == 0u) { const unsigned bin = (u >> shift) & bmask; atomicAdd(&hist[(4 * g + j) * C1_HP + (bin >> 1)], 1u << ((bin & 1u) * 16u)); }
;         } else {
;           const bool eq = u == pfx[j];
;           const unsigned fe = (unsigned)(__ballot(eq) >> (16 * g)) & 0xffffu;
;           if (MODE == 1) {
;             base[j] += __popc(fe);
;           } else {
;             const unsigned rank = base[j] + __popc(fe & ((1u << lr) - 1u));
;             const bool sel = (u > pfx[j]) || (eq && rank < need[j]);
;             base[j] += __popc(fe);
;             const unsigned fs = (unsigned)(__ballot(sel) >> (16 * g)) & 0xffffu;
;             word[j] |= (u64)fs << (16 * kt);
;           }
;         }
;       }
;     }
;     if ((MODE == 1 || MODE == 3) && lr == 0) {
; #pragma unroll
;       for (int j = 0; j < 4; ++j) cnt[(4 * g + j) * 64 + n] = (unsigned short)base[j];
;     }
.LBB0_1005:
	s_waitcnt vmcnt(15)
	v_mfma_f32_16x16x32_f16 v[132:135], v[24:27], v[100:103], 0
	v_mfma_f32_16x16x32_f16 v[136:139], v[4:7], v[100:103], 0
	v_mfma_f32_16x16x32_f16 v[140:143], v[12:15], v[100:103], 0
	v_mfma_f32_16x16x32_f16 v[100:103], v[20:23], v[100:103], 0
	s_waitcnt vmcnt(14)
	v_mfma_f32_16x16x32_f16 v[132:135], v[0:3], v[96:99], v[132:135]
	v_mfma_f32_16x16x32_f16 v[136:139], v[8:11], v[96:99], v[136:139]
	v_mfma_f32_16x16x32_f16 v[140:143], v[16:19], v[96:99], v[140:143]
	s_nop 5
	v_max_f32_e32 v144, 0, v132
	v_mfma_f32_16x16x32_f16 v[96:99], v[28:31], v[96:99], v[100:103]
	v_max_f32_e32 v145, 0, v136
	v_max_f32_e32 v132, v140, v140
	v_pk_mul_f32 v[144:145], v[144:145], v[106:107]
	v_max_f32_e32 v146, 0, v132
	s_nop 3
	v_max_f32_e32 v147, 0, v96
	v_pk_mul_f32 v[100:101], v[146:147], v[108:109]
	v_add_f32_e32 v96, v144, v145
	v_add_f32_e32 v96, v96, v100
	v_add_f32_e32 v96, v96, v101
	v_add_f32_e32 v96, 0, v96
	v_not_b32_e32 v100, v96
	v_or_b32_e32 v101, 0x80000000, v96
	v_cmp_gt_i32_e32 vcc, 0, v96
	v_max_f32_e32 v97, v97, v97
	v_max_f32_e32 v98, v98, v98
	v_cndmask_b32_e32 v96, v101, v100, vcc
	v_cmp_gt_u32_e32 vcc, v96, v32
	v_max_f32_e32 v97, 0, v97
	v_max_f32_e32 v99, v99, v99
	v_cndmask_b32_e64 v102, 0, 1, vcc
	v_cmp_eq_u32_e32 vcc, v96, v32
	v_max_f32_e32 v99, 0, v99
	s_nop 0
	v_lshrrev_b64 v[100:101], v150, vcc
	v_and_b32_e32 v96, 0xffff, v100
	v_and_b32_e32 v100, v100, v105
	s_waitcnt lgkmcnt(3)
	v_bcnt_u32_b32 v100, v100, v131
	v_cmp_lt_u32_e64 s[4:5], v100, v36
	v_bcnt_u32_b32 v144, v96, v131
	s_nop 0
	v_cndmask_b32_e64 v100, 0, 1, s[4:5]
	v_cndmask_b32_e32 v100, v102, v100, vcc
	v_and_b32_e32 v96, 1, v100
	v_cmp_ne_u32_e32 vcc, 0, v96
	v_max_f32_e32 v100, 0, v133
	v_max_f32_e32 v101, 0, v137
	v_pk_mul_f32 v[136:137], v[100:101], v[110:111]
	v_max_f32_e32 v96, 0, v141
	v_max_f32_e32 v101, 0, v98
	v_pk_mul_f32 v[140:141], v[96:97], v[112:113]
	v_max_f32_e32 v102, 0, v135
	v_max_f32_e32 v96, 0, v134
	v_max_f32_e32 v97, 0, v138
	v_max_f32_e32 v103, 0, v139
	v_pk_mul_f32 v[96:97], v[96:97], v[114:115]
	v_max_f32_e32 v100, 0, v142
	v_pk_mul_f32 v[102:103], v[102:103], v[118:119]
	v_max_f32_e32 v98, 0, v143
	v_pk_mul_f32 v[100:101], v[100:101], v[116:117]
	v_pk_mul_f32 v[98:99], v[98:99], v[120:121]
	v_mov_b32_e32 v132, v96
	v_mov_b32_e32 v133, v102
	v_mov_b32_e32 v102, v97
	v_pk_add_f32 v[96:97], v[132:133], v[102:103]
	v_mov_b32_e32 v102, v100
	v_mov_b32_e32 v103, v98
	v_pk_add_f32 v[96:97], v[96:97], v[102:103]
	v_mov_b32_e32 v98, v101
	v_pk_add_f32 v[96:97], v[96:97], v[98:99]
	s_nop 0
	v_pk_add_f32 v[96:97], v[96:97], 0 op_sel_hi:[1,0]
	s_nop 0
	v_and_b32_e32 v99, 0x7fffffff, v97
	v_and_b32_e32 v98, 0x7fffffff, v96
	v_xor_b32_e32 v101, -1, v96
	v_pk_add_f32 v[98:99], v[98:99], 0 neg_lo:[1,1] neg_hi:[1,1]
	v_cmp_gt_i32_e64 s[4:5], 0, v96
	v_xor_b32_e32 v100, -1, v97
	s_nop 0
	v_cndmask_b32_e64 v101, v98, v101, s[4:5]
	v_cmp_gt_u32_e64 s[6:7], v101, v34
	v_cmp_gt_i32_e64 s[4:5], 0, v97
	s_nop 0
	v_cndmask_b32_e64 v131, 0, 1, s[6:7]
	v_cmp_eq_u32_e64 s[6:7], v101, v34
	v_cndmask_b32_e64 v96, v99, v100, s[4:5]
	v_cmp_gt_u32_e64 s[4:5], v96, v35
	v_lshrrev_b64 v[100:101], v150, s[6:7]
	v_and_b32_e32 v132, 0xffff, v100
	v_and_b32_e32 v100, v100, v105
	s_waitcnt lgkmcnt(1)
	v_bcnt_u32_b32 v133, v100, v130
	v_cmp_lt_u32_e64 s[8:9], v133, v38
	v_cndmask_b32_e64 v138, 0, 1, s[4:5]
	v_cmp_eq_u32_e64 s[4:5], v96, v35
	v_cndmask_b32_e64 v133, 0, 1, s[8:9]
	v_cndmask_b32_e64 v131, v131, v133, s[6:7]
	s_waitcnt vmcnt(13)
	v_mfma_f32_16x16x32_f16 v[96:99], v[24:27], v[92:95], 0
	v_bcnt_u32_b32 v139, v132, v130
	v_and_b32_e32 v130, 1, v131
	v_cmp_ne_u32_e64 s[44:45], 0, v130
	v_mfma_f32_16x16x32_f16 v[100:103], v[4:7], v[92:95], 0
	v_lshrrev_b64 v[134:135], v150, s[4:5]
	v_and_b32_e32 v135, 0xffff, v134
	v_and_b32_e32 v134, v134, v105
	v_mfma_f32_16x16x32_f16 v[130:133], v[12:15], v[92:95], 0
	s_waitcnt lgkmcnt(0)
	v_bcnt_u32_b32 v134, v134, v129
	v_cmp_lt_u32_e64 s[6:7], v134, v39
	v_mfma_f32_16x16x32_f16 v[92:95], v[20:23], v[92:95], 0
	s_nop 0
	v_cndmask_b32_e64 v134, 0, 1, s[6:7]
	v_cndmask_b32_e64 v134, v138, v134, s[4:5]
	v_bcnt_u32_b32 v138, v135, v129
	s_waitcnt vmcnt(12)
	v_mfma_f32_16x16x32_f16 v[96:99], v[0:3], v[88:91], v[96:99]
	v_and_b32_e32 v129, 1, v134
	v_mov_b32_e32 v135, v136
	v_cmp_ne_u32_e64 s[48:49], 0, v129
	v_mfma_f32_16x16x32_f16 v[100:103], v[8:11], v[88:91], v[100:103]
	v_mfma_f32_16x16x32_f16 v[130:133], v[16:19], v[88:91], v[130:133]
	v_mfma_f32_16x16x32_f16 v[88:91], v[28:31], v[88:91], v[92:95]
	s_nop 2
	s_nop 1
	v_max_f32_e32 v92, 0, v96
	v_max_f32_e32 v93, 0, v100
	v_pk_mul_f32 v[92:93], v[92:93], v[106:107]
	v_max_f32_e32 v94, 0, v130
	v_max_f32_e32 v95, 0, v88
	v_pk_mul_f32 v[94:95], v[94:95], v[108:109]
	v_mov_b32_e32 v134, v92
	v_mov_b32_e32 v136, v93
	v_pk_add_f32 v[92:93], v[134:135], v[136:137]
	v_mov_b32_e32 v134, v94
	v_mov_b32_e32 v135, v140
	v_pk_add_f32 v[92:93], v[92:93], v[134:135]
	v_mov_b32_e32 v140, v95
	v_pk_add_f32 v[92:93], v[92:93], v[140:141]
	v_pk_add_f32 v[92:93], v[92:93], 0 op_sel_hi:[1,0]
	v_and_b32_e32 v95, 0x7fffffff, v93
	v_and_b32_e32 v94, 0x7fffffff, v92
	v_xor_b32_e32 v88, -1, v93
	v_pk_add_f32 v[94:95], v[94:95], 0 neg_lo:[1,1] neg_hi:[1,1]
	v_cmp_gt_i32_e64 s[4:5], 0, v93
	v_xor_b32_e32 v96, -1, v92
	v_max_f32_e32 v89, 0, v89
	v_cndmask_b32_e64 v88, v95, v88, s[4:5]
	v_cmp_gt_i32_e64 s[4:5], 0, v92
	v_cmp_gt_u32_e64 s[6:7], v88, v33
	v_max_f32_e32 v91, v91, v91
	v_cndmask_b32_e64 v92, v94, v96, s[4:5]
	v_cmp_gt_u32_e64 s[4:5], v92, v32
	v_cndmask_b32_e64 v95, 0, 1, s[6:7]
	v_cmp_eq_u32_e64 s[6:7], v88, v33
	v_cndmask_b32_e64 v94, 0, 1, s[4:5]
; template <int MODE> ...
;     ...
; #pragma unroll
;     for (int kt = 0; kt < 4; ++kt) {
;       f32x4 sh[4];
; #pragma unroll
;       for (int h = 0; h < 4; ++h) {
;         sh[h] = (f32x4){0.f, 0.f, 0.f, 0.f};
; #pragma unroll
;         for (int ks = 0; ks < 2; ++ks) sh[h] = MFMA16(qf[h][ks], kf[kt][ks], sh[h]);
;       }
; #pragma unroll
;       for (int j = 0; j < 4; ++j) {
;         float sc = w[j][0] * fmaxf(sh[0][j], 0.f) + w[j][1] * fmaxf(sh[1][j], 0.f) + w[j][2] * fmaxf(sh[2][j], 0.f) + w[j][3] * fmaxf(sh[3][j], 0.f);
;         sc += 0.0f;
;         const unsigned u = sortable(sc);
;         if (MODE == 4) {
;           const unsigned um = u & himask;
;           const bool eq = um == pfx[j], zr = u == 0x80000000u;
;           unsigned* qx = hist + (4 * g + j) * C1_HP + 512;
;           if (eq) {
;             const unsigned bin = u & bmask; atomicAdd(&hist[(4 * g + j) * C1_HP + (bin >> 1)], 1u << ((bin & 1u) * 16u));
;             if (!zr) { const unsigned idx = atomicAdd(&qx[320], 1u); if (idx < 64u) qx[256 + idx] = ((unsigned)n << 16) | ((unsigned)(kt * 16 + lr) << 10) | (u & 1023u); }
;           }
;           word[j] |= (u64)((unsigned)(__ballot(um > pfx[j]) >> (16 * g)) & 0xffffu) << (16 * kt);
;           zword[j] |= (u64)((unsigned)(__ballot(zr) >> (16 * g)) & 0xffffu) << (16 * kt);
;         } else if (MODE == 0 || MODE == 3) {
;           if (MODE == 3) base[j] += __popc((unsigned)(__ballot(u == 0x80000000u) >> (16 * g)) & 0xffffu);
;           if (((u ^ pfx[j]) & himask) == 0u) { const unsigned bin = (u >> shift) & bmask; atomicAdd(&hist[(4 * g + j) * C1_HP + (bin >> 1)], 1u << ((bin & 1u) * 16u)); }
;         } else {
;           const bool eq = u == pfx[j];
;           const unsigned fe = (unsigned)(__ballot(eq) >> (16 * g)) & 0xffffu;
;           if (MODE == 1) {
;             base[j] += __popc(fe);
;           } else {
;             const unsigned rank = base[j] + __popc(fe & ((1u << lr) - 1u));
;             const bool sel = (u > pfx[j]) || (eq && rank < need[j]);
;             base[j] += __popc(fe);
;             const unsigned fs = (unsigned)(__ballot(sel) >> (16 * g)) & 0xffffu;
;             word[j] |= (u64)fs << (16 * kt);
;           }
;         }
;       }
;     }
;     if ((MODE == 1 || MODE == 3) && lr == 0) {
; #pragma unroll
;       for (int j = 0; j < 4; ++j) cnt[(4 * g + j) * 64 + n] = (unsigned short)base[j];
;     }
	v_cmp_eq_u32_e64 s[4:5], v92, v32
	v_lshrrev_b64 v[92:93], v150, s[6:7]
	v_and_b32_e32 v88, 0xffff, v92
	v_and_b32_e32 v92, v92, v105
	v_bcnt_u32_b32 v92, v92, v128
	v_cmp_lt_u32_e64 s[8:9], v92, v37
	v_bcnt_u32_b32 v140, v88, v128
	v_max_f32_e32 v91, 0, v91
	v_cndmask_b32_e64 v92, 0, 1, s[8:9]
	v_cndmask_b32_e64 v92, v95, v92, s[6:7]
	v_and_b32_e32 v88, 1, v92
	v_lshrrev_b64 v[92:93], v150, s[4:5]
	v_cmp_ne_u32_e64 s[50:51], 0, v88
	v_and_b32_e32 v88, 0xffff, v92
	v_and_b32_e32 v92, v92, v105
	v_bcnt_u32_b32 v92, v92, v144
	v_cmp_lt_u32_e64 s[6:7], v92, v36
	v_bcnt_u32_b32 v100, v88, v144
	s_nop 0
	v_cndmask_b32_e64 v92, 0, 1, s[6:7]
	v_cndmask_b32_e64 v92, v94, v92, s[4:5]
	v_and_b32_e32 v88, 1, v92
	v_cmp_ne_u32_e64 s[52:53], 0, v88
	v_max_f32_e32 v92, 0, v97
	v_max_f32_e32 v93, 0, v101
	v_pk_mul_f32 v[134:135], v[92:93], v[110:111]
	v_max_f32_e32 v88, 0, v131
	v_max_f32_e32 v93, 0, v90
	v_pk_mul_f32 v[136:137], v[88:89], v[112:113]
	v_max_f32_e32 v94, 0, v99
	v_max_f32_e32 v88, 0, v98
	v_max_f32_e32 v89, 0, v102
	v_max_f32_e32 v95, 0, v103
	v_pk_mul_f32 v[88:89], v[88:89], v[114:115]
	v_max_f32_e32 v92, 0, v132
	v_pk_mul_f32 v[94:95], v[94:95], v[118:119]
	v_max_f32_e32 v90, 0, v133
	v_pk_mul_f32 v[92:93], v[92:93], v[116:117]
	v_pk_mul_f32 v[90:91], v[90:91], v[120:121]
	v_mov_b32_e32 v96, v88
	v_mov_b32_e32 v97, v94
	v_mov_b32_e32 v94, v89
	v_pk_add_f32 v[88:89], v[96:97], v[94:95]
	v_mov_b32_e32 v94, v92
	v_mov_b32_e32 v95, v90
	v_pk_add_f32 v[88:89], v[88:89], v[94:95]
	v_mov_b32_e32 v90, v93
	v_pk_add_f32 v[88:89], v[88:89], v[90:91]
	s_waitcnt vmcnt(11)
	v_mfma_f32_16x16x32_f16 v[128:131], v[12:15], v[84:87], 0
	v_add_f32_e64 v88, v88, 0
	v_add_f32_e64 v89, v89, 0
	v_and_b32_e32 v91, 0x7fffffff, v89
	v_and_b32_e32 v90, 0x7fffffff, v88
	v_xor_b32_e32 v93, -1, v88
	v_pk_add_f32 v[90:91], v[90:91], 0 neg_lo:[1,1] neg_hi:[1,1]
	v_cmp_gt_i32_e64 s[4:5], 0, v88
	v_xor_b32_e32 v92, -1, v89
	s_waitcnt vmcnt(10)
	v_mfma_f32_16x16x32_f16 v[128:131], v[16:19], v[80:83], v[128:131]
	v_cndmask_b32_e64 v93, v90, v93, s[4:5]
	v_cmp_gt_u32_e64 s[6:7], v93, v34
	v_cmp_gt_i32_e64 s[4:5], 0, v89
	s_nop 0
	v_cndmask_b32_e64 v96, 0, 1, s[6:7]
	v_cmp_eq_u32_e64 s[6:7], v93, v34
	v_cndmask_b32_e64 v88, v91, v92, s[4:5]
	v_cmp_gt_u32_e64 s[4:5], v88, v35
	v_lshrrev_b64 v[92:93], v150, s[6:7]
	v_and_b32_e32 v97, 0xffff, v92
	v_and_b32_e32 v92, v92, v105
	v_bcnt_u32_b32 v98, v92, v139
	v_mfma_f32_16x16x32_f16 v[92:95], v[4:7], v[84:87], 0
	v_cndmask_b32_e64 v99, 0, 1, s[4:5]
	v_cmp_eq_u32_e64 s[4:5], v88, v35
	v_cmp_lt_u32_e64 s[8:9], v98, v38
	v_mfma_f32_16x16x32_f16 v[88:91], v[24:27], v[84:87], 0
	s_nop 0
	v_cndmask_b32_e64 v98, 0, 1, s[8:9]
	v_cndmask_b32_e64 v101, v96, v98, s[6:7]
	v_mfma_f32_16x16x32_f16 v[84:87], v[20:23], v[84:87], 0
	v_bcnt_u32_b32 v98, v97, v139
	v_mfma_f32_16x16x32_f16 v[94:97], v[8:11], v[80:83], v[92:95]
	s_nop 2
	v_and_b32_e32 v92, 1, v101
	v_mfma_f32_16x16x32_f16 v[88:91], v[0:3], v[80:83], v[88:91]
	v_cmp_ne_u32_e64 s[54:55], 0, v92
	v_lshrrev_b64 v[92:93], v150, s[4:5]
	v_and_b32_e32 v93, 0xffff, v92
	v_and_b32_e32 v92, v92, v105
	v_mfma_f32_16x16x32_f16 v[80:83], v[28:31], v[80:83], v[84:87]
	v_bcnt_u32_b32 v92, v92, v138
	v_cmp_lt_u32_e64 s[6:7], v92, v39
	s_nop 0
	v_max_f32_e32 v84, v88, v88
	v_cndmask_b32_e64 v92, 0, 1, s[6:7]
	v_cndmask_b32_e64 v92, v99, v92, s[4:5]
	v_max_f32_e32 v84, 0, v84
	v_max_f32_e32 v85, 0, v94
	v_and_b32_e32 v92, 1, v92
	v_pk_mul_f32 v[84:85], v[84:85], v[106:107]
	v_max_f32_e32 v86, 0, v128
	v_max_f32_e32 v87, 0, v80
	v_bcnt_u32_b32 v99, v93, v138
	v_cmp_ne_u32_e64 s[56:57], 0, v92
	v_pk_mul_f32 v[86:87], v[86:87], v[108:109]
	v_mov_b32_e32 v92, v84
	v_mov_b32_e32 v93, v134
	v_mov_b32_e32 v134, v85
	v_pk_add_f32 v[84:85], v[92:93], v[134:135]
	v_mov_b32_e32 v92, v86
	v_mov_b32_e32 v93, v136
	v_pk_add_f32 v[84:85], v[84:85], v[92:93]
	v_mov_b32_e32 v136, v87
	v_pk_add_f32 v[84:85], v[84:85], v[136:137]
	v_pk_add_f32 v[84:85], v[84:85], 0 op_sel_hi:[1,0]
	v_and_b32_e32 v87, 0x7fffffff, v85
	v_and_b32_e32 v86, 0x7fffffff, v84
	v_xor_b32_e32 v80, -1, v85
	v_pk_add_f32 v[86:87], v[86:87], 0 neg_lo:[1,1] neg_hi:[1,1]
	v_cmp_gt_i32_e64 s[4:5], 0, v85
	v_xor_b32_e32 v88, -1, v84
	v_max_f32_e32 v81, 0, v81
	v_cndmask_b32_e64 v80, v87, v80, s[4:5]
	v_cmp_gt_i32_e64 s[4:5], 0, v84
	v_max_f32_e32 v83, v83, v83
	v_max_f32_e32 v83, 0, v83
	v_cndmask_b32_e64 v84, v86, v88, s[4:5]
	v_cmp_gt_u32_e64 s[4:5], v84, v32
	v_cmp_eq_u32_e64 s[6:7], v84, v32
	s_nop 0
	v_cndmask_b32_e64 v86, 0, 1, s[4:5]
	v_cmp_gt_u32_e64 s[4:5], v80, v33
	v_lshrrev_b64 v[92:93], v150, s[6:7]
	s_nop 0
	v_cndmask_b32_e64 v87, 0, 1, s[4:5]
	v_cmp_eq_u32_e64 s[4:5], v80, v33
	s_nop 1
	v_lshrrev_b64 v[84:85], v150, s[4:5]
	v_and_b32_e32 v80, 0xffff, v84
	v_and_b32_e32 v84, v84, v105
	v_bcnt_u32_b32 v84, v84, v140
	v_cmp_lt_u32_e64 s[8:9], v84, v37
	v_bcnt_u32_b32 v101, v80, v140
	s_nop 0
	v_cndmask_b32_e64 v84, 0, 1, s[8:9]
	v_cndmask_b32_e64 v84, v87, v84, s[4:5]
	v_and_b32_e32 v80, 1, v84
	v_cmp_ne_u32_e64 s[4:5], 0, v80
	v_and_b32_e32 v80, v92, v105
	v_bcnt_u32_b32 v80, v80, v100
	v_cmp_lt_u32_e64 s[8:9], v80, v36
	s_nop 1
	v_cndmask_b32_e64 v80, 0, 1, s[8:9]
	v_cndmask_b32_e64 v80, v86, v80, s[6:7]
	v_and_b32_e32 v80, 1, v80
	v_cmp_ne_u32_e64 s[58:59], 0, v80
	v_max_f32_e32 v84, 0, v89
	v_max_f32_e32 v85, 0, v95
	v_pk_mul_f32 v[102:103], v[84:85], v[110:111]
	v_max_f32_e32 v80, 0, v129
	v_max_f32_e32 v85, 0, v82
	v_pk_mul_f32 v[128:129], v[80:81], v[112:113]
	v_max_f32_e32 v86, 0, v91
	v_max_f32_e32 v80, 0, v90
	v_max_f32_e32 v81, 0, v96
	v_max_f32_e32 v87, 0, v97
	v_pk_mul_f32 v[80:81], v[80:81], v[114:115]
	v_max_f32_e32 v84, 0, v130
	v_pk_mul_f32 v[86:87], v[86:87], v[118:119]
	v_max_f32_e32 v82, 0, v131
	v_pk_mul_f32 v[84:85], v[84:85], v[116:117]
	v_pk_mul_f32 v[82:83], v[82:83], v[120:121]
	v_mov_b32_e32 v88, v80
	v_mov_b32_e32 v89, v86
	v_mov_b32_e32 v86, v81
	v_pk_add_f32 v[80:81], v[88:89], v[86:87]
	v_mov_b32_e32 v86, v84
	v_mov_b32_e32 v87, v82
	v_pk_add_f32 v[80:81], v[80:81], v[86:87]
	v_mov_b32_e32 v82, v85
	v_pk_add_f32 v[80:81], v[80:81], v[82:83]
	v_mov_b32_e32 v131, v102
	v_pk_add_f32 v[80:81], v[80:81], 0 op_sel_hi:[1,0]
	s_nop 0
	v_and_b32_e32 v83, 0x7fffffff, v81
	v_and_b32_e32 v82, 0x7fffffff, v80
	v_xor_b32_e32 v85, -1, v80
	v_pk_add_f32 v[82:83], v[82:83], 0 neg_lo:[1,1] neg_hi:[1,1]
	v_cmp_gt_i32_e64 s[6:7], 0, v80
	v_xor_b32_e32 v84, -1, v81
	s_nop 0
	v_cndmask_b32_e64 v85, v82, v85, s[6:7]
	v_cmp_gt_i32_e64 s[6:7], 0, v81
	s_nop 1
	v_cndmask_b32_e64 v84, v83, v84, s[6:7]
	v_cmp_gt_u32_e64 s[6:7], v84, v35
	s_waitcnt vmcnt(9)
; #define MFMA16(a, b, c) __builtin_amdgcn_mfma_f32_16x16x32_f16((a), (b), (c), 0, 0, 0)
; template <int MODE> ...
;     ...
; #pragma unroll
;     for (int kt = 0; kt < 4; ++kt) {
;       f32x4 sh[4];
; #pragma unroll
;       for (int h = 0; h < 4; ++h) {
;         sh[h] = (f32x4){0.f, 0.f, 0.f, 0.f};
; #pragma unroll
;         for (int ks = 0; ks < 2; ++ks) sh[h] = MFMA16(qf[h][ks], kf[kt][ks], sh[h]);
;       }
; #pragma unroll
;       for (int j = 0; j < 4; ++j) {
;         float sc = w[j][0] * fmaxf(sh[0][j], 0.f) + w[j][1] * fmaxf(sh[1][j], 0.f) + w[j][2] * fmaxf(sh[2][j], 0.f) + w[j][3] * fmaxf(sh[3][j], 0.f);
;         sc += 0.0f;
;         const unsigned u = sortable(sc);
;         if (MODE == 4) {
;           const unsigned um = u & himask;
;           const bool eq = um == pfx[j], zr = u == 0x80000000u;
;           unsigned* qx = hist + (4 * g + j) * C1_HP + 512;
;           if (eq) {
;             const unsigned bin = u & bmask; atomicAdd(&hist[(4 * g + j) * C1_HP + (bin >> 1)], 1u << ((bin & 1u) * 16u));
;             if (!zr) { const unsigned idx = atomicAdd(&qx[320], 1u); if (idx < 64u) qx[256 + idx] = ((unsigned)n << 16) | ((unsigned)(kt * 16 + lr) << 10) | (u & 1023u); }
;           }
;           word[j] |= (u64)((unsigned)(__ballot(um > pfx[j]) >> (16 * g)) & 0xffffu) << (16 * kt);
;           zword[j] |= (u64)((unsigned)(__ballot(zr) >> (16 * g)) & 0xffffu) << (16 * kt);
;         } else if (MODE == 0 || MODE == 3) {
;           if (MODE == 3) base[j] += __popc((unsigned)(__ballot(u == 0x80000000u) >> (16 * g)) & 0xffffu);
;           if (((u ^ pfx[j]) & himask) == 0u) { const unsigned bin = (u >> shift) & bmask; atomicAdd(&hist[(4 * g + j) * C1_HP + (bin >> 1)], 1u << ((bin & 1u) * 16u)); }
;         } else {
;           const bool eq = u == pfx[j];
;           const unsigned fe = (unsigned)(__ballot(eq) >> (16 * g)) & 0xffffu;
;           if (MODE == 1) {
;             base[j] += __popc(fe);
;           } else {
;             const unsigned rank = base[j] + __popc(fe & ((1u << lr) - 1u));
;             const bool sel = (u > pfx[j]) || (eq && rank < need[j]);
;             base[j] += __popc(fe);
;             const unsigned fs = (unsigned)(__ballot(sel) >> (16 * g)) & 0xffffu;
;             word[j] |= (u64)fs << (16 * kt);
;           }
;         }
	v_mfma_f32_16x16x32_f16 v[80:83], v[24:27], v[76:79], 0
	v_cmp_eq_u32_e64 s[8:9], v84, v35
	v_cndmask_b32_e64 v93, 0, 1, s[6:7]
	v_cmp_gt_u32_e64 s[6:7], v85, v34
	s_waitcnt vmcnt(8)
	v_mfma_f32_16x16x32_f16 v[80:83], v[0:3], v[72:75], v[80:83]
	v_lshrrev_b64 v[96:97], v150, s[8:9]
	v_cndmask_b32_e64 v88, 0, 1, s[6:7]
	v_cmp_eq_u32_e64 s[6:7], v85, v34
	v_mfma_f32_16x16x32_f16 v[84:87], v[4:7], v[76:79], 0
	s_nop 0
	v_lshrrev_b64 v[94:95], v150, s[6:7]
	v_and_b32_e32 v89, v94, v105
	v_bcnt_u32_b32 v89, v89, v98
	v_cmp_lt_u32_e64 s[10:11], v89, v38
	v_mfma_f32_16x16x32_f16 v[84:87], v[8:11], v[72:75], v[84:87]
	s_nop 0
	v_cndmask_b32_e64 v89, 0, 1, s[10:11]
	v_cndmask_b32_e64 v88, v88, v89, s[6:7]
	v_and_b32_e32 v95, 1, v88
	v_mfma_f32_16x16x32_f16 v[88:91], v[12:15], v[76:79], 0
	v_cmp_ne_u32_e64 s[6:7], 0, v95
	v_and_b32_e32 v95, v96, v105
	v_bcnt_u32_b32 v95, v95, v99
	v_mfma_f32_16x16x32_f16 v[76:79], v[20:23], v[76:79], 0
	v_cmp_lt_u32_e64 s[10:11], v95, v39
	v_mfma_f32_16x16x32_f16 v[88:91], v[16:19], v[72:75], v[88:91]
	s_nop 0
	v_cndmask_b32_e64 v95, 0, 1, s[10:11]
	v_cndmask_b32_e64 v93, v93, v95, s[8:9]
	v_and_b32_e32 v93, 1, v93
	v_mfma_f32_16x16x32_f16 v[72:75], v[28:31], v[72:75], v[76:79]
	v_cmp_ne_u32_e64 s[8:9], 0, v93
	s_nop 1
	v_max_f32_e32 v76, 0, v80
	v_max_f32_e32 v77, 0, v84
	v_max_f32_e32 v78, v88, v88
	v_pk_mul_f32 v[76:77], v[76:77], v[106:107]
	v_max_f32_e32 v78, 0, v78
	v_max_f32_e32 v79, 0, v72
	v_pk_mul_f32 v[78:79], v[78:79], v[108:109]
	v_mov_b32_e32 v130, v76
	v_mov_b32_e32 v102, v77
	v_pk_add_f32 v[76:77], v[130:131], v[102:103]
	v_mov_b32_e32 v102, v78
	v_mov_b32_e32 v103, v128
	v_pk_add_f32 v[76:77], v[76:77], v[102:103]
	v_mov_b32_e32 v128, v79
	v_pk_add_f32 v[76:77], v[76:77], v[128:129]
	s_nop 0
	v_pk_add_f32 v[76:77], v[76:77], 0 op_sel_hi:[1,0]
	s_nop 0
	v_and_b32_e32 v79, 0x7fffffff, v77
	v_and_b32_e32 v78, 0x7fffffff, v76
	v_xor_b32_e32 v72, -1, v77
	v_pk_add_f32 v[78:79], v[78:79], 0 neg_lo:[1,1] neg_hi:[1,1]
	v_cmp_gt_i32_e64 s[10:11], 0, v77
	v_xor_b32_e32 v80, -1, v76
	s_nop 0
	v_cndmask_b32_e64 v72, v79, v72, s[10:11]
	v_cmp_gt_i32_e64 s[10:11], 0, v76
	s_nop 1
	v_cndmask_b32_e64 v78, v78, v80, s[10:11]
	v_cmp_gt_u32_e64 s[10:11], v72, v33
	v_cmp_eq_u32_e64 s[12:13], v78, v32
	s_nop 0
	v_cndmask_b32_e64 v79, 0, 1, s[10:11]
	v_cmp_eq_u32_e64 s[10:11], v72, v33
	s_nop 1
	v_lshrrev_b64 v[76:77], v150, s[10:11]
	v_and_b32_e32 v72, v76, v105
	v_bcnt_u32_b32 v72, v72, v101
	v_cmp_lt_u32_e64 s[14:15], v72, v37
	s_nop 1
	v_cndmask_b32_e64 v72, 0, 1, s[14:15]
	v_cndmask_b32_e64 v72, v79, v72, s[10:11]
	v_and_b32_e32 v72, 1, v72
	v_cmp_ne_u32_e64 s[10:11], 0, v72
	v_cmp_gt_u32_e64 s[14:15], v78, v32
	s_and_saveexec_b64 s[16:17], s[12:13]
	s_cbranch_execz .LBB0_1007
	v_lshrrev_b64 v[78:79], v150, s[12:13]
	v_and_b32_e32 v72, 0xffff, v92
	v_and_b32_e32 v77, v78, v105
	v_bcnt_u32_b32 v72, v72, 0
	v_bcnt_u32_b32 v77, v77, 0
	v_add3_u32 v72, v72, v100, v77
	v_cmp_lt_u32_e64 s[12:13], v72, v36
	s_andn2_b64 s[14:15], s[14:15], exec
	s_and_b64 s[12:13], s[12:13], exec
	s_or_b64 s[14:15], s[14:15], s[12:13]
; template <int MODE> ...
;     ...
; #pragma unroll
;     for (int kt = 0; kt < 4; ++kt) {
;       f32x4 sh[4];
; #pragma unroll
;       for (int h = 0; h < 4; ++h) {
;         sh[h] = (f32x4){0.f, 0.f, 0.f, 0.f};
; #pragma unroll
;         for (int ks = 0; ks < 2; ++ks) sh[h] = MFMA16(qf[h][ks], kf[kt][ks], sh[h]);
;       }
; #pragma unroll
;       for (int j = 0; j < 4; ++j) {
;         float sc = w[j][0] * fmaxf(sh[0][j], 0.f) + w[j][1] * fmaxf(sh[1][j], 0.f) + w[j][2] * fmaxf(sh[2][j], 0.f) + w[j][3] * fmaxf(sh[3][j], 0.f);
;         sc += 0.0f;
;         const unsigned u = sortable(sc);
;         if (MODE == 4) {
;           const unsigned um = u & himask;
;           const bool eq = um == pfx[j], zr = u == 0x80000000u;
;           unsigned* qx = hist + (4 * g + j) * C1_HP + 512;
;           if (eq) {
;             const unsigned bin = u & bmask; atomicAdd(&hist[(4 * g + j) * C1_HP + (bin >> 1)], 1u << ((bin & 1u) * 16u));
;             if (!zr) { const unsigned idx = atomicAdd(&qx[320], 1u); if (idx < 64u) qx[256 + idx] = ((unsigned)n << 16) | ((unsigned)(kt * 16 + lr) << 10) | (u & 1023u); }
;           }
;           word[j] |= (u64)((unsigned)(__ballot(um > pfx[j]) >> (16 * g)) & 0xffffu) << (16 * kt);
;           zword[j] |= (u64)((unsigned)(__ballot(zr) >> (16 * g)) & 0xffffu) << (16 * kt);
;         } else if (MODE == 0 || MODE == 3) {
;           if (MODE == 3) base[j] += __popc((unsigned)(__ballot(u == 0x80000000u) >> (16 * g)) & 0xffffu);
;           if (((u ^ pfx[j]) & himask) == 0u) { const unsigned bin = (u >> shift) & bmask; atomicAdd(&hist[(4 * g + j) * C1_HP + (bin >> 1)], 1u << ((bin & 1u) * 16u)); }
;         } else {
;           const bool eq = u == pfx[j];
;           const unsigned fe = (unsigned)(__ballot(eq) >> (16 * g)) & 0xffffu;
;           if (MODE == 1) {
;             base[j] += __popc(fe);
;           } else {
;             const unsigned rank = base[j] + __popc(fe & ((1u << lr) - 1u));
;             const bool sel = (u > pfx[j]) || (eq && rank < need[j]);
;             base[j] += __popc(fe);
;             const unsigned fs = (unsigned)(__ballot(sel) >> (16 * g)) & 0xffffu;
;             word[j] |= (u64)fs << (16 * kt);
;           }
;         }
;       }
;     }
;     if ((MODE == 1 || MODE == 3) && lr == 0) {
; #pragma unroll
;       for (int j = 0; j < 4; ++j) cnt[(4 * g + j) * 64 + n] = (unsigned short)base[j];
;     }
.LBB0_1007:
	s_or_b64 exec, exec, s[16:17]
	v_and_b32_e32 v72, 0xffff, v94
	v_bcnt_u32_b32 v84, v72, 0
	v_and_b32_e32 v72, 0xffff, v96
	v_bcnt_u32_b32 v88, v72, 0
	v_and_b32_e32 v72, 0xffff, v76
	v_bcnt_u32_b32 v78, v72, 0
	v_cndmask_b32_e64 v72, 0, 1, s[14:15]
	v_cmp_ne_u32_e64 s[12:13], 0, v72
	v_max_f32_e32 v76, 0, v81
	v_max_f32_e32 v77, 0, v85
	v_pk_mul_f32 v[76:77], v[76:77], v[110:111]
	v_max_f32_e32 v72, 0, v89
	v_max_f32_e32 v73, 0, v73
	v_pk_mul_f32 v[72:73], v[72:73], v[112:113]
	v_add_f32_e32 v76, v76, v77
	v_add_f32_e32 v72, v76, v72
	v_add_f32_e32 v72, v72, v73
	v_add_f32_e32 v72, 0, v72
	v_not_b32_e32 v73, v72
	v_or_b32_e32 v76, 0x80000000, v72
	v_cmp_gt_i32_e64 s[14:15], 0, v72
	v_max_f32_e32 v74, v74, v74
	v_max_f32_e32 v77, 0, v74
	v_cndmask_b32_e64 v72, v76, v73, s[14:15]
	v_cmp_gt_u32_e64 s[14:15], v72, v33
	v_max_f32_e32 v74, v83, v83
	v_max_f32_e32 v75, v75, v75
	v_cndmask_b32_e64 v76, 0, 1, s[14:15]
	v_cmp_eq_u32_e64 s[14:15], v72, v33
	v_max_f32_e32 v75, 0, v75
	s_nop 0
	v_lshrrev_b64 v[72:73], v150, s[14:15]
	v_and_b32_e32 v72, v72, v105
	v_bcnt_u32_b32 v72, v72, 0
	v_add3_u32 v72, v78, v101, v72
	v_cmp_lt_u32_e64 s[16:17], v72, v37
	v_max_f32_e32 v73, v86, v86
	v_max_f32_e32 v78, 0, v74
	v_cndmask_b32_e64 v72, 0, 1, s[16:17]
	v_cndmask_b32_e64 v72, v76, v72, s[14:15]
	v_and_b32_e32 v72, 1, v72
	v_cmp_ne_u32_e64 s[14:15], 0, v72
	v_max_f32_e32 v72, 0, v82
	v_max_f32_e32 v73, 0, v73
	v_max_f32_e32 v79, 0, v87
	v_pk_mul_f32 v[72:73], v[72:73], v[114:115]
	v_max_f32_e32 v76, 0, v90
	v_pk_mul_f32 v[78:79], v[78:79], v[118:119]
	v_max_f32_e32 v74, 0, v91
	v_pk_mul_f32 v[76:77], v[76:77], v[116:117]
	v_pk_mul_f32 v[74:75], v[74:75], v[120:121]
	v_mov_b32_e32 v80, v72
	v_mov_b32_e32 v81, v78
	v_mov_b32_e32 v78, v73
	v_pk_add_f32 v[72:73], v[80:81], v[78:79]
	v_mov_b32_e32 v78, v76
	v_mov_b32_e32 v79, v74
	v_pk_add_f32 v[72:73], v[72:73], v[78:79]
	v_mov_b32_e32 v74, v77
	v_pk_add_f32 v[72:73], v[72:73], v[74:75]
	s_nop 0
	v_pk_add_f32 v[72:73], v[72:73], 0 op_sel_hi:[1,0]
	s_nop 0
	v_and_b32_e32 v75, 0x7fffffff, v73
	v_and_b32_e32 v74, 0x7fffffff, v72
	v_xor_b32_e32 v77, -1, v72
	v_pk_add_f32 v[74:75], v[74:75], 0 neg_lo:[1,1] neg_hi:[1,1]
	v_cmp_gt_i32_e64 s[16:17], 0, v72
	v_xor_b32_e32 v76, -1, v73
	s_nop 0
	v_cndmask_b32_e64 v72, v74, v77, s[16:17]
	v_cmp_gt_i32_e64 s[16:17], 0, v73
	s_nop 1
	v_cndmask_b32_e64 v73, v75, v76, s[16:17]
	v_cmp_gt_u32_e64 s[16:17], v73, v35
	v_cmp_eq_u32_e64 s[18:19], v73, v35
	s_nop 0
	v_cndmask_b32_e64 v74, 0, 1, s[16:17]
	v_cmp_gt_u32_e64 s[16:17], v72, v34
	s_nop 1
	v_cndmask_b32_e64 v75, 0, 1, s[16:17]
	v_cmp_eq_u32_e64 s[16:17], v72, v34
	s_nop 1
	v_lshrrev_b64 v[72:73], v150, s[16:17]
	v_and_b32_e32 v72, v72, v105
	v_bcnt_u32_b32 v72, v72, 0
	v_add3_u32 v72, v84, v98, v72
	v_cmp_lt_u32_e64 s[20:21], v72, v38
	s_nop 1
	v_cndmask_b32_e64 v72, 0, 1, s[20:21]
	v_cndmask_b32_e64 v72, v75, v72, s[16:17]
	v_and_b32_e32 v72, 1, v72
	v_cmp_ne_u32_e64 s[16:17], 0, v72
	v_lshrrev_b64 v[72:73], v150, s[18:19]
	v_and_b32_e32 v72, v72, v105
	v_bcnt_u32_b32 v72, v72, 0
	v_add3_u32 v72, v88, v99, v72
	v_cmp_lt_u32_e64 s[20:21], v72, v39
	s_nop 1
	v_cndmask_b32_e64 v72, 0, 1, s[20:21]
	v_cndmask_b32_e64 v72, v74, v72, s[18:19]
	v_and_b32_e32 v72, 1, v72
	v_cmp_ne_u32_e64 s[18:19], 0, v72
	s_and_saveexec_b64 s[20:21], s[40:41]
	s_cbranch_execz .LBB0_1001
	v_lshrrev_b64 v[72:73], v150, vcc
	v_lshrrev_b64 v[80:81], v150, s[52:53]
	v_lshlrev_b32_e32 v73, 16, v80
	v_and_or_b32 v80, v72, s33, v73
	v_lshrrev_b64 v[72:73], v150, s[54:55]
	v_lshrrev_b64 v[74:75], v150, s[44:45]
	v_lshrrev_b64 v[76:77], v150, s[48:49]
	v_lshlrev_b32_e32 v72, 16, v72
	v_and_or_b32 v77, v74, s33, v72
	v_lshrrev_b64 v[72:73], v150, s[56:57]
	v_lshlrev_b32_e32 v72, 16, v72
	v_and_or_b32 v74, v76, s33, v72
	v_lshrrev_b64 v[72:73], v150, s[4:5]
	v_lshrrev_b64 v[78:79], v150, s[50:51]
	v_lshlrev_b32_e32 v72, 16, v72
	v_and_or_b32 v78, v78, s33, v72
	v_lshrrev_b64 v[72:73], v150, s[58:59]
	v_and_b32_e32 v81, 0xffff, v72
	v_lshrrev_b64 v[72:73], v150, s[6:7]
	v_and_b32_e32 v76, 0xffff, v72
	v_lshrrev_b64 v[72:73], v150, s[8:9]
	v_and_b32_e32 v75, 0xffff, v72
	v_lshrrev_b64 v[72:73], v150, s[10:11]
	v_and_b32_e32 v79, 0xffff, v72
	v_lshrrev_b64 v[72:73], v150, s[18:19]
	v_lshlrev_b32_e32 v72, 16, v72
	v_or3_b32 v73, 0, v75, v72
	v_or3_b32 v72, v74, 0, 0
	v_lshrrev_b64 v[74:75], v150, s[16:17]
	v_lshlrev_b32_e32 v74, 16, v74
	v_or3_b32 v75, 0, v76, v74
	v_or3_b32 v74, v77, 0, 0
	v_lshrrev_b64 v[76:77], v150, s[14:15]
	v_lshlrev_b32_e32 v76, 16, v76
	v_or3_b32 v77, 0, v79, v76
	v_or3_b32 v76, v78, 0, 0
	v_lshrrev_b64 v[78:79], v150, s[12:13]
	v_lshlrev_b32_e32 v78, 16, v78
	v_or3_b32 v79, 0, v81, v78
	v_or3_b32 v78, v80, 0, 0
	global_store_dwordx2 v[126:127], v[78:79], off offset:-1024
	global_store_dwordx2 v[126:127], v[76:77], off offset:-512
	global_store_dwordx2 v[126:127], v[74:75], off
	global_store_dwordx2 v[126:127], v[72:73], off offset:512
	s_branch .LBB0_1001

; DI float softmax_step(f32x4 (&st)[4], float& m, float& lsum) {
;   float mx = fmaxf(fmaxf(fmaxf(st[0][0], st[0][1]), fmaxf(st[0][2], st[0][3])), fmaxf(fmaxf(st[1][0], st[1][1]), fmaxf(st[1][2], st[1][3])));
;   mx = fmaxf(mx, fmaxf(fmaxf(fmaxf(st[2][0], st[2][1]), fmaxf(st[2][2], st[2][3])), fmaxf(fmaxf(st[3][0], st[3][1]), fmaxf(st[3][2], st[3][3]))));
;   mx = fmaxf(mx, __shfl_xor(mx, 16)); mx = fmaxf(mx, __shfl_xor(mx, 32));
.LBB0_1079:
	v_readlane_b32 s16, v254, 55
	s_add_i32 s1, s15, -2
	v_readlane_b32 s18, v254, 57
	v_readlane_b32 s19, v254, 58
	v_cmp_le_i32_e32 vcc, s1, v107
	v_readlane_b32 s17, v254, 56
	v_lshl_add_u64 v[122:123], s[18:19], 0, v[112:113]
	s_and_saveexec_b64 s[12:13], vcc
	s_cbranch_execz .LBB0_1081
	v_add_co_u32_e32 v80, vcc, 0x1b900000, v122
	s_mov_b32 s16, 0xff800000
	s_nop 0
	v_addc_co_u32_e32 v81, vcc, 0, v123, vcc
	global_load_dwordx2 v[126:127], v[80:81], off
	v_add_co_u32_e32 v80, vcc, 0x1b902000, v122
	s_waitcnt vmcnt(0)
	v_lshrrev_b32_e32 v147, v132, v126
	v_addc_co_u32_e32 v81, vcc, 0, v123, vcc
	global_load_dwordx2 v[128:129], v[80:81], off
	ds_read_b128 v[80:83], v139
	ds_read_b128 v[84:87], v140
	s_waitcnt lgkmcnt(1)
	v_mfma_f32_16x16x32_f16 v[88:91], v[80:83], v[0:3], 0
	v_and_b32_e32 v130, 1, v147
	v_cmp_eq_u32_e32 vcc, 1, v130
	v_and_b32_e32 v141, 2, v147
	v_mfma_f32_16x16x32_f16 v[80:83], v[80:83], v[4:7], 0
	v_lshrrev_b32_e32 v126, v138, v126
	s_waitcnt lgkmcnt(0)
	v_mfma_f32_16x16x32_f16 v[142:145], v[84:87], v[8:11], v[88:91]
	v_mfma_f32_16x16x32_f16 v[154:157], v[84:87], v[12:15], v[80:83]
	s_nop 3
	ds_read_b128 v[80:83], v139 offset:2048
	ds_read_b128 v[84:87], v140 offset:2048
	s_waitcnt lgkmcnt(1)
	v_mfma_f32_16x16x32_f16 v[88:91], v[80:83], v[0:3], 0
	v_mfma_f32_16x16x32_f16 v[80:83], v[80:83], v[4:7], 0
	s_waitcnt lgkmcnt(0)
	v_mfma_f32_16x16x32_f16 v[100:103], v[84:87], v[8:11], v[88:91]
	v_mfma_f32_16x16x32_f16 v[96:99], v[84:87], v[12:15], v[80:83]
	s_nop 4
	ds_read_b128 v[80:83], v139 offset:4096
	ds_read_b128 v[88:91], v140 offset:4096
	s_waitcnt lgkmcnt(1)
	v_mfma_f32_16x16x32_f16 v[84:87], v[80:83], v[0:3], 0
	v_mfma_f32_16x16x32_f16 v[80:83], v[80:83], v[4:7], 0
	s_waitcnt lgkmcnt(0)
	v_mfma_f32_16x16x32_f16 v[84:87], v[88:91], v[8:11], v[84:87]
	v_mfma_f32_16x16x32_f16 v[80:83], v[88:91], v[12:15], v[80:83]
	ds_read_b128 v[88:91], v139 offset:6144
	ds_read_b128 v[92:95], v140 offset:6144
	s_waitcnt lgkmcnt(1)
	v_mfma_f32_16x16x32_f16 v[158:161], v[88:91], v[0:3], 0
	v_mfma_f32_16x16x32_f16 v[162:165], v[88:91], v[4:7], 0
	s_waitcnt lgkmcnt(0)
	v_mfma_f32_16x16x32_f16 v[88:91], v[92:95], v[8:11], v[158:161]
	s_nop 4
	v_cndmask_b32_e32 v159, v187, v142, vcc
	v_and_b32_e32 v142, 4, v147
	v_mfma_f32_16x16x32_f16 v[92:95], v[92:95], v[12:15], v[162:165]
	s_waitcnt vmcnt(0)
	v_lshrrev_b32_e32 v158, v132, v128
	v_and_b32_e32 v130, 1, v158
	v_cmp_eq_u32_e32 vcc, 1, v130
	v_lshrrev_b32_e32 v128, v138, v128
	s_nop 0
	v_cndmask_b32_e32 v130, v187, v154, vcc
	v_cmp_ne_u32_e32 vcc, 0, v141
	v_and_b32_e32 v141, 2, v158
	s_nop 0
	v_cndmask_b32_e32 v154, v187, v143, vcc
	v_cmp_ne_u32_e32 vcc, 0, v141
	v_and_b32_e32 v143, 8, v147
	v_and_b32_e32 v147, 1, v126
	v_cndmask_b32_e32 v141, v187, v155, vcc
	v_cmp_ne_u32_e32 vcc, 0, v142
	v_and_b32_e32 v142, 4, v158
	s_nop 0
	v_cndmask_b32_e32 v144, v187, v144, vcc
	v_cmp_ne_u32_e32 vcc, 0, v142
	s_nop 1
	v_cndmask_b32_e32 v142, v187, v156, vcc
	v_cmp_ne_u32_e32 vcc, 0, v143
	v_and_b32_e32 v143, 8, v158
	s_nop 0
	v_cndmask_b32_e32 v145, v187, v145, vcc
	v_cmp_ne_u32_e32 vcc, 0, v143
	s_nop 1
	v_cndmask_b32_e32 v143, v187, v157, vcc
	v_cmp_eq_u32_e32 vcc, 1, v147
	v_and_b32_e32 v147, 1, v128
	s_nop 0
	v_cndmask_b32_e32 v100, v187, v100, vcc
	v_cmp_eq_u32_e32 vcc, 1, v147
	s_nop 1
	v_cndmask_b32_e32 v147, v187, v96, vcc
	v_and_b32_e32 v96, 2, v126
	v_cmp_ne_u32_e32 vcc, 0, v96
	s_nop 1
	v_cndmask_b32_e32 v96, v187, v101, vcc
	v_and_b32_e32 v101, 2, v128
	v_cmp_ne_u32_e32 vcc, 0, v101
	v_and_b32_e32 v101, 4, v126
	s_nop 0
	v_cndmask_b32_e32 v97, v187, v97, vcc
	v_cmp_ne_u32_e32 vcc, 0, v101
	s_nop 1
	v_cndmask_b32_e32 v101, v187, v102, vcc
	v_and_b32_e32 v102, 4, v128
	v_cmp_ne_u32_e32 vcc, 0, v102
	v_and_b32_e32 v102, 8, v126
	v_lshrrev_b32_e32 v126, v132, v129
	v_cndmask_b32_e32 v98, v187, v98, vcc
	v_cmp_ne_u32_e32 vcc, 0, v102
	s_nop 1
	v_cndmask_b32_e32 v102, v187, v103, vcc
	v_and_b32_e32 v103, 8, v128
	v_cmp_ne_u32_e32 vcc, 0, v103
	s_nop 1
	v_cndmask_b32_e32 v103, v187, v99, vcc
	v_lshrrev_b32_e32 v99, v132, v127
	v_and_b32_e32 v128, 1, v99
	v_cmp_eq_u32_e32 vcc, 1, v128
	v_and_b32_e32 v128, 1, v126
	s_nop 0
	v_cndmask_b32_e32 v84, v187, v84, vcc
	v_cmp_eq_u32_e32 vcc, 1, v128
	s_nop 1
	v_cndmask_b32_e32 v128, v187, v80, vcc
	v_and_b32_e32 v80, 2, v99
	v_cmp_ne_u32_e32 vcc, 0, v80
	s_nop 1
	v_cndmask_b32_e32 v80, v187, v85, vcc
	v_and_b32_e32 v85, 2, v126
	v_cmp_ne_u32_e32 vcc, 0, v85
	v_and_b32_e32 v85, 4, v99
	s_nop 0
	v_cndmask_b32_e32 v81, v187, v81, vcc
	v_cmp_ne_u32_e32 vcc, 0, v85
	s_nop 1
	v_cndmask_b32_e32 v85, v187, v86, vcc
	v_and_b32_e32 v86, 4, v126
	v_cmp_ne_u32_e32 vcc, 0, v86
	v_and_b32_e32 v86, 8, v126
	s_nop 0
	v_cndmask_b32_e32 v155, v187, v82, vcc
	v_and_b32_e32 v82, 8, v99
	v_cmp_ne_u32_e32 vcc, 0, v82
	s_nop 1
	v_cndmask_b32_e32 v82, v187, v87, vcc
	v_cmp_ne_u32_e32 vcc, 0, v86
	v_lshrrev_b32_e32 v86, v138, v127
	v_lshrrev_b32_e32 v87, v138, v129
	v_and_b32_e32 v99, 1, v86
	v_cndmask_b32_e32 v83, v187, v83, vcc
	v_cmp_eq_u32_e32 vcc, 1, v99
	v_and_b32_e32 v99, 1, v87
	s_nop 0
	v_cndmask_b32_e32 v88, v187, v88, vcc
	v_cmp_eq_u32_e32 vcc, 1, v99
	s_nop 1
	v_cndmask_b32_e32 v126, v187, v92, vcc
	v_and_b32_e32 v92, 2, v86
	v_cmp_ne_u32_e32 vcc, 0, v92
	v_and_b32_e32 v92, 2, v87
	s_nop 0
	v_cndmask_b32_e32 v89, v187, v89, vcc
	v_cmp_ne_u32_e32 vcc, 0, v92
	v_and_b32_e32 v92, 4, v86
	v_and_b32_e32 v86, 8, v86
	v_cndmask_b32_e32 v127, v187, v93, vcc
	v_cmp_ne_u32_e32 vcc, 0, v92
	v_max_f32_e32 v92, v84, v84
	s_nop 0
	v_cndmask_b32_e32 v93, v187, v90, vcc
	v_and_b32_e32 v90, 4, v87
	v_cmp_ne_u32_e32 vcc, 0, v90
	v_max_f32_e32 v90, v101, v101
	s_nop 0
	v_cndmask_b32_e32 v129, v187, v94, vcc
	v_cmp_ne_u32_e32 vcc, 0, v86
	v_and_b32_e32 v86, 8, v87
	v_max_f32_e32 v87, v144, v144
	v_cndmask_b32_e32 v91, v187, v91, vcc
	v_cmp_ne_u32_e32 vcc, 0, v86
	v_max_f32_e32 v86, v87, v145
	v_max_f32_e32 v87, v90, v102
	v_max_f32_e32 v90, v92, v80
	v_cndmask_b32_e32 v156, v187, v95, vcc
	v_max_f32_e32 v92, v85, v82
	v_max_f32_e32 v94, v93, v91
	v_max3_f32 v94, v88, v89, v94
	v_max3_f32 v86, v159, v154, v86
	v_max3_f32 v87, v100, v96, v87
	v_max3_f32 v90, v90, v92, v94
	v_max3_f32 v86, v86, v87, v90
	ds_bpermute_b32 v87, v189, v86
	s_waitcnt lgkmcnt(0)
; DI float softmax_step(f32x4 (&st)[4], float& m, float& lsum) {
;   float mx = fmaxf(fmaxf(fmaxf(st[0][0], st[0][1]), fmaxf(st[0][2], st[0][3])), fmaxf(fmaxf(st[1][0], st[1][1]), fmaxf(st[1][2], st[1][3])));
;   mx = fmaxf(mx, fmaxf(fmaxf(fmaxf(st[2][0], st[2][1]), fmaxf(st[2][2], st[2][3])), fmaxf(fmaxf(st[3][0], st[3][1]), fmaxf(st[3][2], st[3][3]))));
;   mx = fmaxf(mx, __shfl_xor(mx, 16)); mx = fmaxf(mx, __shfl_xor(mx, 32));
;   const float mn = fmaxf(m, mx);
;   const float mu = mn == -INFINITY ? 0.f : mn;
;   const float alpha = __builtin_amdgcn_exp2f(m - mu);
;   float ps = 0.f;
; #pragma unroll
;   for (int kt = 0; kt < 4; ++kt)
; #pragma unroll
;     for (int j = 0; j < 4; ++j) { const float p = __builtin_amdgcn_exp2f(st[kt][j] - mu); st[kt][j] = p; ps += p; }
;   lsum = lsum * alpha + ps; m = mn;
;   return alpha;
; }
	v_max_f32_e32 v86, v86, v87
	ds_bpermute_b32 v87, v188, v86
	s_waitcnt lgkmcnt(0)
	v_max3_f32 v99, v131, v86, v87
	v_cmp_neq_f32_e32 vcc, s16, v99
	s_nop 1
	v_cndmask_b32_e32 v87, 0, v99, vcc
	v_sub_f32_e32 v86, v159, v87
	v_exp_f32_e32 v162, v86
	v_sub_f32_e32 v86, v154, v87
	v_exp_f32_e32 v164, v86
	v_sub_f32_e32 v86, v144, v87
	v_exp_f32_e32 v166, v86
	v_sub_f32_e32 v86, v145, v87
	v_sub_f32_e32 v80, v80, v87
	v_exp_f32_e32 v168, v86
	v_sub_f32_e32 v86, v100, v87
	v_exp_f32_e32 v94, v80
	v_sub_f32_e32 v80, v85, v87
	v_exp_f32_e32 v170, v86
	v_sub_f32_e32 v86, v96, v87
	v_exp_f32_e32 v92, v80
	v_sub_f32_e32 v80, v82, v87
	v_exp_f32_e32 v190, v86
	v_sub_f32_e32 v86, v101, v87
	v_exp_f32_e32 v90, v80
	v_sub_f32_e32 v80, v88, v87
	v_exp_f32_e32 v192, v86
	v_sub_f32_e32 v86, v102, v87
	v_exp_f32_e32 v88, v80
	v_sub_f32_e32 v80, v89, v87
	v_exp_f32_e32 v194, v86
	v_sub_f32_e32 v84, v84, v87
	v_exp_f32_e32 v86, v80
	v_sub_f32_e32 v80, v93, v87
	v_exp_f32_e32 v96, v84
	v_exp_f32_e32 v82, v80
	v_sub_f32_e32 v80, v91, v87
	v_sub_f32_e32 v84, v131, v87
	v_max_f32_e32 v85, v142, v143
	v_max_f32_e32 v87, v98, v103
	v_max_f32_e32 v89, v128, v81
	v_max_f32_e32 v91, v155, v83
	v_max_f32_e32 v93, v129, v156
	v_max3_f32 v93, v126, v127, v93
	v_max3_f32 v85, v130, v141, v85
	v_max3_f32 v87, v147, v97, v87
	v_max3_f32 v89, v89, v91, v93
	v_max3_f32 v85, v85, v87, v89
	ds_bpermute_b32 v87, v189, v85
	v_exp_f32_e32 v84, v84
	v_exp_f32_e32 v80, v80
	v_mov_b32_e32 v131, v99
	s_waitcnt lgkmcnt(0)
	v_max_f32_e32 v85, v85, v87
	ds_bpermute_b32 v87, v188, v85
	s_waitcnt lgkmcnt(0)
	v_max3_f32 v102, v146, v85, v87
	v_cmp_neq_f32_e32 vcc, s16, v102
	s_nop 1
	v_cndmask_b32_e32 v85, 0, v102, vcc
	v_sub_f32_e32 v87, v130, v85
	v_exp_f32_e32 v163, v87
	v_sub_f32_e32 v87, v141, v85
	v_exp_f32_e32 v165, v87
	v_sub_f32_e32 v87, v142, v85
	v_exp_f32_e32 v167, v87
	v_sub_f32_e32 v87, v143, v85
	v_exp_f32_e32 v169, v87
	v_sub_f32_e32 v87, v147, v85
	v_sub_f32_e32 v81, v81, v85
	v_exp_f32_e32 v171, v87
	v_sub_f32_e32 v87, v97, v85
	v_exp_f32_e32 v95, v81
	v_sub_f32_e32 v81, v155, v85
	v_exp_f32_e32 v191, v87
	v_sub_f32_e32 v87, v98, v85
	v_exp_f32_e32 v93, v81
	v_sub_f32_e32 v81, v83, v85
	v_exp_f32_e32 v193, v87
	v_sub_f32_e32 v87, v103, v85
	v_exp_f32_e32 v91, v81
	v_sub_f32_e32 v81, v126, v85
	v_exp_f32_e32 v195, v87
	v_sub_f32_e32 v87, v128, v85
	v_exp_f32_e32 v89, v81
	v_sub_f32_e32 v81, v127, v85
	v_exp_f32_e32 v97, v87
	v_exp_f32_e32 v87, v81
	v_sub_f32_e32 v81, v129, v85
	v_exp_f32_e32 v83, v81
	v_sub_f32_e32 v81, v156, v85
	v_sub_f32_e32 v85, v146, v85
	v_exp_f32_e32 v98, v85
	v_pk_mul_f32 v[156:157], v[70:71], v[84:85] op_sel_hi:[1,0]
	v_pk_mul_f32 v[154:155], v[68:69], v[84:85] op_sel_hi:[1,0]
	v_pk_mul_f32 v[128:129], v[62:63], v[84:85] op_sel_hi:[1,0]
	v_pk_mul_f32 v[142:143], v[56:57], v[98:99] op_sel_hi:[1,0]
	v_pk_mul_f32 v[70:71], v[50:51], v[98:99] op_sel_hi:[1,0]
	v_pk_mul_f32 v[68:69], v[48:49], v[98:99] op_sel_hi:[1,0]
	v_pk_mul_f32 v[50:51], v[74:75], v[84:85] op_sel_hi:[1,0]
	v_pk_mul_f32 v[48:49], v[72:73], v[84:85] op_sel_hi:[1,0]
	v_pk_add_f32 v[56:57], v[162:163], 0 op_sel_hi:[1,0]
	ds_read_b128 v[72:75], v139 offset:9216
	v_pk_add_f32 v[56:57], v[164:165], v[56:57]
	v_pk_mul_f32 v[126:127], v[60:61], v[84:85] op_sel_hi:[1,0]
	v_pk_add_f32 v[56:57], v[166:167], v[56:57]
	v_pk_mul_f32 v[144:145], v[58:59], v[98:99] op_sel_hi:[1,0]
	v_pk_add_f32 v[56:57], v[168:169], v[56:57]
	v_cvt_pk_f16_f32 v58, v170, v190
	v_pk_add_f32 v[56:57], v[170:171], v[56:57]
	v_cvt_pk_f16_f32 v59, v192, v194
	v_pk_add_f32 v[56:57], v[190:191], v[56:57]
	v_pk_mul_f32 v[160:161], v[66:67], v[98:99] op_sel_hi:[1,0]
	v_pk_add_f32 v[56:57], v[192:193], v[56:57]
	v_pk_mul_f32 v[158:159], v[64:65], v[98:99] op_sel_hi:[1,0]
	v_pk_add_f32 v[56:57], v[194:195], v[56:57]
	v_pk_mul_f32 v[66:67], v[54:55], v[84:85] op_sel_hi:[1,0]
	v_pk_add_f32 v[100:101], v[96:97], v[56:57]
	v_cvt_pk_f16_f32 v56, v162, v164
	v_cvt_pk_f16_f32 v57, v166, v168
	v_pk_mul_f32 v[64:65], v[52:53], v[84:85] op_sel_hi:[1,0]
	v_pk_mul_f32 v[54:55], v[78:79], v[98:99] op_sel_hi:[1,0]
	v_pk_mul_f32 v[52:53], v[76:77], v[98:99] op_sel_hi:[1,0]
	s_waitcnt lgkmcnt(0)
	v_mfma_f32_16x16x32_f16 v[76:79], v[72:75], v[56:59], v[126:129]
	v_cvt_pk_f16_f32 v60, v163, v165
	v_cvt_pk_f16_f32 v61, v167, v169
	v_cvt_pk_f16_f32 v62, v171, v191
	ds_read_b128 v[126:129], v139 offset:11264
	v_cvt_pk_f16_f32 v63, v193, v195
	v_exp_f32_e32 v81, v81
	v_cvt_pk_f16_f32 v190, v96, v94
	v_mfma_f32_16x16x32_f16 v[72:75], v[72:75], v[60:63], v[142:145]
	v_cvt_pk_f16_f32 v191, v92, v90
	v_cvt_pk_f16_f32 v192, v88, v86
	v_cvt_pk_f16_f32 v193, v82, v80
	s_waitcnt lgkmcnt(0)
	v_mfma_f32_16x16x32_f16 v[142:145], v[126:129], v[56:59], v[154:157]
	v_cvt_pk_f16_f32 v194, v97, v95
	v_cvt_pk_f16_f32 v195, v93, v91
	s_nop 0
	ds_read_b128 v[154:157], v139 offset:13312
	v_mfma_f32_16x16x32_f16 v[126:129], v[126:129], v[60:63], v[158:161]
	v_cvt_pk_f16_f32 v196, v89, v87
	v_cvt_pk_f16_f32 v197, v83, v81
	v_pk_add_f32 v[94:95], v[94:95], v[100:101]
	s_waitcnt lgkmcnt(0)
	v_mfma_f32_16x16x32_f16 v[158:161], v[154:157], v[56:59], v[64:67]
	s_nop 2
	ds_read_b128 v[64:67], v139 offset:15360
	v_pk_add_f32 v[92:93], v[92:93], v[94:95]
	v_mov_b32_e32 v85, v98
	s_waitcnt lgkmcnt(0)
	v_mfma_f32_16x16x32_f16 v[162:165], v[64:67], v[56:59], v[48:51]
	s_nop 2
	ds_read_b128 v[48:51], v140 offset:9216
	v_pk_add_f32 v[90:91], v[90:91], v[92:93]
	v_mov_b32_e32 v146, v102
	v_mfma_f32_16x16x32_f16 v[154:157], v[154:157], v[60:63], v[68:71]
	v_add_f32_e64 v88, v88, v90
	v_add_f32_e64 v89, v89, v91
	v_pk_add_f32 v[86:87], v[86:87], v[88:89]
	v_mfma_f32_16x16x32_f16 v[166:169], v[64:67], v[60:63], v[52:55]
	v_add_f32_e64 v82, v82, v86
	v_add_f32_e64 v83, v83, v87
	v_pk_add_f32 v[80:81], v[80:81], v[82:83]
	s_waitcnt lgkmcnt(0)
	v_mfma_f32_16x16x32_f16 v[60:63], v[48:51], v[190:193], v[76:79]
	v_fma_f32 v118, v118, v84, v80
	v_fma_f32 v119, v119, v85, v81
	v_mfma_f32_16x16x32_f16 v[56:59], v[48:51], v[194:197], v[72:75]
	ds_read_b128 v[48:51], v140 offset:11264
	ds_read_b128 v[76:79], v140 offset:15360
	s_waitcnt lgkmcnt(1)
	v_mfma_f32_16x16x32_f16 v[68:71], v[48:51], v[190:193], v[142:145]
	v_mfma_f32_16x16x32_f16 v[64:67], v[48:51], v[194:197], v[126:129]
	ds_read_b128 v[48:51], v140 offset:13312
	s_waitcnt lgkmcnt(0)
	v_mfma_f32_16x16x32_f16 v[52:55], v[48:51], v[190:193], v[158:161]
	v_mfma_f32_16x16x32_f16 v[48:51], v[48:51], v[194:197], v[154:157]
	v_mfma_f32_16x16x32_f16 v[72:75], v[76:79], v[190:193], v[162:165]
	v_mfma_f32_16x16x32_f16 v[76:79], v[76:79], v[194:197], v[166:169]

; #define MFMA16(a, b, c) __builtin_amdgcn_mfma_f32_16x16x32_f16((a), (b), (c), 0, 0, 0)
; DI void qk_tile2(f32x4 (&sa)[4], f32x4 (&sb)[4], const char* sK, const bf16x8 (&qa)[2], const bf16x8 (&qb)[2], int lr, int g) {
; #pragma unroll
;   for (int kt = 0; kt < 4; ++kt) {
;     const bf16x8 k0 = *(const bf16x8*)(sK + (kt * 16 + lr) * 128 + ((g ^ ((lr >> 1) & 7)) << 4)), k1 = *(const bf16x8*)(sK + (kt * 16 + lr) * 128 + (((4 + g) ^ ((lr >> 1) & 7)) << 4));
;     sa[kt] = MFMA16(k0, qa[0], ((f32x4){0.f, 0.f, 0.f, 0.f})); sb[kt] = MFMA16(k0, qb[0], ((f32x4){0.f, 0.f, 0.f, 0.f}));
;     sa[kt] = MFMA16(k1, qa[1], sa[kt]); sb[kt] = MFMA16(k1, qb[1], sb[kt]);
;   }
; }
; DI float softmax_step(f32x4 (&st)[4], float& m, float& lsum) {
;   float mx = fmaxf(fmaxf(fmaxf(st[0][0], st[0][1]), fmaxf(st[0][2], st[0][3])), fmaxf(fmaxf(st[1][0], st[1][1]), fmaxf(st[1][2], st[1][3])));
;   mx = fmaxf(mx, fmaxf(fmaxf(fmaxf(st[2][0], st[2][1]), fmaxf(st[2][2], st[2][3])), fmaxf(fmaxf(st[3][0], st[3][1]), fmaxf(st[3][2], st[3][3]))));
;   mx = fmaxf(mx, __shfl_xor(mx, 16)); mx = fmaxf(mx, __shfl_xor(mx, 32));
.LBB0_1085:
	v_add_co_u32_e32 v80, vcc, 0x1b900000, v122
	s_mov_b32 s1, 0xff800000
	s_nop 0
	v_addc_co_u32_e32 v81, vcc, 0, v123, vcc
	global_load_dwordx2 v[128:129], v[80:81], off offset:8
	v_add_co_u32_e32 v80, vcc, 0x1b902000, v122
	s_nop 1
	v_addc_co_u32_e32 v81, vcc, 0, v123, vcc
	global_load_dwordx2 v[144:145], v[80:81], off offset:8
	ds_read_b128 v[80:83], v139 offset:18432
	ds_read_b128 v[84:87], v140 offset:18432
	s_waitcnt lgkmcnt(1)
	v_mfma_f32_16x16x32_f16 v[88:91], v[80:83], v[0:3], 0
	v_mfma_f32_16x16x32_f16 v[80:83], v[80:83], v[4:7], 0
	s_waitcnt lgkmcnt(0)
	v_mfma_f32_16x16x32_f16 v[88:91], v[84:87], v[8:11], v[88:91]
	v_mfma_f32_16x16x32_f16 v[80:83], v[84:87], v[12:15], v[80:83]
	ds_read_b128 v[84:87], v139 offset:20480
	ds_read_b128 v[92:95], v140 offset:20480
	s_waitcnt lgkmcnt(1)
	v_mfma_f32_16x16x32_f16 v[96:99], v[84:87], v[0:3], 0
	v_mfma_f32_16x16x32_f16 v[84:87], v[84:87], v[4:7], 0
	s_waitcnt lgkmcnt(0)
	v_mfma_f32_16x16x32_f16 v[96:99], v[92:95], v[8:11], v[96:99]
	v_mfma_f32_16x16x32_f16 v[84:87], v[92:95], v[12:15], v[84:87]
	ds_read_b128 v[92:95], v139 offset:22528
	ds_read_b128 v[100:103], v140 offset:22528
	s_waitcnt lgkmcnt(1)
	v_mfma_f32_16x16x32_f16 v[120:123], v[92:95], v[0:3], 0
	v_mfma_f32_16x16x32_f16 v[92:95], v[92:95], v[4:7], 0
	s_waitcnt lgkmcnt(0)
	v_mfma_f32_16x16x32_f16 v[120:123], v[100:103], v[8:11], v[120:123]
	v_mfma_f32_16x16x32_f16 v[92:95], v[100:103], v[12:15], v[92:95]
	ds_read_b128 v[100:103], v139 offset:24576
	ds_read_b128 v[124:127], v140 offset:24576
	s_waitcnt lgkmcnt(1)
	v_mfma_f32_16x16x32_f16 v[154:157], v[100:103], v[0:3], 0
	v_mfma_f32_16x16x32_f16 v[100:103], v[100:103], v[4:7], 0
	s_waitcnt lgkmcnt(0)
	v_mfma_f32_16x16x32_f16 v[154:157], v[124:127], v[8:11], v[154:157]
	v_mfma_f32_16x16x32_f16 v[100:103], v[124:127], v[12:15], v[100:103]
	s_waitcnt vmcnt(1)
	v_lshrrev_b32_e32 v124, v132, v128
	v_and_b32_e32 v126, 1, v124
	v_cmp_eq_u32_e32 vcc, 1, v126
	s_waitcnt vmcnt(0)
	v_lshrrev_b32_e32 v125, v132, v144
	v_and_b32_e32 v126, 1, v125
	v_cndmask_b32_e32 v88, v187, v88, vcc
	v_cmp_eq_u32_e32 vcc, 1, v126
	v_and_b32_e32 v126, 2, v124
	s_nop 0
	v_cndmask_b32_e32 v80, v187, v80, vcc
	v_cmp_ne_u32_e32 vcc, 0, v126
	v_and_b32_e32 v126, 2, v125
	s_nop 0
	v_cndmask_b32_e32 v89, v187, v89, vcc
	v_cmp_ne_u32_e32 vcc, 0, v126
	v_and_b32_e32 v126, 4, v124
	v_and_b32_e32 v124, 8, v124
	v_cndmask_b32_e32 v81, v187, v81, vcc
	v_cmp_ne_u32_e32 vcc, 0, v126
	v_and_b32_e32 v126, 4, v125
	s_nop 0
	v_cndmask_b32_e32 v90, v187, v90, vcc
	v_cmp_ne_u32_e32 vcc, 0, v126
	s_nop 1
	v_cndmask_b32_e32 v82, v187, v82, vcc
	v_cmp_ne_u32_e32 vcc, 0, v124
	v_and_b32_e32 v124, 8, v125
	v_lshrrev_b32_e32 v125, v138, v144
	v_cndmask_b32_e32 v91, v187, v91, vcc
	v_cmp_ne_u32_e32 vcc, 0, v124
	v_lshrrev_b32_e32 v124, v138, v128
	v_and_b32_e32 v126, 1, v124
	v_cndmask_b32_e32 v83, v187, v83, vcc
	v_cmp_eq_u32_e32 vcc, 1, v126
	v_and_b32_e32 v126, 1, v125
	s_nop 0
	v_cndmask_b32_e32 v96, v187, v96, vcc
	v_cmp_eq_u32_e32 vcc, 1, v126
	s_nop 1
	v_cndmask_b32_e32 v127, v187, v84, vcc
	v_and_b32_e32 v84, 2, v124
	v_cmp_ne_u32_e32 vcc, 0, v84
	v_and_b32_e32 v84, 2, v125
	s_nop 0
	v_cndmask_b32_e32 v97, v187, v97, vcc
	v_cmp_ne_u32_e32 vcc, 0, v84
	v_and_b32_e32 v84, 4, v124
	s_nop 0
	v_cndmask_b32_e32 v147, v187, v85, vcc
	v_cmp_ne_u32_e32 vcc, 0, v84
	v_and_b32_e32 v84, 4, v125
	s_nop 0
	v_cndmask_b32_e32 v85, v187, v98, vcc
	v_cmp_ne_u32_e32 vcc, 0, v84
	v_and_b32_e32 v84, 8, v124
	s_nop 0
	v_cndmask_b32_e32 v98, v187, v86, vcc
	v_cmp_ne_u32_e32 vcc, 0, v84
	v_and_b32_e32 v84, 8, v125
	v_lshrrev_b32_e32 v86, v132, v145
	v_cndmask_b32_e32 v99, v187, v99, vcc
	v_cmp_ne_u32_e32 vcc, 0, v84
	v_lshrrev_b32_e32 v84, v132, v129
	s_nop 0
	v_cndmask_b32_e32 v125, v187, v87, vcc
	v_and_b32_e32 v87, 1, v84
	v_cmp_eq_u32_e32 vcc, 1, v87
	s_nop 1
	v_cndmask_b32_e32 v87, v187, v120, vcc
	v_and_b32_e32 v120, 1, v86
	v_cmp_eq_u32_e32 vcc, 1, v120
	v_and_b32_e32 v120, 2, v84
	v_max_f32_e32 v126, v87, v87
	v_cndmask_b32_e32 v92, v187, v92, vcc
	v_cmp_ne_u32_e32 vcc, 0, v120
	s_nop 1
	v_cndmask_b32_e32 v120, v187, v121, vcc
	v_and_b32_e32 v121, 2, v86
	v_cmp_ne_u32_e32 vcc, 0, v121
	v_and_b32_e32 v121, 4, v84
	v_and_b32_e32 v84, 8, v84
	v_cndmask_b32_e32 v93, v187, v93, vcc
	v_cmp_ne_u32_e32 vcc, 0, v121
	s_nop 1
	v_cndmask_b32_e32 v121, v187, v122, vcc
	v_and_b32_e32 v122, 4, v86
	v_cmp_ne_u32_e32 vcc, 0, v122
	v_max_f32_e32 v144, v121, v121
	s_nop 0
	v_cndmask_b32_e32 v94, v187, v94, vcc
	v_cmp_ne_u32_e32 vcc, 0, v84
	v_and_b32_e32 v84, 8, v86
	v_lshrrev_b32_e32 v86, v138, v145
	v_cndmask_b32_e32 v122, v187, v123, vcc
	v_cmp_ne_u32_e32 vcc, 0, v84
	v_lshrrev_b32_e32 v84, v138, v129
	v_and_b32_e32 v123, 1, v84
	v_cndmask_b32_e32 v95, v187, v95, vcc
	v_cmp_eq_u32_e32 vcc, 1, v123
	v_and_b32_e32 v124, 1, v86
	s_nop 0
	v_cndmask_b32_e32 v123, v187, v154, vcc
	v_cmp_eq_u32_e32 vcc, 1, v124
	v_and_b32_e32 v124, 2, v86
	s_nop 0
	v_cndmask_b32_e32 v129, v187, v100, vcc
	v_and_b32_e32 v100, 2, v84
	v_cmp_ne_u32_e32 vcc, 0, v100
	s_nop 1
	v_cndmask_b32_e32 v100, v187, v155, vcc
	v_cmp_ne_u32_e32 vcc, 0, v124
	v_and_b32_e32 v124, 4, v84
	v_and_b32_e32 v84, 8, v84
	v_cndmask_b32_e32 v101, v187, v101, vcc
	v_cmp_ne_u32_e32 vcc, 0, v124
	v_and_b32_e32 v124, 4, v86
	s_nop 0
	v_cndmask_b32_e32 v128, v187, v156, vcc
	v_cmp_ne_u32_e32 vcc, 0, v124
	v_max_f32_e32 v124, v85, v85
	v_max_f32_e32 v145, v128, v128
	v_cndmask_b32_e32 v102, v187, v102, vcc
	v_cmp_ne_u32_e32 vcc, 0, v84
	v_and_b32_e32 v84, 8, v86
	v_max_f32_e32 v86, v90, v90
	v_cndmask_b32_e32 v130, v187, v157, vcc
	v_cmp_ne_u32_e32 vcc, 0, v84
	v_max_f32_e32 v84, v86, v91
	v_max_f32_e32 v86, v124, v99
	v_max_f32_e32 v124, v126, v120
	v_max_f32_e32 v126, v144, v122
	v_max_f32_e32 v144, v145, v130
	v_max3_f32 v144, v123, v100, v144
	v_max3_f32 v84, v88, v89, v84
	v_max3_f32 v86, v96, v97, v86
	v_max3_f32 v124, v124, v126, v144
	v_max3_f32 v84, v84, v86, v124
	ds_bpermute_b32 v86, v189, v84
	v_cndmask_b32_e32 v103, v187, v103, vcc
	s_waitcnt lgkmcnt(0)
; DI float softmax_step(f32x4 (&st)[4], float& m, float& lsum) {
;   float mx = fmaxf(fmaxf(fmaxf(st[0][0], st[0][1]), fmaxf(st[0][2], st[0][3])), fmaxf(fmaxf(st[1][0], st[1][1]), fmaxf(st[1][2], st[1][3])));
;   mx = fmaxf(mx, fmaxf(fmaxf(fmaxf(st[2][0], st[2][1]), fmaxf(st[2][2], st[2][3])), fmaxf(fmaxf(st[3][0], st[3][1]), fmaxf(st[3][2], st[3][3]))));
;   mx = fmaxf(mx, __shfl_xor(mx, 16)); mx = fmaxf(mx, __shfl_xor(mx, 32));
;   const float mn = fmaxf(m, mx);
;   const float mu = mn == -INFINITY ? 0.f : mn;
;   const float alpha = __builtin_amdgcn_exp2f(m - mu);
;   float ps = 0.f;
; #pragma unroll
;   for (int kt = 0; kt < 4; ++kt)
; #pragma unroll
;     for (int j = 0; j < 4; ++j) { const float p = __builtin_amdgcn_exp2f(st[kt][j] - mu); st[kt][j] = p; ps += p; }
;   lsum = lsum * alpha + ps; m = mn;
;   return alpha;
; }
	v_max_f32_e32 v84, v84, v86
	ds_bpermute_b32 v86, v188, v84
	s_waitcnt lgkmcnt(0)
	v_max3_f32 v144, v131, v84, v86
	v_cmp_neq_f32_e32 vcc, s1, v144
	s_nop 1
	v_cndmask_b32_e32 v145, 0, v144, vcc
	v_sub_f32_e32 v84, v88, v145
	v_sub_f32_e32 v88, v90, v145
	v_exp_f32_e32 v162, v88
	v_sub_f32_e32 v88, v91, v145
	v_sub_f32_e32 v85, v85, v145
	v_exp_f32_e32 v164, v88
	v_sub_f32_e32 v88, v96, v145
	v_exp_f32_e32 v170, v85
	v_sub_f32_e32 v85, v99, v145
	v_exp_f32_e32 v166, v88
	v_sub_f32_e32 v88, v97, v145
	v_exp_f32_e32 v190, v85
	v_sub_f32_e32 v85, v87, v145
	v_exp_f32_e32 v168, v88
	v_exp_f32_e32 v88, v85
	v_sub_f32_e32 v85, v120, v145
	v_exp_f32_e32 v90, v85
	v_sub_f32_e32 v85, v121, v145
	v_exp_f32_e32 v120, v85
	v_sub_f32_e32 v85, v122, v145
	v_exp_f32_e32 v122, v85
	v_sub_f32_e32 v85, v123, v145
	v_exp_f32_e32 v124, v85
	v_sub_f32_e32 v85, v100, v145
	v_exp_f32_e32 v126, v85
	v_sub_f32_e32 v85, v128, v145
	v_exp_f32_e32 v128, v85
	v_sub_f32_e32 v85, v130, v145
	v_exp_f32_e32 v130, v85
	v_sub_f32_e32 v85, v131, v145
	v_exp_f32_e32 v100, v85
	v_sub_f32_e32 v86, v89, v145
	v_max_f32_e32 v85, v82, v83
	v_max_f32_e32 v87, v98, v125
	v_max_f32_e32 v89, v92, v93
	v_max_f32_e32 v91, v94, v95
	v_max_f32_e32 v96, v102, v103
	v_max3_f32 v96, v129, v101, v96
	v_max3_f32 v85, v80, v81, v85
	v_max3_f32 v87, v127, v147, v87
	v_max3_f32 v89, v89, v91, v96
	v_max3_f32 v85, v85, v87, v89
	ds_bpermute_b32 v87, v189, v85
	v_exp_f32_e32 v84, v84
	v_exp_f32_e32 v86, v86
	v_pk_mul_f32 v[70:71], v[70:71], v[100:101] op_sel_hi:[1,0]
	v_pk_mul_f32 v[68:69], v[68:69], v[100:101] op_sel_hi:[1,0]
	s_waitcnt lgkmcnt(0)
	v_max_f32_e32 v85, v85, v87
	ds_bpermute_b32 v87, v188, v85
	v_pk_mul_f32 v[156:157], v[54:55], v[100:101] op_sel_hi:[1,0]
	v_pk_mul_f32 v[154:155], v[52:53], v[100:101] op_sel_hi:[1,0]
	s_waitcnt lgkmcnt(0)
	v_max3_f32 v145, v146, v85, v87
	v_cmp_neq_f32_e32 vcc, s1, v145
	s_nop 1
	v_cndmask_b32_e32 v96, 0, v145, vcc
	v_sub_f32_e32 v80, v80, v96
	v_exp_f32_e32 v85, v80
	v_sub_f32_e32 v80, v81, v96
	v_exp_f32_e32 v87, v80
	v_sub_f32_e32 v80, v82, v96
	v_exp_f32_e32 v163, v80
	v_sub_f32_e32 v80, v83, v96
	v_exp_f32_e32 v165, v80
	v_sub_f32_e32 v80, v127, v96
	v_exp_f32_e32 v167, v80
	v_sub_f32_e32 v80, v147, v96
	v_exp_f32_e32 v169, v80
	v_sub_f32_e32 v80, v98, v96
	v_exp_f32_e32 v171, v80
	v_sub_f32_e32 v80, v125, v96
	v_exp_f32_e32 v191, v80
	v_sub_f32_e32 v80, v92, v96
	v_exp_f32_e32 v89, v80
	v_sub_f32_e32 v80, v93, v96
	v_exp_f32_e32 v91, v80
	v_sub_f32_e32 v80, v94, v96
	v_exp_f32_e32 v121, v80
	v_sub_f32_e32 v80, v95, v96
	v_exp_f32_e32 v123, v80
	v_sub_f32_e32 v80, v129, v96
	v_exp_f32_e32 v125, v80
	v_sub_f32_e32 v80, v101, v96
	v_exp_f32_e32 v127, v80
	v_sub_f32_e32 v80, v102, v96
	v_exp_f32_e32 v129, v80
	v_sub_f32_e32 v80, v103, v96
	v_exp_f32_e32 v131, v80
	v_sub_f32_e32 v80, v146, v96
	v_exp_f32_e32 v102, v80
	v_pk_mul_f32 v[82:83], v[62:63], v[100:101] op_sel_hi:[1,0]
	v_pk_mul_f32 v[80:81], v[60:61], v[100:101] op_sel_hi:[1,0]
	v_cvt_pk_f16_f32 v60, v84, v86
	v_pk_mul_f32 v[160:161], v[50:51], v[102:103] op_sel_hi:[1,0]
	v_pk_mul_f32 v[158:159], v[48:49], v[102:103] op_sel_hi:[1,0]
	v_pk_mul_f32 v[50:51], v[74:75], v[100:101] op_sel_hi:[1,0]
	v_pk_mul_f32 v[48:49], v[72:73], v[100:101] op_sel_hi:[1,0]
	ds_read_b128 v[72:75], v139 offset:29696
	v_pk_mul_f32 v[92:93], v[56:57], v[102:103] op_sel_hi:[1,0]
	v_pk_add_f32 v[56:57], v[84:85], 0 op_sel_hi:[1,0]
	v_pk_mul_f32 v[98:99], v[66:67], v[102:103] op_sel_hi:[1,0]
	v_pk_add_f32 v[56:57], v[86:87], v[56:57]
	v_pk_mul_f32 v[96:97], v[64:65], v[102:103] op_sel_hi:[1,0]
	v_pk_add_f32 v[56:57], v[162:163], v[56:57]
	v_cvt_pk_f16_f32 v61, v162, v164
	v_pk_add_f32 v[56:57], v[164:165], v[56:57]
	v_cvt_pk_f16_f32 v62, v166, v168
	v_pk_add_f32 v[56:57], v[166:167], v[56:57]
	v_cvt_pk_f16_f32 v63, v170, v190
	v_pk_add_f32 v[56:57], v[168:169], v[56:57]
	v_cvt_pk_f16_f32 v84, v85, v87
	v_pk_add_f32 v[56:57], v[170:171], v[56:57]
	v_cvt_pk_f16_f32 v85, v163, v165
	v_cvt_pk_f16_f32 v86, v167, v169
	v_cvt_pk_f16_f32 v87, v171, v191
	ds_read_b128 v[64:67], v139 offset:27648
	v_pk_add_f32 v[56:57], v[190:191], v[56:57]
	s_waitcnt lgkmcnt(1)
	v_mfma_f32_16x16x32_f16 v[68:71], v[72:75], v[60:63], v[68:71]
	v_add_f32_e64 v56, v88, v56
	v_add_f32_e64 v57, v89, v57
	v_pk_mul_f32 v[94:95], v[58:59], v[102:103] op_sel_hi:[1,0]
	v_pk_add_f32 v[56:57], v[90:91], v[56:57]
	v_mfma_f32_16x16x32_f16 v[72:75], v[72:75], v[84:87], v[96:99]
	v_add_f32_e64 v56, v120, v56
	v_add_f32_e64 v57, v121, v57
	v_pk_mul_f32 v[54:55], v[78:79], v[102:103] op_sel_hi:[1,0]
	v_pk_add_f32 v[56:57], v[122:123], v[56:57]
	ds_read_b128 v[96:99], v139 offset:33792
	v_pk_add_f32 v[56:57], v[124:125], v[56:57]
	v_pk_mul_f32 v[52:53], v[76:77], v[102:103] op_sel_hi:[1,0]
	v_pk_add_f32 v[56:57], v[126:127], v[56:57]
	v_mov_b32_e32 v101, v102
	v_pk_add_f32 v[56:57], v[128:129], v[56:57]
	v_mov_b32_e32 v146, v145
	v_pk_add_f32 v[102:103], v[130:131], v[56:57]
	s_waitcnt lgkmcnt(1)
	v_mfma_f32_16x16x32_f16 v[56:59], v[64:67], v[60:63], v[80:83]
	v_fma_f32 v118, v118, v100, v102
	v_fma_f32 v119, v119, v101, v103
	s_nop 0
	ds_read_b128 v[80:83], v139 offset:31744
	v_mfma_f32_16x16x32_f16 v[64:67], v[64:67], v[84:87], v[92:95]
	s_waitcnt lgkmcnt(1)
	v_mfma_f32_16x16x32_f16 v[92:95], v[96:99], v[60:63], v[48:51]
	s_nop 2
	ds_read_b128 v[48:51], v140 offset:27648
	s_waitcnt lgkmcnt(1)
	v_mfma_f32_16x16x32_f16 v[76:79], v[80:83], v[60:63], v[154:157]
	v_mfma_f32_16x16x32_f16 v[80:83], v[80:83], v[84:87], v[158:161]
	v_mfma_f32_16x16x32_f16 v[84:87], v[96:99], v[84:87], v[52:55]
	v_cvt_pk_f16_f32 v96, v88, v90
	v_cvt_pk_f16_f32 v97, v120, v122
	v_cvt_pk_f16_f32 v98, v124, v126
	v_cvt_pk_f16_f32 v99, v128, v130
	v_cvt_pk_f16_f32 v88, v89, v91
	v_cvt_pk_f16_f32 v89, v121, v123
	v_cvt_pk_f16_f32 v90, v125, v127
	v_cvt_pk_f16_f32 v91, v129, v131
	s_waitcnt lgkmcnt(0)
	v_mfma_f32_16x16x32_f16 v[60:63], v[48:51], v[96:99], v[56:59]
	v_mov_b32_e32 v131, v144
	v_mfma_f32_16x16x32_f16 v[56:59], v[48:51], v[88:91], v[64:67]
	ds_read_b128 v[48:51], v140 offset:29696
	s_waitcnt lgkmcnt(0)
	v_mfma_f32_16x16x32_f16 v[68:71], v[48:51], v[96:99], v[68:71]
	v_mfma_f32_16x16x32_f16 v[64:67], v[48:51], v[88:91], v[72:75]
	ds_read_b128 v[48:51], v140 offset:31744
	s_waitcnt lgkmcnt(0)
	v_mfma_f32_16x16x32_f16 v[52:55], v[48:51], v[96:99], v[76:79]
	s_nop 2
	ds_read_b128 v[76:79], v140 offset:33792
	v_mfma_f32_16x16x32_f16 v[48:51], v[48:51], v[88:91], v[80:83]
	s_waitcnt lgkmcnt(0)
	v_mfma_f32_16x16x32_f16 v[72:75], v[76:79], v[96:99], v[92:95]
	v_mfma_f32_16x16x32_f16 v[76:79], v[76:79], v[88:91], v[84:87]
	s_or_b64 exec, exec, s[12:13]
	s_andn2_b64 vcc, exec, s[10:11]
	s_cbranch_vccnz .LBB0_1076
